# split-K tail units (WO, down, pool) run a lean K-loop copy: ai=1 MFMAs dropped, ai=0 MFMAs only on the wr=0 waves
# speedup vs baseline: 1.0156x; 1.0069x over previous
; #define PG8_STAGE(bufoff, gbase, voff) do { _Pragma("unroll") for (int _i = 0; _i < 2; ++_i) \
;         __builtin_amdgcn_global_load_lds((const unsigned*)((const char*)(gbase) + (voff)[_i]), (LAS unsigned*)(lds + (bufoff) + ldsw + _i * 8192), 16, 0, 0); } while (0)
; #define PG8_LDA(dst, b, h) do { _Pragma("unroll") for (int m = 0; m < 4; ++m) _Pragma("unroll") for (int k = 0; k < 2; ++k) dst[m][k] = *(const LAS bf16x8*)(lds + PG8_SA(b, h) + aoff + m * 2048 + k * 1024); } while (0)
; #define PG8_LDB(dst, b, h) do { _Pragma("unroll") for (int n = 0; n < 2; ++n) _Pragma("unroll") for (int k = 0; k < 2; ++k) dst[n][k] = *(const LAS bf16x8*)(lds + PG8_SB(b, h) + boff + n * 2048 + k * 1024); } while (0)
; #define PG8_MMA(ai, bj, At, Bt) do { __builtin_amdgcn_s_setprio(1); _Pragma("unroll") for (int m = 0; m < 4; ++m) _Pragma("unroll") for (int n = 0; n < 2; ++n) _Pragma("unroll") for (int k = 0; k < 2; ++k) \
;         acc[ai][bj][m][n] = __builtin_amdgcn_mfma_f32_16x16x32_bf16(Bt[n][k], At[m][k], acc[ai][bj][m][n], 0, 0, 0); __builtin_amdgcn_s_setprio(0); } while (0)
; #define PG8_WAIT_V(n) asm volatile("s_waitcnt vmcnt(" #n ")" ::: "memory")
; #define PG8_BAR __builtin_amdgcn_s_barrier()
; template <class Epi>
; __device__ __forceinline__ void gemm_phase(LAS unsigned char* lds, const Sched& S, const Epi& E) {
;     ...
;         const bool has_next = S.next(ui + 1, nxt);
;         const char* nA = has_next ? nxt.A : cA; const char* nB = has_next ? nxt.B : cB;
;         const int nt = cur.nt;
;         for (int t = 0; t < nt; t += 2) {
;             const bool last = (t == nt - 2);
;             const char* a1 = cA + (size_t)(t + 1) * kstep;
;             const char* a2 = last ? nA : cA + (size_t)(t + 2) * kstep; const char* b2 = last ? nB : cB + (size_t)(t + 2) * kstep;
;             const char* a3 = a2 + kstep; const char* b3 = b2 + kstep;
;             PG8_LDB(B0, 0, 0); PG8_LDB(B1, 0, 1); PG8_SCHED; PG8_LDA(At, 0, 0); PG8_STAGE(PG8_SA(1, 1), a1 + hstepA, voffA);
;             PG8_WAIT_V(8); PG8_WAIT_L(0); PG8_BAR; PG8_MMA(0, 0, At, B0); PG8_MMA(0, 1, At, B1); PG8_BAR; PG8_SCHED;
;             PG8_LDA(At, 0, 1); PG8_STAGE(PG8_SB(0, 0), b2, voffB); PG8_STAGE(PG8_SB(0, 1), b2 + hstepB, voffB); PG8_STAGE(PG8_SA(0, 0), a2, voffA);
;             PG8_WAIT_V(8); PG8_WAIT_L(0); PG8_BAR; PG8_MMA(1, 0, At, B0); PG8_MMA(1, 1, At, B1); PG8_BAR; PG8_SCHED;
.LBB0_1388:
	s_and_b64 s[24:25], s[16:17], exec
	s_cselect_b32 s9, s11, s21
	s_cselect_b32 s13, s10, s20
	s_cselect_b32 s26, s15, s23
	s_cselect_b32 s27, s14, s22
	s_add_i32 s69, s19, -2
	s_add_u32 s20, s20, 0x80080
	s_addc_u32 s21, s21, 0
	s_add_u32 s82, s22, 0x100
	v_mov_b32_e32 v2, 0
	s_addc_u32 s94, s23, 0
	s_mov_b32 s22, 0
	s_waitcnt lgkmcnt(0)
	s_cmp_eq_u32 s18, 32
	s_cbranch_scc1 .Ltail_peel_wo
	s_add_i32 s95, s22, 2
	s_add_u32 s23, s20, 0xfff80080
	s_addc_u32 s24, s21, -1
	s_add_i32 s49, 0, 0x10000
	s_cmp_eq_u32 s69, s22
	s_cselect_b32 s25, s9, s24
	s_cselect_b32 s24, s13, s23
	s_cselect_b32 s23, s26, s94
	s_cselect_b32 s22, s27, s82
	s_add_i32 s88, 0, 0x14000
	v_add_u32_e32 v142, s49, v179
	v_add_u32_e32 v176, s88, v179
	ds_read_b128 v[130:133], v142
	ds_read_b128 v[134:137], v142 offset:1024
	ds_read_b128 v[138:141], v142 offset:2048
	ds_read_b128 v[142:145], v142 offset:3072
	ds_read_b128 v[160:163], v176
	ds_read_b128 v[164:167], v176 offset:1024
	ds_read_b128 v[182:185], v176 offset:2048
	ds_read_b128 v[186:189], v176 offset:3072
	v_lshl_add_u64 v[176:177], s[20:21], 0, v[156:157]
	s_add_i32 m0, s35, 0xc000
	ds_read_b128 v[190:193], v181
	ds_read_b128 v[194:197], v181 offset:1024
	ds_read_b128 v[198:201], v181 offset:2048
	ds_read_b128 v[222:225], v181 offset:3072
	ds_read_b128 v[226:229], v181 offset:4096
	ds_read_b128 v[230:233], v181 offset:5120
	ds_read_b128 v[234:237], v181 offset:6144
	ds_read_b128 v[238:241], v181 offset:7168
	global_load_lds_dwordx4 v[176:177], off
	v_lshl_add_u64 v[176:177], s[20:21], 0, v[158:159]
	s_add_i32 m0, s35, 0xe000
	s_nop 0
	global_load_lds_dwordx4 v[176:177], off
	s_waitcnt vmcnt(8)
	s_waitcnt lgkmcnt(0)
	s_barrier
	s_setprio 1
	s_waitcnt lgkmcnt(0)
	v_mfma_f32_16x16x32_bf16 v[126:129], v[130:133], v[190:193], 0
	v_mfma_f32_16x16x32_bf16 v[122:125], v[138:141], v[190:193], 0
	v_mfma_f32_16x16x32_bf16 v[110:113], v[130:133], v[198:201], 0
	v_mfma_f32_16x16x32_bf16 v[106:109], v[138:141], v[198:201], 0
	v_mfma_f32_16x16x32_bf16 v[94:97], v[130:133], v[226:229], 0
	v_mfma_f32_16x16x32_bf16 v[90:93], v[138:141], v[226:229], 0
	v_mfma_f32_16x16x32_bf16 v[78:81], v[130:133], v[234:237], 0
	v_mfma_f32_16x16x32_bf16 v[74:77], v[138:141], v[234:237], 0
	v_mfma_f32_16x16x32_bf16 v[126:129], v[134:137], v[194:197], v[126:129]
	v_mfma_f32_16x16x32_bf16 v[122:125], v[142:145], v[194:197], v[122:125]
	v_mfma_f32_16x16x32_bf16 v[110:113], v[134:137], v[222:225], v[110:113]
	v_mfma_f32_16x16x32_bf16 v[106:109], v[142:145], v[222:225], v[106:109]
	v_mfma_f32_16x16x32_bf16 v[94:97], v[134:137], v[230:233], v[94:97]
	v_mfma_f32_16x16x32_bf16 v[90:93], v[142:145], v[230:233], v[90:93]
	v_mfma_f32_16x16x32_bf16 v[78:81], v[134:137], v[238:241], v[78:81]
	v_mfma_f32_16x16x32_bf16 v[74:77], v[142:145], v[238:241], v[74:77]
	s_setprio 0
	s_setprio 1
	v_mfma_f32_16x16x32_bf16 v[118:121], v[160:163], v[190:193], 0
	v_mfma_f32_16x16x32_bf16 v[114:117], v[182:185], v[190:193], 0
	v_mfma_f32_16x16x32_bf16 v[102:105], v[160:163], v[198:201], 0
	v_mfma_f32_16x16x32_bf16 v[98:101], v[182:185], v[198:201], 0
	v_mfma_f32_16x16x32_bf16 v[86:89], v[160:163], v[226:229], 0
	v_mfma_f32_16x16x32_bf16 v[82:85], v[182:185], v[226:229], 0
	v_mfma_f32_16x16x32_bf16 v[70:73], v[160:163], v[234:237], 0
	v_mfma_f32_16x16x32_bf16 v[66:69], v[182:185], v[234:237], 0
	v_mfma_f32_16x16x32_bf16 v[118:121], v[164:167], v[194:197], v[118:121]
	v_mfma_f32_16x16x32_bf16 v[114:117], v[186:189], v[194:197], v[114:117]
	v_mfma_f32_16x16x32_bf16 v[102:105], v[164:167], v[222:225], v[102:105]
	v_mfma_f32_16x16x32_bf16 v[98:101], v[186:189], v[222:225], v[98:101]
	v_mfma_f32_16x16x32_bf16 v[86:89], v[164:167], v[230:233], v[86:89]
	v_mfma_f32_16x16x32_bf16 v[82:85], v[186:189], v[230:233], v[82:85]
	v_mfma_f32_16x16x32_bf16 v[70:73], v[164:167], v[238:241], v[70:73]
	v_mfma_f32_16x16x32_bf16 v[66:69], v[186:189], v[238:241], v[66:69]
	s_setprio 0
	s_barrier
	s_add_i32 s49, s49, s34
	v_lshl_add_u64 v[176:177], s[22:23], 0, v[168:169]
	s_mov_b32 m0, s49
	ds_read_b128 v[190:193], v181 offset:16384
	ds_read_b128 v[194:197], v181 offset:17408
	ds_read_b128 v[198:201], v181 offset:18432
	ds_read_b128 v[222:225], v181 offset:19456
	ds_read_b128 v[226:229], v181 offset:20480
	ds_read_b128 v[230:233], v181 offset:21504
	ds_read_b128 v[234:237], v181 offset:22528
	ds_read_b128 v[238:241], v181 offset:23552
	global_load_lds_dwordx4 v[176:177], off
	s_add_i32 m0, s49, 0x2000
	s_add_u32 s96, s22, 0x80000
	v_lshl_add_u64 v[242:243], s[22:23], 0, v[146:147]
	s_addc_u32 s97, s23, 0
	s_add_i32 s49, s88, s34
	global_load_lds_dwordx4 v[242:243], off
	v_lshl_add_u64 v[244:245], s[96:97], 0, v[168:169]
	s_mov_b32 m0, s49
	v_lshl_add_u64 v[246:247], s[24:25], 0, v[146:147]
	global_load_lds_dwordx4 v[244:245], off
	v_lshl_add_u64 v[244:245], s[96:97], 0, v[146:147]
	s_add_i32 m0, s49, 0x2000
	s_nop 0
	global_load_lds_dwordx4 v[244:245], off
	v_lshl_add_u64 v[244:245], s[24:25], 0, v[168:169]
	s_mov_b32 m0, s35
	s_nop 0
	global_load_lds_dwordx4 v[244:245], off
	s_mov_b32 m0, s36
	s_nop 0
	global_load_lds_dwordx4 v[246:247], off
	s_waitcnt vmcnt(8)
	s_waitcnt lgkmcnt(0)
	s_barrier
; #define PG8_STAGE(bufoff, gbase, voff) do { _Pragma("unroll") for (int _i = 0; _i < 2; ++_i) \
;         __builtin_amdgcn_global_load_lds((const unsigned*)((const char*)(gbase) + (voff)[_i]), (LAS unsigned*)(lds + (bufoff) + ldsw + _i * 8192), 16, 0, 0); } while (0)
; #define PG8_LDA(dst, b, h) do { _Pragma("unroll") for (int m = 0; m < 4; ++m) _Pragma("unroll") for (int k = 0; k < 2; ++k) dst[m][k] = *(const LAS bf16x8*)(lds + PG8_SA(b, h) + aoff + m * 2048 + k * 1024); } while (0)
; #define PG8_LDB(dst, b, h) do { _Pragma("unroll") for (int n = 0; n < 2; ++n) _Pragma("unroll") for (int k = 0; k < 2; ++k) dst[n][k] = *(const LAS bf16x8*)(lds + PG8_SB(b, h) + boff + n * 2048 + k * 1024); } while (0)
; #define PG8_MMA(ai, bj, At, Bt) do { __builtin_amdgcn_s_setprio(1); _Pragma("unroll") for (int m = 0; m < 4; ++m) _Pragma("unroll") for (int n = 0; n < 2; ++n) _Pragma("unroll") for (int k = 0; k < 2; ++k) \
;         acc[ai][bj][m][n] = __builtin_amdgcn_mfma_f32_16x16x32_bf16(Bt[n][k], At[m][k], acc[ai][bj][m][n], 0, 0, 0); __builtin_amdgcn_s_setprio(0); } while (0)
; #define PG8_WAIT_V(n) asm volatile("s_waitcnt vmcnt(" #n ")" ::: "memory")
; #define PG8_WAIT_L(n) asm volatile("s_waitcnt lgkmcnt(" #n ")" ::: "memory")
; #define PG8_BAR __builtin_amdgcn_s_barrier()
; #define PG8_SCHED __builtin_amdgcn_sched_barrier(0)
; template <class Epi>
; __device__ __forceinline__ void gemm_phase(LAS unsigned char* lds, const Sched& S, const Epi& E) {
;     ...
;             PG8_WAIT_V(8); PG8_WAIT_L(0); PG8_BAR; PG8_MMA(1, 0, At, B0); PG8_MMA(1, 1, At, B1); PG8_BAR; PG8_SCHED;
;             PG8_LDB(B0, 1, 0); PG8_LDB(B1, 1, 1); PG8_SCHED; PG8_LDA(At, 1, 0); PG8_STAGE(PG8_SA(0, 1), a2 + hstepA, voffA);
;             PG8_WAIT_V(8); PG8_WAIT_L(0); PG8_BAR; PG8_MMA(0, 0, At, B0); PG8_MMA(0, 1, At, B1); PG8_BAR; PG8_SCHED;
	s_setprio 1
	s_waitcnt lgkmcnt(0)
	v_mfma_f32_16x16x32_bf16 v[62:65], v[130:133], v[190:193], 0
	v_mfma_f32_16x16x32_bf16 v[58:61], v[138:141], v[190:193], 0
	v_mfma_f32_16x16x32_bf16 v[46:49], v[130:133], v[198:201], 0
	v_mfma_f32_16x16x32_bf16 v[42:45], v[138:141], v[198:201], 0
	v_mfma_f32_16x16x32_bf16 v[30:33], v[130:133], v[226:229], 0
	v_mfma_f32_16x16x32_bf16 v[26:29], v[138:141], v[226:229], 0
	v_mfma_f32_16x16x32_bf16 v[14:17], v[130:133], v[234:237], 0
	v_mfma_f32_16x16x32_bf16 v[10:13], v[138:141], v[234:237], 0
	v_mfma_f32_16x16x32_bf16 v[62:65], v[134:137], v[194:197], v[62:65]
	v_mfma_f32_16x16x32_bf16 v[58:61], v[142:145], v[194:197], v[58:61]
	v_mfma_f32_16x16x32_bf16 v[46:49], v[134:137], v[222:225], v[46:49]
	v_mfma_f32_16x16x32_bf16 v[42:45], v[142:145], v[222:225], v[42:45]
	v_mfma_f32_16x16x32_bf16 v[30:33], v[134:137], v[230:233], v[30:33]
	v_mfma_f32_16x16x32_bf16 v[26:29], v[142:145], v[230:233], v[26:29]
	v_mfma_f32_16x16x32_bf16 v[14:17], v[134:137], v[238:241], v[14:17]
	v_mfma_f32_16x16x32_bf16 v[10:13], v[142:145], v[238:241], v[10:13]
	s_setprio 0
	s_setprio 1
	v_mfma_f32_16x16x32_bf16 v[54:57], v[160:163], v[190:193], 0
	v_mfma_f32_16x16x32_bf16 v[50:53], v[182:185], v[190:193], 0
	v_mfma_f32_16x16x32_bf16 v[38:41], v[160:163], v[198:201], 0
	v_mfma_f32_16x16x32_bf16 v[34:37], v[182:185], v[198:201], 0
	v_mfma_f32_16x16x32_bf16 v[22:25], v[160:163], v[226:229], 0
	v_mfma_f32_16x16x32_bf16 v[18:21], v[182:185], v[226:229], 0
	v_mfma_f32_16x16x32_bf16 v[6:9], v[160:163], v[234:237], 0
	v_mfma_f32_16x16x32_bf16 v[2:5], v[182:185], v[234:237], 0
	v_mfma_f32_16x16x32_bf16 v[54:57], v[164:167], v[194:197], v[54:57]
	v_mfma_f32_16x16x32_bf16 v[50:53], v[186:189], v[194:197], v[50:53]
	v_mfma_f32_16x16x32_bf16 v[38:41], v[164:167], v[222:225], v[38:41]
	v_mfma_f32_16x16x32_bf16 v[34:37], v[186:189], v[222:225], v[34:37]
	v_mfma_f32_16x16x32_bf16 v[22:25], v[164:167], v[230:233], v[22:25]
	v_mfma_f32_16x16x32_bf16 v[18:21], v[186:189], v[230:233], v[18:21]
	v_mfma_f32_16x16x32_bf16 v[6:9], v[164:167], v[238:241], v[6:9]
	v_mfma_f32_16x16x32_bf16 v[2:5], v[186:189], v[238:241], v[2:5]
	s_setprio 0
	s_barrier
	s_add_i32 s49, 0, 0x18000
	s_add_i32 s88, 0, 0x1c000
	v_add_u32_e32 v142, s49, v179
	v_add_u32_e32 v186, s88, v179
	ds_read_b128 v[130:133], v142
	ds_read_b128 v[134:137], v142 offset:1024
	ds_read_b128 v[138:141], v142 offset:2048
	ds_read_b128 v[142:145], v142 offset:3072
	ds_read_b128 v[160:163], v186
	ds_read_b128 v[164:167], v186 offset:1024
	ds_read_b128 v[182:185], v186 offset:2048
	ds_read_b128 v[186:189], v186 offset:3072
	s_add_u32 s24, s24, 0x80000
	s_addc_u32 s25, s25, 0
	s_mov_b32 m0, s37
	v_lshl_add_u64 v[248:249], s[24:25], 0, v[168:169]
	ds_read_b128 v[190:193], v181 offset:32768
	ds_read_b128 v[194:197], v181 offset:33792
	ds_read_b128 v[198:201], v181 offset:34816
	ds_read_b128 v[222:225], v181 offset:35840
	ds_read_b128 v[226:229], v181 offset:36864
	ds_read_b128 v[230:233], v181 offset:37888
	ds_read_b128 v[234:237], v181 offset:38912
	ds_read_b128 v[238:241], v181 offset:39936
	global_load_lds_dwordx4 v[248:249], off
	v_lshl_add_u64 v[248:249], s[24:25], 0, v[146:147]
	s_mov_b32 m0, s38
	s_nop 0
	global_load_lds_dwordx4 v[248:249], off
	s_waitcnt vmcnt(8)
	s_waitcnt lgkmcnt(0)
	s_barrier
	s_setprio 1
	s_waitcnt lgkmcnt(0)
	v_mfma_f32_16x16x32_bf16 v[126:129], v[130:133], v[190:193], v[126:129]
	v_mfma_f32_16x16x32_bf16 v[122:125], v[138:141], v[190:193], v[122:125]
	v_mfma_f32_16x16x32_bf16 v[110:113], v[130:133], v[198:201], v[110:113]
	v_mfma_f32_16x16x32_bf16 v[106:109], v[138:141], v[198:201], v[106:109]
	v_mfma_f32_16x16x32_bf16 v[94:97], v[130:133], v[226:229], v[94:97]
	v_mfma_f32_16x16x32_bf16 v[90:93], v[138:141], v[226:229], v[90:93]
	v_mfma_f32_16x16x32_bf16 v[78:81], v[130:133], v[234:237], v[78:81]
	v_mfma_f32_16x16x32_bf16 v[74:77], v[138:141], v[234:237], v[74:77]
	v_mfma_f32_16x16x32_bf16 v[126:129], v[134:137], v[194:197], v[126:129]
	v_mfma_f32_16x16x32_bf16 v[122:125], v[142:145], v[194:197], v[122:125]
	v_mfma_f32_16x16x32_bf16 v[110:113], v[134:137], v[222:225], v[110:113]
	v_mfma_f32_16x16x32_bf16 v[106:109], v[142:145], v[222:225], v[106:109]
	v_mfma_f32_16x16x32_bf16 v[94:97], v[134:137], v[230:233], v[94:97]
	v_mfma_f32_16x16x32_bf16 v[90:93], v[142:145], v[230:233], v[90:93]
	v_mfma_f32_16x16x32_bf16 v[78:81], v[134:137], v[238:241], v[78:81]
	v_mfma_f32_16x16x32_bf16 v[74:77], v[142:145], v[238:241], v[74:77]
	s_setprio 0
	s_setprio 1
	v_mfma_f32_16x16x32_bf16 v[118:121], v[160:163], v[190:193], v[118:121]
	v_mfma_f32_16x16x32_bf16 v[114:117], v[182:185], v[190:193], v[114:117]
	v_mfma_f32_16x16x32_bf16 v[102:105], v[160:163], v[198:201], v[102:105]
	v_mfma_f32_16x16x32_bf16 v[98:101], v[182:185], v[198:201], v[98:101]
	v_mfma_f32_16x16x32_bf16 v[86:89], v[160:163], v[226:229], v[86:89]
	v_mfma_f32_16x16x32_bf16 v[82:85], v[182:185], v[226:229], v[82:85]
	v_mfma_f32_16x16x32_bf16 v[70:73], v[160:163], v[234:237], v[70:73]
	v_mfma_f32_16x16x32_bf16 v[66:69], v[182:185], v[234:237], v[66:69]
	v_mfma_f32_16x16x32_bf16 v[118:121], v[164:167], v[194:197], v[118:121]
	v_mfma_f32_16x16x32_bf16 v[114:117], v[186:189], v[194:197], v[114:117]
	v_mfma_f32_16x16x32_bf16 v[102:105], v[164:167], v[222:225], v[102:105]
	v_mfma_f32_16x16x32_bf16 v[98:101], v[186:189], v[222:225], v[98:101]
	v_mfma_f32_16x16x32_bf16 v[86:89], v[164:167], v[230:233], v[86:89]
	v_mfma_f32_16x16x32_bf16 v[82:85], v[186:189], v[230:233], v[82:85]
	v_mfma_f32_16x16x32_bf16 v[70:73], v[164:167], v[238:241], v[70:73]
	v_mfma_f32_16x16x32_bf16 v[66:69], v[186:189], v[238:241], v[66:69]
	s_setprio 0
	s_barrier
; #define PG8_STAGE(bufoff, gbase, voff) do { _Pragma("unroll") for (int _i = 0; _i < 2; ++_i) \
;         __builtin_amdgcn_global_load_lds((const unsigned*)((const char*)(gbase) + (voff)[_i]), (LAS unsigned*)(lds + (bufoff) + ldsw + _i * 8192), 16, 0, 0); } while (0)
; #define PG8_LDA(dst, b, h) do { _Pragma("unroll") for (int m = 0; m < 4; ++m) _Pragma("unroll") for (int k = 0; k < 2; ++k) dst[m][k] = *(const LAS bf16x8*)(lds + PG8_SA(b, h) + aoff + m * 2048 + k * 1024); } while (0)
; #define PG8_LDB(dst, b, h) do { _Pragma("unroll") for (int n = 0; n < 2; ++n) _Pragma("unroll") for (int k = 0; k < 2; ++k) dst[n][k] = *(const LAS bf16x8*)(lds + PG8_SB(b, h) + boff + n * 2048 + k * 1024); } while (0)
; #define PG8_WAIT_V(n) asm volatile("s_waitcnt vmcnt(" #n ")" ::: "memory")
; #define PG8_WAIT_L(n) asm volatile("s_waitcnt lgkmcnt(" #n ")" ::: "memory")
; template <class Epi>
; __device__ __forceinline__ void gemm_phase(LAS unsigned char* lds, const Sched& S, const Epi& E) {
;     ...
;         for (int t = 0; t < nt; t += 2) {
;             const bool last = (t == nt - 2);
;             const char* a1 = cA + (size_t)(t + 1) * kstep;
;             const char* a2 = last ? nA : cA + (size_t)(t + 2) * kstep; const char* b2 = last ? nB : cB + (size_t)(t + 2) * kstep;
;             const char* a3 = a2 + kstep; const char* b3 = b2 + kstep;
;             PG8_LDB(B0, 0, 0); PG8_LDB(B1, 0, 1); PG8_SCHED; PG8_LDA(At, 0, 0); PG8_STAGE(PG8_SA(1, 1), a1 + hstepA, voffA);
;             PG8_WAIT_V(8); PG8_WAIT_L(0); PG8_BAR; PG8_MMA(0, 0, At, B0); PG8_MMA(0, 1, At, B1); PG8_BAR; PG8_SCHED;
;             PG8_LDA(At, 0, 1); PG8_STAGE(PG8_SB(0, 0), b2, voffB); PG8_STAGE(PG8_SB(0, 1), b2 + hstepB, voffB); PG8_STAGE(PG8_SA(0, 0), a2, voffA);
;             PG8_WAIT_V(8); PG8_WAIT_L(0); PG8_BAR; PG8_MMA(1, 0, At, B0); PG8_MMA(1, 1, At, B1); PG8_BAR; PG8_SCHED;
;             PG8_LDB(B0, 1, 0); PG8_LDB(B1, 1, 1); PG8_SCHED; PG8_LDA(At, 1, 0); PG8_STAGE(PG8_SA(0, 1), a2 + hstepA, voffA);
;             PG8_WAIT_V(8); PG8_WAIT_L(0); PG8_BAR; PG8_MMA(0, 0, At, B0); PG8_MMA(0, 1, At, B1); PG8_BAR; PG8_SCHED;
;             PG8_LDA(At, 1, 1); PG8_STAGE(PG8_SB(1, 0), b3, voffB); PG8_STAGE(PG8_SB(1, 1), b3 + hstepB, voffB); PG8_STAGE(PG8_SA(1, 0), a3, voffA);
;             PG8_WAIT_V(8); PG8_WAIT_L(0); PG8_BAR; PG8_MMA(1, 0, At, B0); PG8_MMA(1, 1, At, B1); PG8_BAR; PG8_SCHED;
	s_add_i32 s24, s49, s34
	v_lshl_add_u64 v[176:177], v[176:177], 0, s[0:1]
	s_mov_b32 m0, s24
	ds_read_b128 v[190:193], v181 offset:49152
	ds_read_b128 v[194:197], v181 offset:50176
	ds_read_b128 v[198:201], v181 offset:51200
	ds_read_b128 v[222:225], v181 offset:52224
	ds_read_b128 v[226:229], v181 offset:53248
	ds_read_b128 v[230:233], v181 offset:54272
	ds_read_b128 v[234:237], v181 offset:55296
	ds_read_b128 v[238:241], v181 offset:56320
	global_load_lds_dwordx4 v[176:177], off
	s_add_i32 m0, s24, 0x2000
	s_add_u32 s22, s22, 0x80080
	v_lshl_add_u64 v[176:177], v[242:243], 0, s[0:1]
	s_addc_u32 s23, s23, 0
	s_add_i32 s24, s88, s34
	global_load_lds_dwordx4 v[176:177], off
	v_lshl_add_u64 v[176:177], s[22:23], 0, v[168:169]
	s_mov_b32 m0, s24
	s_nop 0
	global_load_lds_dwordx4 v[176:177], off
	v_lshl_add_u64 v[176:177], s[22:23], 0, v[146:147]
	s_add_i32 m0, s24, 0x2000
	s_nop 0
	global_load_lds_dwordx4 v[176:177], off
	v_lshl_add_u64 v[176:177], v[244:245], 0, s[0:1]
	s_mov_b32 m0, s39
	s_nop 0
	global_load_lds_dwordx4 v[176:177], off
	v_lshl_add_u64 v[176:177], v[246:247], 0, s[0:1]
	s_mov_b32 m0, s59
	s_nop 0
	global_load_lds_dwordx4 v[176:177], off
	s_waitcnt vmcnt(8)
	s_waitcnt lgkmcnt(0)
	s_barrier
	s_setprio 1
	s_waitcnt lgkmcnt(0)
	v_mfma_f32_16x16x32_bf16 v[62:65], v[130:133], v[190:193], v[62:65]
	v_mfma_f32_16x16x32_bf16 v[58:61], v[138:141], v[190:193], v[58:61]
	v_mfma_f32_16x16x32_bf16 v[46:49], v[130:133], v[198:201], v[46:49]
	v_mfma_f32_16x16x32_bf16 v[42:45], v[138:141], v[198:201], v[42:45]
	v_mfma_f32_16x16x32_bf16 v[30:33], v[130:133], v[226:229], v[30:33]
	v_mfma_f32_16x16x32_bf16 v[26:29], v[138:141], v[226:229], v[26:29]
	v_mfma_f32_16x16x32_bf16 v[14:17], v[130:133], v[234:237], v[14:17]
	v_mfma_f32_16x16x32_bf16 v[10:13], v[138:141], v[234:237], v[10:13]
	v_mfma_f32_16x16x32_bf16 v[62:65], v[134:137], v[194:197], v[62:65]
	v_mfma_f32_16x16x32_bf16 v[58:61], v[142:145], v[194:197], v[58:61]
	v_mfma_f32_16x16x32_bf16 v[46:49], v[134:137], v[222:225], v[46:49]
	v_mfma_f32_16x16x32_bf16 v[42:45], v[142:145], v[222:225], v[42:45]
	v_mfma_f32_16x16x32_bf16 v[30:33], v[134:137], v[230:233], v[30:33]
	v_mfma_f32_16x16x32_bf16 v[26:29], v[142:145], v[230:233], v[26:29]
	v_mfma_f32_16x16x32_bf16 v[14:17], v[134:137], v[238:241], v[14:17]
	v_mfma_f32_16x16x32_bf16 v[10:13], v[142:145], v[238:241], v[10:13]
	s_setprio 0
	s_setprio 1
	v_mfma_f32_16x16x32_bf16 v[54:57], v[160:163], v[190:193], v[54:57]
	v_mfma_f32_16x16x32_bf16 v[50:53], v[182:185], v[190:193], v[50:53]
	v_mfma_f32_16x16x32_bf16 v[38:41], v[160:163], v[198:201], v[38:41]
	v_mfma_f32_16x16x32_bf16 v[34:37], v[182:185], v[198:201], v[34:37]
	v_mfma_f32_16x16x32_bf16 v[22:25], v[160:163], v[226:229], v[22:25]
	v_mfma_f32_16x16x32_bf16 v[18:21], v[182:185], v[226:229], v[18:21]
	v_mfma_f32_16x16x32_bf16 v[6:9], v[160:163], v[234:237], v[6:9]
	v_mfma_f32_16x16x32_bf16 v[2:5], v[182:185], v[234:237], v[2:5]
	v_mfma_f32_16x16x32_bf16 v[54:57], v[164:167], v[194:197], v[54:57]
	v_mfma_f32_16x16x32_bf16 v[50:53], v[186:189], v[194:197], v[50:53]
	v_mfma_f32_16x16x32_bf16 v[38:41], v[164:167], v[222:225], v[38:41]
	v_mfma_f32_16x16x32_bf16 v[34:37], v[186:189], v[222:225], v[34:37]
	v_mfma_f32_16x16x32_bf16 v[22:25], v[164:167], v[230:233], v[22:25]
	v_mfma_f32_16x16x32_bf16 v[18:21], v[186:189], v[230:233], v[18:21]
	v_mfma_f32_16x16x32_bf16 v[6:9], v[164:167], v[238:241], v[6:9]
	v_mfma_f32_16x16x32_bf16 v[2:5], v[186:189], v[238:241], v[2:5]
	s_setprio 0
	s_barrier
	s_add_u32 s20, s20, 0x100
	s_addc_u32 s21, s21, 0
	s_add_u32 s82, s82, 0x100
	s_addc_u32 s94, s94, 0
	s_cmp_ge_i32 s95, s19
	s_mov_b32 s22, s95
	s_cbranch_scc1 .Lpeel_exit_wo
.LBB0_1389:
	s_add_i32 s95, s22, 2
	s_add_u32 s23, s20, 0xfff80080
	s_addc_u32 s24, s21, -1
	s_add_i32 s49, 0, 0x10000
	s_cmp_eq_u32 s69, s22
	s_cselect_b32 s25, s9, s24
	s_cselect_b32 s24, s13, s23
	s_cselect_b32 s23, s26, s94
	s_cselect_b32 s22, s27, s82
	s_add_i32 s88, 0, 0x14000
	v_add_u32_e32 v142, s49, v179
	v_add_u32_e32 v176, s88, v179
	ds_read_b128 v[130:133], v142
	ds_read_b128 v[134:137], v142 offset:1024
	ds_read_b128 v[138:141], v142 offset:2048
	ds_read_b128 v[142:145], v142 offset:3072
	ds_read_b128 v[160:163], v176
	ds_read_b128 v[164:167], v176 offset:1024
	ds_read_b128 v[182:185], v176 offset:2048
	ds_read_b128 v[186:189], v176 offset:3072
	v_lshl_add_u64 v[176:177], s[20:21], 0, v[156:157]
	s_add_i32 m0, s35, 0xc000
	ds_read_b128 v[190:193], v181
	ds_read_b128 v[194:197], v181 offset:1024
	ds_read_b128 v[198:201], v181 offset:2048
	ds_read_b128 v[222:225], v181 offset:3072
	ds_read_b128 v[226:229], v181 offset:4096
	ds_read_b128 v[230:233], v181 offset:5120
	ds_read_b128 v[234:237], v181 offset:6144
	ds_read_b128 v[238:241], v181 offset:7168
	global_load_lds_dwordx4 v[176:177], off
	v_lshl_add_u64 v[176:177], s[20:21], 0, v[158:159]
	s_add_i32 m0, s35, 0xe000
	s_nop 0
	global_load_lds_dwordx4 v[176:177], off
	s_waitcnt vmcnt(8)
	s_waitcnt lgkmcnt(0)
	s_barrier
; #define PG8_STAGE(bufoff, gbase, voff) do { _Pragma("unroll") for (int _i = 0; _i < 2; ++_i) \
;         __builtin_amdgcn_global_load_lds((const unsigned*)((const char*)(gbase) + (voff)[_i]), (LAS unsigned*)(lds + (bufoff) + ldsw + _i * 8192), 16, 0, 0); } while (0)
; #define PG8_LDA(dst, b, h) do { _Pragma("unroll") for (int m = 0; m < 4; ++m) _Pragma("unroll") for (int k = 0; k < 2; ++k) dst[m][k] = *(const LAS bf16x8*)(lds + PG8_SA(b, h) + aoff + m * 2048 + k * 1024); } while (0)
; #define PG8_LDB(dst, b, h) do { _Pragma("unroll") for (int n = 0; n < 2; ++n) _Pragma("unroll") for (int k = 0; k < 2; ++k) dst[n][k] = *(const LAS bf16x8*)(lds + PG8_SB(b, h) + boff + n * 2048 + k * 1024); } while (0)
; #define PG8_MMA(ai, bj, At, Bt) do { __builtin_amdgcn_s_setprio(1); _Pragma("unroll") for (int m = 0; m < 4; ++m) _Pragma("unroll") for (int n = 0; n < 2; ++n) _Pragma("unroll") for (int k = 0; k < 2; ++k) \
;         acc[ai][bj][m][n] = __builtin_amdgcn_mfma_f32_16x16x32_bf16(Bt[n][k], At[m][k], acc[ai][bj][m][n], 0, 0, 0); __builtin_amdgcn_s_setprio(0); } while (0)
; #define PG8_WAIT_V(n) asm volatile("s_waitcnt vmcnt(" #n ")" ::: "memory")
; #define PG8_WAIT_L(n) asm volatile("s_waitcnt lgkmcnt(" #n ")" ::: "memory")
; #define PG8_BAR __builtin_amdgcn_s_barrier()
; #define PG8_SCHED __builtin_amdgcn_sched_barrier(0)
; template <class Epi>
; __device__ __forceinline__ void gemm_phase(LAS unsigned char* lds, const Sched& S, const Epi& E) {
;     ...
;             PG8_WAIT_V(8); PG8_WAIT_L(0); PG8_BAR; PG8_MMA(0, 0, At, B0); PG8_MMA(0, 1, At, B1); PG8_BAR; PG8_SCHED;
;             PG8_LDA(At, 0, 1); PG8_STAGE(PG8_SB(0, 0), b2, voffB); PG8_STAGE(PG8_SB(0, 1), b2 + hstepB, voffB); PG8_STAGE(PG8_SA(0, 0), a2, voffA);
;             PG8_WAIT_V(8); PG8_WAIT_L(0); PG8_BAR; PG8_MMA(1, 0, At, B0); PG8_MMA(1, 1, At, B1); PG8_BAR; PG8_SCHED;
;             PG8_LDB(B0, 1, 0); PG8_LDB(B1, 1, 1); PG8_SCHED; PG8_LDA(At, 1, 0); PG8_STAGE(PG8_SA(0, 1), a2 + hstepA, voffA);
;             PG8_WAIT_V(8); PG8_WAIT_L(0); PG8_BAR; PG8_MMA(0, 0, At, B0); PG8_MMA(0, 1, At, B1); PG8_BAR; PG8_SCHED;
	s_setprio 1
	s_waitcnt lgkmcnt(0)
	v_mfma_f32_16x16x32_bf16 v[126:129], v[130:133], v[190:193], v[126:129]
	v_mfma_f32_16x16x32_bf16 v[122:125], v[138:141], v[190:193], v[122:125]
	v_mfma_f32_16x16x32_bf16 v[110:113], v[130:133], v[198:201], v[110:113]
	v_mfma_f32_16x16x32_bf16 v[106:109], v[138:141], v[198:201], v[106:109]
	v_mfma_f32_16x16x32_bf16 v[94:97], v[130:133], v[226:229], v[94:97]
	v_mfma_f32_16x16x32_bf16 v[90:93], v[138:141], v[226:229], v[90:93]
	v_mfma_f32_16x16x32_bf16 v[78:81], v[130:133], v[234:237], v[78:81]
	v_mfma_f32_16x16x32_bf16 v[74:77], v[138:141], v[234:237], v[74:77]
	v_mfma_f32_16x16x32_bf16 v[126:129], v[134:137], v[194:197], v[126:129]
	v_mfma_f32_16x16x32_bf16 v[122:125], v[142:145], v[194:197], v[122:125]
	v_mfma_f32_16x16x32_bf16 v[110:113], v[134:137], v[222:225], v[110:113]
	v_mfma_f32_16x16x32_bf16 v[106:109], v[142:145], v[222:225], v[106:109]
	v_mfma_f32_16x16x32_bf16 v[94:97], v[134:137], v[230:233], v[94:97]
	v_mfma_f32_16x16x32_bf16 v[90:93], v[142:145], v[230:233], v[90:93]
	v_mfma_f32_16x16x32_bf16 v[78:81], v[134:137], v[238:241], v[78:81]
	v_mfma_f32_16x16x32_bf16 v[74:77], v[142:145], v[238:241], v[74:77]
	s_setprio 0
	s_setprio 1
	v_mfma_f32_16x16x32_bf16 v[118:121], v[160:163], v[190:193], v[118:121]
	v_mfma_f32_16x16x32_bf16 v[114:117], v[182:185], v[190:193], v[114:117]
	v_mfma_f32_16x16x32_bf16 v[102:105], v[160:163], v[198:201], v[102:105]
	v_mfma_f32_16x16x32_bf16 v[98:101], v[182:185], v[198:201], v[98:101]
	v_mfma_f32_16x16x32_bf16 v[86:89], v[160:163], v[226:229], v[86:89]
	v_mfma_f32_16x16x32_bf16 v[82:85], v[182:185], v[226:229], v[82:85]
	v_mfma_f32_16x16x32_bf16 v[70:73], v[160:163], v[234:237], v[70:73]
	v_mfma_f32_16x16x32_bf16 v[66:69], v[182:185], v[234:237], v[66:69]
	v_mfma_f32_16x16x32_bf16 v[118:121], v[164:167], v[194:197], v[118:121]
	v_mfma_f32_16x16x32_bf16 v[114:117], v[186:189], v[194:197], v[114:117]
	v_mfma_f32_16x16x32_bf16 v[102:105], v[164:167], v[222:225], v[102:105]
	v_mfma_f32_16x16x32_bf16 v[98:101], v[186:189], v[222:225], v[98:101]
	v_mfma_f32_16x16x32_bf16 v[86:89], v[164:167], v[230:233], v[86:89]
	v_mfma_f32_16x16x32_bf16 v[82:85], v[186:189], v[230:233], v[82:85]
	v_mfma_f32_16x16x32_bf16 v[70:73], v[164:167], v[238:241], v[70:73]
	v_mfma_f32_16x16x32_bf16 v[66:69], v[186:189], v[238:241], v[66:69]
	s_setprio 0
	s_barrier
	s_add_i32 s49, s49, s34
	v_lshl_add_u64 v[176:177], s[22:23], 0, v[168:169]
	s_mov_b32 m0, s49
	ds_read_b128 v[190:193], v181 offset:16384
	ds_read_b128 v[194:197], v181 offset:17408
	ds_read_b128 v[198:201], v181 offset:18432
	ds_read_b128 v[222:225], v181 offset:19456
	ds_read_b128 v[226:229], v181 offset:20480
	ds_read_b128 v[230:233], v181 offset:21504
	ds_read_b128 v[234:237], v181 offset:22528
	ds_read_b128 v[238:241], v181 offset:23552
	global_load_lds_dwordx4 v[176:177], off
	s_add_i32 m0, s49, 0x2000
	s_add_u32 s96, s22, 0x80000
	v_lshl_add_u64 v[242:243], s[22:23], 0, v[146:147]
	s_addc_u32 s97, s23, 0
	s_add_i32 s49, s88, s34
	global_load_lds_dwordx4 v[242:243], off
	v_lshl_add_u64 v[244:245], s[96:97], 0, v[168:169]
	s_mov_b32 m0, s49
	v_lshl_add_u64 v[246:247], s[24:25], 0, v[146:147]
	global_load_lds_dwordx4 v[244:245], off
	v_lshl_add_u64 v[244:245], s[96:97], 0, v[146:147]
	s_add_i32 m0, s49, 0x2000
	s_nop 0
	global_load_lds_dwordx4 v[244:245], off
	v_lshl_add_u64 v[244:245], s[24:25], 0, v[168:169]
	s_mov_b32 m0, s35
	s_nop 0
	global_load_lds_dwordx4 v[244:245], off
	s_mov_b32 m0, s36
	s_nop 0
	global_load_lds_dwordx4 v[246:247], off
	s_waitcnt vmcnt(8)
	s_waitcnt lgkmcnt(0)
	s_barrier
	s_setprio 1
	s_waitcnt lgkmcnt(0)
	v_mfma_f32_16x16x32_bf16 v[62:65], v[130:133], v[190:193], v[62:65]
	v_mfma_f32_16x16x32_bf16 v[58:61], v[138:141], v[190:193], v[58:61]
	v_mfma_f32_16x16x32_bf16 v[46:49], v[130:133], v[198:201], v[46:49]
	v_mfma_f32_16x16x32_bf16 v[42:45], v[138:141], v[198:201], v[42:45]
	v_mfma_f32_16x16x32_bf16 v[30:33], v[130:133], v[226:229], v[30:33]
	v_mfma_f32_16x16x32_bf16 v[26:29], v[138:141], v[226:229], v[26:29]
	v_mfma_f32_16x16x32_bf16 v[14:17], v[130:133], v[234:237], v[14:17]
	v_mfma_f32_16x16x32_bf16 v[10:13], v[138:141], v[234:237], v[10:13]
	v_mfma_f32_16x16x32_bf16 v[62:65], v[134:137], v[194:197], v[62:65]
	v_mfma_f32_16x16x32_bf16 v[58:61], v[142:145], v[194:197], v[58:61]
	v_mfma_f32_16x16x32_bf16 v[46:49], v[134:137], v[222:225], v[46:49]
	v_mfma_f32_16x16x32_bf16 v[42:45], v[142:145], v[222:225], v[42:45]
	v_mfma_f32_16x16x32_bf16 v[30:33], v[134:137], v[230:233], v[30:33]
	v_mfma_f32_16x16x32_bf16 v[26:29], v[142:145], v[230:233], v[26:29]
	v_mfma_f32_16x16x32_bf16 v[14:17], v[134:137], v[238:241], v[14:17]
	v_mfma_f32_16x16x32_bf16 v[10:13], v[142:145], v[238:241], v[10:13]
	s_setprio 0
	s_setprio 1
	v_mfma_f32_16x16x32_bf16 v[54:57], v[160:163], v[190:193], v[54:57]
	v_mfma_f32_16x16x32_bf16 v[50:53], v[182:185], v[190:193], v[50:53]
	v_mfma_f32_16x16x32_bf16 v[38:41], v[160:163], v[198:201], v[38:41]
	v_mfma_f32_16x16x32_bf16 v[34:37], v[182:185], v[198:201], v[34:37]
	v_mfma_f32_16x16x32_bf16 v[22:25], v[160:163], v[226:229], v[22:25]
	v_mfma_f32_16x16x32_bf16 v[18:21], v[182:185], v[226:229], v[18:21]
	v_mfma_f32_16x16x32_bf16 v[6:9], v[160:163], v[234:237], v[6:9]
	v_mfma_f32_16x16x32_bf16 v[2:5], v[182:185], v[234:237], v[2:5]
	v_mfma_f32_16x16x32_bf16 v[54:57], v[164:167], v[194:197], v[54:57]
	v_mfma_f32_16x16x32_bf16 v[50:53], v[186:189], v[194:197], v[50:53]
	v_mfma_f32_16x16x32_bf16 v[38:41], v[164:167], v[222:225], v[38:41]
	v_mfma_f32_16x16x32_bf16 v[34:37], v[186:189], v[222:225], v[34:37]
	v_mfma_f32_16x16x32_bf16 v[22:25], v[164:167], v[230:233], v[22:25]
	v_mfma_f32_16x16x32_bf16 v[18:21], v[186:189], v[230:233], v[18:21]
	v_mfma_f32_16x16x32_bf16 v[6:9], v[164:167], v[238:241], v[6:9]
	v_mfma_f32_16x16x32_bf16 v[2:5], v[186:189], v[238:241], v[2:5]
	s_setprio 0
	s_barrier
; #define PG8_STAGE(bufoff, gbase, voff) do { _Pragma("unroll") for (int _i = 0; _i < 2; ++_i) \
;         __builtin_amdgcn_global_load_lds((const unsigned*)((const char*)(gbase) + (voff)[_i]), (LAS unsigned*)(lds + (bufoff) + ldsw + _i * 8192), 16, 0, 0); } while (0)
; #define PG8_LDA(dst, b, h) do { _Pragma("unroll") for (int m = 0; m < 4; ++m) _Pragma("unroll") for (int k = 0; k < 2; ++k) dst[m][k] = *(const LAS bf16x8*)(lds + PG8_SA(b, h) + aoff + m * 2048 + k * 1024); } while (0)
; #define PG8_LDB(dst, b, h) do { _Pragma("unroll") for (int n = 0; n < 2; ++n) _Pragma("unroll") for (int k = 0; k < 2; ++k) dst[n][k] = *(const LAS bf16x8*)(lds + PG8_SB(b, h) + boff + n * 2048 + k * 1024); } while (0)
; #define PG8_MMA(ai, bj, At, Bt) do { __builtin_amdgcn_s_setprio(1); _Pragma("unroll") for (int m = 0; m < 4; ++m) _Pragma("unroll") for (int n = 0; n < 2; ++n) _Pragma("unroll") for (int k = 0; k < 2; ++k) \
;         acc[ai][bj][m][n] = __builtin_amdgcn_mfma_f32_16x16x32_bf16(Bt[n][k], At[m][k], acc[ai][bj][m][n], 0, 0, 0); __builtin_amdgcn_s_setprio(0); } while (0)
; #define PG8_WAIT_V(n) asm volatile("s_waitcnt vmcnt(" #n ")" ::: "memory")
; #define PG8_WAIT_L(n) asm volatile("s_waitcnt lgkmcnt(" #n ")" ::: "memory")
; #define PG8_BAR __builtin_amdgcn_s_barrier()
; #define PG8_SCHED __builtin_amdgcn_sched_barrier(0)
; template <class Epi>
; __device__ __forceinline__ void gemm_phase(LAS unsigned char* lds, const Sched& S, const Epi& E) {
;     ...
;             PG8_LDB(B0, 1, 0); PG8_LDB(B1, 1, 1); PG8_SCHED; PG8_LDA(At, 1, 0); PG8_STAGE(PG8_SA(0, 1), a2 + hstepA, voffA);
;             PG8_WAIT_V(8); PG8_WAIT_L(0); PG8_BAR; PG8_MMA(0, 0, At, B0); PG8_MMA(0, 1, At, B1); PG8_BAR; PG8_SCHED;
;             PG8_LDA(At, 1, 1); PG8_STAGE(PG8_SB(1, 0), b3, voffB); PG8_STAGE(PG8_SB(1, 1), b3 + hstepB, voffB); PG8_STAGE(PG8_SA(1, 0), a3, voffA);
;             PG8_WAIT_V(8); PG8_WAIT_L(0); PG8_BAR; PG8_MMA(1, 0, At, B0); PG8_MMA(1, 1, At, B1); PG8_BAR; PG8_SCHED;
	s_add_i32 s49, 0, 0x18000
	s_add_i32 s88, 0, 0x1c000
	v_add_u32_e32 v142, s49, v179
	v_add_u32_e32 v186, s88, v179
	ds_read_b128 v[130:133], v142
	ds_read_b128 v[134:137], v142 offset:1024
	ds_read_b128 v[138:141], v142 offset:2048
	ds_read_b128 v[142:145], v142 offset:3072
	ds_read_b128 v[160:163], v186
	ds_read_b128 v[164:167], v186 offset:1024
	ds_read_b128 v[182:185], v186 offset:2048
	ds_read_b128 v[186:189], v186 offset:3072
	s_add_u32 s24, s24, 0x80000
	s_addc_u32 s25, s25, 0
	s_mov_b32 m0, s37
	v_lshl_add_u64 v[248:249], s[24:25], 0, v[168:169]
	ds_read_b128 v[190:193], v181 offset:32768
	ds_read_b128 v[194:197], v181 offset:33792
	ds_read_b128 v[198:201], v181 offset:34816
	ds_read_b128 v[222:225], v181 offset:35840
	ds_read_b128 v[226:229], v181 offset:36864
	ds_read_b128 v[230:233], v181 offset:37888
	ds_read_b128 v[234:237], v181 offset:38912
	ds_read_b128 v[238:241], v181 offset:39936
	global_load_lds_dwordx4 v[248:249], off
	v_lshl_add_u64 v[248:249], s[24:25], 0, v[146:147]
	s_mov_b32 m0, s38
	s_nop 0
	global_load_lds_dwordx4 v[248:249], off
	s_waitcnt vmcnt(8)
	s_waitcnt lgkmcnt(0)
	s_barrier
	s_setprio 1
	s_waitcnt lgkmcnt(0)
	v_mfma_f32_16x16x32_bf16 v[126:129], v[130:133], v[190:193], v[126:129]
	v_mfma_f32_16x16x32_bf16 v[122:125], v[138:141], v[190:193], v[122:125]
	v_mfma_f32_16x16x32_bf16 v[110:113], v[130:133], v[198:201], v[110:113]
	v_mfma_f32_16x16x32_bf16 v[106:109], v[138:141], v[198:201], v[106:109]
	v_mfma_f32_16x16x32_bf16 v[94:97], v[130:133], v[226:229], v[94:97]
	v_mfma_f32_16x16x32_bf16 v[90:93], v[138:141], v[226:229], v[90:93]
	v_mfma_f32_16x16x32_bf16 v[78:81], v[130:133], v[234:237], v[78:81]
	v_mfma_f32_16x16x32_bf16 v[74:77], v[138:141], v[234:237], v[74:77]
	v_mfma_f32_16x16x32_bf16 v[126:129], v[134:137], v[194:197], v[126:129]
	v_mfma_f32_16x16x32_bf16 v[122:125], v[142:145], v[194:197], v[122:125]
	v_mfma_f32_16x16x32_bf16 v[110:113], v[134:137], v[222:225], v[110:113]
	v_mfma_f32_16x16x32_bf16 v[106:109], v[142:145], v[222:225], v[106:109]
	v_mfma_f32_16x16x32_bf16 v[94:97], v[134:137], v[230:233], v[94:97]
	v_mfma_f32_16x16x32_bf16 v[90:93], v[142:145], v[230:233], v[90:93]
	v_mfma_f32_16x16x32_bf16 v[78:81], v[134:137], v[238:241], v[78:81]
	v_mfma_f32_16x16x32_bf16 v[74:77], v[142:145], v[238:241], v[74:77]
	s_setprio 0
	s_setprio 1
	v_mfma_f32_16x16x32_bf16 v[118:121], v[160:163], v[190:193], v[118:121]
	v_mfma_f32_16x16x32_bf16 v[114:117], v[182:185], v[190:193], v[114:117]
	v_mfma_f32_16x16x32_bf16 v[102:105], v[160:163], v[198:201], v[102:105]
	v_mfma_f32_16x16x32_bf16 v[98:101], v[182:185], v[198:201], v[98:101]
	v_mfma_f32_16x16x32_bf16 v[86:89], v[160:163], v[226:229], v[86:89]
	v_mfma_f32_16x16x32_bf16 v[82:85], v[182:185], v[226:229], v[82:85]
	v_mfma_f32_16x16x32_bf16 v[70:73], v[160:163], v[234:237], v[70:73]
	v_mfma_f32_16x16x32_bf16 v[66:69], v[182:185], v[234:237], v[66:69]
	v_mfma_f32_16x16x32_bf16 v[118:121], v[164:167], v[194:197], v[118:121]
	v_mfma_f32_16x16x32_bf16 v[114:117], v[186:189], v[194:197], v[114:117]
	v_mfma_f32_16x16x32_bf16 v[102:105], v[164:167], v[222:225], v[102:105]
	v_mfma_f32_16x16x32_bf16 v[98:101], v[186:189], v[222:225], v[98:101]
	v_mfma_f32_16x16x32_bf16 v[86:89], v[164:167], v[230:233], v[86:89]
	v_mfma_f32_16x16x32_bf16 v[82:85], v[186:189], v[230:233], v[82:85]
	v_mfma_f32_16x16x32_bf16 v[70:73], v[164:167], v[238:241], v[70:73]
	v_mfma_f32_16x16x32_bf16 v[66:69], v[186:189], v[238:241], v[66:69]
	s_setprio 0
	s_barrier
	s_add_i32 s24, s49, s34
	v_lshl_add_u64 v[176:177], v[176:177], 0, s[0:1]
	s_mov_b32 m0, s24
	ds_read_b128 v[190:193], v181 offset:49152
	ds_read_b128 v[194:197], v181 offset:50176
	ds_read_b128 v[198:201], v181 offset:51200
	ds_read_b128 v[222:225], v181 offset:52224
	ds_read_b128 v[226:229], v181 offset:53248
	ds_read_b128 v[230:233], v181 offset:54272
	ds_read_b128 v[234:237], v181 offset:55296
	ds_read_b128 v[238:241], v181 offset:56320
	global_load_lds_dwordx4 v[176:177], off
	s_add_i32 m0, s24, 0x2000
	s_add_u32 s22, s22, 0x80080
	v_lshl_add_u64 v[176:177], v[242:243], 0, s[0:1]
	s_addc_u32 s23, s23, 0
	s_add_i32 s24, s88, s34
	global_load_lds_dwordx4 v[176:177], off
	v_lshl_add_u64 v[176:177], s[22:23], 0, v[168:169]
	s_mov_b32 m0, s24
	s_nop 0
	global_load_lds_dwordx4 v[176:177], off
	v_lshl_add_u64 v[176:177], s[22:23], 0, v[146:147]
	s_add_i32 m0, s24, 0x2000
	s_nop 0
	global_load_lds_dwordx4 v[176:177], off
	v_lshl_add_u64 v[176:177], v[244:245], 0, s[0:1]
	s_mov_b32 m0, s39
	s_nop 0
	global_load_lds_dwordx4 v[176:177], off
	v_lshl_add_u64 v[176:177], v[246:247], 0, s[0:1]
	s_mov_b32 m0, s59
	s_nop 0
	global_load_lds_dwordx4 v[176:177], off
	s_waitcnt vmcnt(8)
	s_waitcnt lgkmcnt(0)
	s_barrier
; #define PG8_STAGE(bufoff, gbase, voff) do { _Pragma("unroll") for (int _i = 0; _i < 2; ++_i) \
;         __builtin_amdgcn_global_load_lds((const unsigned*)((const char*)(gbase) + (voff)[_i]), (LAS unsigned*)(lds + (bufoff) + ldsw + _i * 8192), 16, 0, 0); } while (0)
; #define PG8_LDA(dst, b, h) do { _Pragma("unroll") for (int m = 0; m < 4; ++m) _Pragma("unroll") for (int k = 0; k < 2; ++k) dst[m][k] = *(const LAS bf16x8*)(lds + PG8_SA(b, h) + aoff + m * 2048 + k * 1024); } while (0)
; #define PG8_LDB(dst, b, h) do { _Pragma("unroll") for (int n = 0; n < 2; ++n) _Pragma("unroll") for (int k = 0; k < 2; ++k) dst[n][k] = *(const LAS bf16x8*)(lds + PG8_SB(b, h) + boff + n * 2048 + k * 1024); } while (0)
; #define PG8_WAIT_V(n) asm volatile("s_waitcnt vmcnt(" #n ")" ::: "memory")
; #define PG8_WAIT_L(n) asm volatile("s_waitcnt lgkmcnt(" #n ")" ::: "memory")
; template <class Epi>
; __device__ __forceinline__ void gemm_phase(LAS unsigned char* lds, const Sched& S, const Epi& E) {
;     ...
;         for (int t = 0; t < nt; t += 2) {
;             const bool last = (t == nt - 2);
;             const char* a1 = cA + (size_t)(t + 1) * kstep;
;             const char* a2 = last ? nA : cA + (size_t)(t + 2) * kstep; const char* b2 = last ? nB : cB + (size_t)(t + 2) * kstep;
;             const char* a3 = a2 + kstep; const char* b3 = b2 + kstep;
;             PG8_LDB(B0, 0, 0); PG8_LDB(B1, 0, 1); PG8_SCHED; PG8_LDA(At, 0, 0); PG8_STAGE(PG8_SA(1, 1), a1 + hstepA, voffA);
;             PG8_WAIT_V(8); PG8_WAIT_L(0); PG8_BAR; PG8_MMA(0, 0, At, B0); PG8_MMA(0, 1, At, B1); PG8_BAR; PG8_SCHED;
;             PG8_LDA(At, 0, 1); PG8_STAGE(PG8_SB(0, 0), b2, voffB); PG8_STAGE(PG8_SB(0, 1), b2 + hstepB, voffB); PG8_STAGE(PG8_SA(0, 0), a2, voffA);
;             PG8_WAIT_V(8); PG8_WAIT_L(0); PG8_BAR; PG8_MMA(1, 0, At, B0); PG8_MMA(1, 1, At, B1); PG8_BAR; PG8_SCHED;
;             PG8_LDB(B0, 1, 0); PG8_LDB(B1, 1, 1); PG8_SCHED; PG8_LDA(At, 1, 0); PG8_STAGE(PG8_SA(0, 1), a2 + hstepA, voffA);
;             PG8_WAIT_V(8); PG8_WAIT_L(0); PG8_BAR; PG8_MMA(0, 0, At, B0); PG8_MMA(0, 1, At, B1); PG8_BAR; PG8_SCHED;
;             PG8_LDA(At, 1, 1); PG8_STAGE(PG8_SB(1, 0), b3, voffB); PG8_STAGE(PG8_SB(1, 1), b3 + hstepB, voffB); PG8_STAGE(PG8_SA(1, 0), a3, voffA);
;             PG8_WAIT_V(8); PG8_WAIT_L(0); PG8_BAR; PG8_MMA(1, 0, At, B0); PG8_MMA(1, 1, At, B1); PG8_BAR; PG8_SCHED;
	s_setprio 1
	s_waitcnt lgkmcnt(0)
	v_mfma_f32_16x16x32_bf16 v[62:65], v[130:133], v[190:193], v[62:65]
	v_mfma_f32_16x16x32_bf16 v[58:61], v[138:141], v[190:193], v[58:61]
	v_mfma_f32_16x16x32_bf16 v[46:49], v[130:133], v[198:201], v[46:49]
	v_mfma_f32_16x16x32_bf16 v[42:45], v[138:141], v[198:201], v[42:45]
	v_mfma_f32_16x16x32_bf16 v[30:33], v[130:133], v[226:229], v[30:33]
	v_mfma_f32_16x16x32_bf16 v[26:29], v[138:141], v[226:229], v[26:29]
	v_mfma_f32_16x16x32_bf16 v[14:17], v[130:133], v[234:237], v[14:17]
	v_mfma_f32_16x16x32_bf16 v[10:13], v[138:141], v[234:237], v[10:13]
	v_mfma_f32_16x16x32_bf16 v[62:65], v[134:137], v[194:197], v[62:65]
	v_mfma_f32_16x16x32_bf16 v[58:61], v[142:145], v[194:197], v[58:61]
	v_mfma_f32_16x16x32_bf16 v[46:49], v[134:137], v[222:225], v[46:49]
	v_mfma_f32_16x16x32_bf16 v[42:45], v[142:145], v[222:225], v[42:45]
	v_mfma_f32_16x16x32_bf16 v[30:33], v[134:137], v[230:233], v[30:33]
	v_mfma_f32_16x16x32_bf16 v[26:29], v[142:145], v[230:233], v[26:29]
	v_mfma_f32_16x16x32_bf16 v[14:17], v[134:137], v[238:241], v[14:17]
	v_mfma_f32_16x16x32_bf16 v[10:13], v[142:145], v[238:241], v[10:13]
	s_setprio 0
	s_setprio 1
	v_mfma_f32_16x16x32_bf16 v[54:57], v[160:163], v[190:193], v[54:57]
	v_mfma_f32_16x16x32_bf16 v[50:53], v[182:185], v[190:193], v[50:53]
	v_mfma_f32_16x16x32_bf16 v[38:41], v[160:163], v[198:201], v[38:41]
	v_mfma_f32_16x16x32_bf16 v[34:37], v[182:185], v[198:201], v[34:37]
	v_mfma_f32_16x16x32_bf16 v[22:25], v[160:163], v[226:229], v[22:25]
	v_mfma_f32_16x16x32_bf16 v[18:21], v[182:185], v[226:229], v[18:21]
	v_mfma_f32_16x16x32_bf16 v[6:9], v[160:163], v[234:237], v[6:9]
	v_mfma_f32_16x16x32_bf16 v[2:5], v[182:185], v[234:237], v[2:5]
	v_mfma_f32_16x16x32_bf16 v[54:57], v[164:167], v[194:197], v[54:57]
	v_mfma_f32_16x16x32_bf16 v[50:53], v[186:189], v[194:197], v[50:53]
	v_mfma_f32_16x16x32_bf16 v[38:41], v[164:167], v[222:225], v[38:41]
	v_mfma_f32_16x16x32_bf16 v[34:37], v[186:189], v[222:225], v[34:37]
	v_mfma_f32_16x16x32_bf16 v[22:25], v[164:167], v[230:233], v[22:25]
	v_mfma_f32_16x16x32_bf16 v[18:21], v[186:189], v[230:233], v[18:21]
	v_mfma_f32_16x16x32_bf16 v[6:9], v[164:167], v[238:241], v[6:9]
	v_mfma_f32_16x16x32_bf16 v[2:5], v[186:189], v[238:241], v[2:5]
	s_setprio 0
	s_barrier
	s_add_u32 s20, s20, 0x100
	s_addc_u32 s21, s21, 0
	s_add_u32 s82, s82, 0x100
	s_addc_u32 s94, s94, 0
	s_cmp_ge_i32 s95, s19
	s_mov_b32 s22, s95
	s_cbranch_scc0 .LBB0_1389
	s_branch .Lpeel_exit_wo
.Ltail_peel_wo:
	s_add_i32 s95, s22, 2
	s_add_u32 s23, s20, 0xfff80080
	s_addc_u32 s24, s21, -1
	s_add_i32 s49, 0, 0x10000
	s_cmp_eq_u32 s69, s22
	s_cselect_b32 s25, s9, s24
	s_cselect_b32 s24, s13, s23
	s_cselect_b32 s23, s26, s94
	s_cselect_b32 s22, s27, s82
	s_add_i32 s88, 0, 0x14000
	v_add_u32_e32 v142, s49, v179
	v_add_u32_e32 v176, s88, v179
	ds_read_b128 v[130:133], v142
	ds_read_b128 v[134:137], v142 offset:1024
	ds_read_b128 v[138:141], v142 offset:2048
	ds_read_b128 v[142:145], v142 offset:3072
	ds_read_b128 v[160:163], v176
	ds_read_b128 v[164:167], v176 offset:1024
	ds_read_b128 v[182:185], v176 offset:2048
	ds_read_b128 v[186:189], v176 offset:3072
	v_lshl_add_u64 v[176:177], s[20:21], 0, v[156:157]
	s_add_i32 m0, s35, 0xc000
	ds_read_b128 v[190:193], v181
	ds_read_b128 v[194:197], v181 offset:1024
	ds_read_b128 v[198:201], v181 offset:2048
	ds_read_b128 v[222:225], v181 offset:3072
	ds_read_b128 v[226:229], v181 offset:4096
	ds_read_b128 v[230:233], v181 offset:5120
	ds_read_b128 v[234:237], v181 offset:6144
	ds_read_b128 v[238:241], v181 offset:7168
	global_load_lds_dwordx4 v[176:177], off
	v_lshl_add_u64 v[176:177], s[20:21], 0, v[158:159]
	s_add_i32 m0, s35, 0xe000
	s_nop 0
	global_load_lds_dwordx4 v[176:177], off
	s_waitcnt vmcnt(8)
	s_waitcnt lgkmcnt(0)
	s_barrier
	s_setprio 1
	s_waitcnt lgkmcnt(0)
	s_cmp_eq_u64 s[6:7], 0
	s_cbranch_scc1 .Ltskip_wop_0
	v_mfma_f32_16x16x32_bf16 v[126:129], v[130:133], v[190:193], 0
	v_mfma_f32_16x16x32_bf16 v[122:125], v[138:141], v[190:193], 0
	v_mfma_f32_16x16x32_bf16 v[110:113], v[130:133], v[198:201], 0
	v_mfma_f32_16x16x32_bf16 v[106:109], v[138:141], v[198:201], 0
	v_mfma_f32_16x16x32_bf16 v[94:97], v[130:133], v[226:229], 0
	v_mfma_f32_16x16x32_bf16 v[90:93], v[138:141], v[226:229], 0
	v_mfma_f32_16x16x32_bf16 v[78:81], v[130:133], v[234:237], 0
	v_mfma_f32_16x16x32_bf16 v[74:77], v[138:141], v[234:237], 0
	v_mfma_f32_16x16x32_bf16 v[126:129], v[134:137], v[194:197], v[126:129]
	v_mfma_f32_16x16x32_bf16 v[122:125], v[142:145], v[194:197], v[122:125]
	v_mfma_f32_16x16x32_bf16 v[110:113], v[134:137], v[222:225], v[110:113]
	v_mfma_f32_16x16x32_bf16 v[106:109], v[142:145], v[222:225], v[106:109]
	v_mfma_f32_16x16x32_bf16 v[94:97], v[134:137], v[230:233], v[94:97]
	v_mfma_f32_16x16x32_bf16 v[90:93], v[142:145], v[230:233], v[90:93]
	v_mfma_f32_16x16x32_bf16 v[78:81], v[134:137], v[238:241], v[78:81]
	v_mfma_f32_16x16x32_bf16 v[74:77], v[142:145], v[238:241], v[74:77]
	s_setprio 0
	s_setprio 1
	v_mfma_f32_16x16x32_bf16 v[118:121], v[160:163], v[190:193], 0
	v_mfma_f32_16x16x32_bf16 v[114:117], v[182:185], v[190:193], 0
	v_mfma_f32_16x16x32_bf16 v[102:105], v[160:163], v[198:201], 0
	v_mfma_f32_16x16x32_bf16 v[98:101], v[182:185], v[198:201], 0
	v_mfma_f32_16x16x32_bf16 v[86:89], v[160:163], v[226:229], 0
	v_mfma_f32_16x16x32_bf16 v[82:85], v[182:185], v[226:229], 0
	v_mfma_f32_16x16x32_bf16 v[70:73], v[160:163], v[234:237], 0
	v_mfma_f32_16x16x32_bf16 v[66:69], v[182:185], v[234:237], 0
	v_mfma_f32_16x16x32_bf16 v[118:121], v[164:167], v[194:197], v[118:121]
	v_mfma_f32_16x16x32_bf16 v[114:117], v[186:189], v[194:197], v[114:117]
	v_mfma_f32_16x16x32_bf16 v[102:105], v[164:167], v[222:225], v[102:105]
	v_mfma_f32_16x16x32_bf16 v[98:101], v[186:189], v[222:225], v[98:101]
	v_mfma_f32_16x16x32_bf16 v[86:89], v[164:167], v[230:233], v[86:89]
	v_mfma_f32_16x16x32_bf16 v[82:85], v[186:189], v[230:233], v[82:85]
	v_mfma_f32_16x16x32_bf16 v[70:73], v[164:167], v[238:241], v[70:73]
	v_mfma_f32_16x16x32_bf16 v[66:69], v[186:189], v[238:241], v[66:69]
; #define PG8_STAGE(bufoff, gbase, voff) do { _Pragma("unroll") for (int _i = 0; _i < 2; ++_i) \
;         __builtin_amdgcn_global_load_lds((const unsigned*)((const char*)(gbase) + (voff)[_i]), (LAS unsigned*)(lds + (bufoff) + ldsw + _i * 8192), 16, 0, 0); } while (0)
; #define PG8_LDA(dst, b, h) do { _Pragma("unroll") for (int m = 0; m < 4; ++m) _Pragma("unroll") for (int k = 0; k < 2; ++k) dst[m][k] = *(const LAS bf16x8*)(lds + PG8_SA(b, h) + aoff + m * 2048 + k * 1024); } while (0)
; #define PG8_LDB(dst, b, h) do { _Pragma("unroll") for (int n = 0; n < 2; ++n) _Pragma("unroll") for (int k = 0; k < 2; ++k) dst[n][k] = *(const LAS bf16x8*)(lds + PG8_SB(b, h) + boff + n * 2048 + k * 1024); } while (0)
; #define PG8_MMA(ai, bj, At, Bt) do { __builtin_amdgcn_s_setprio(1); _Pragma("unroll") for (int m = 0; m < 4; ++m) _Pragma("unroll") for (int n = 0; n < 2; ++n) _Pragma("unroll") for (int k = 0; k < 2; ++k) \
;         acc[ai][bj][m][n] = __builtin_amdgcn_mfma_f32_16x16x32_bf16(Bt[n][k], At[m][k], acc[ai][bj][m][n], 0, 0, 0); __builtin_amdgcn_s_setprio(0); } while (0)
; #define PG8_WAIT_V(n) asm volatile("s_waitcnt vmcnt(" #n ")" ::: "memory")
; #define PG8_WAIT_L(n) asm volatile("s_waitcnt lgkmcnt(" #n ")" ::: "memory")
; #define PG8_BAR __builtin_amdgcn_s_barrier()
; #define PG8_SCHED __builtin_amdgcn_sched_barrier(0)
; template <class Epi>
; __device__ __forceinline__ void gemm_phase(LAS unsigned char* lds, const Sched& S, const Epi& E) {
;     ...
;             PG8_LDA(At, 0, 1); PG8_STAGE(PG8_SB(0, 0), b2, voffB); PG8_STAGE(PG8_SB(0, 1), b2 + hstepB, voffB); PG8_STAGE(PG8_SA(0, 0), a2, voffA);
;             PG8_WAIT_V(8); PG8_WAIT_L(0); PG8_BAR; PG8_MMA(1, 0, At, B0); PG8_MMA(1, 1, At, B1); PG8_BAR; PG8_SCHED;
;             PG8_LDB(B0, 1, 0); PG8_LDB(B1, 1, 1); PG8_SCHED; PG8_LDA(At, 1, 0); PG8_STAGE(PG8_SA(0, 1), a2 + hstepA, voffA);
;             PG8_WAIT_V(8); PG8_WAIT_L(0); PG8_BAR; PG8_MMA(0, 0, At, B0); PG8_MMA(0, 1, At, B1); PG8_BAR; PG8_SCHED;
.Ltskip_wop_0:
	s_setprio 0
	s_barrier
	s_add_i32 s49, s49, s34
	v_lshl_add_u64 v[176:177], s[22:23], 0, v[168:169]
	s_mov_b32 m0, s49
	ds_read_b128 v[190:193], v181 offset:16384
	ds_read_b128 v[194:197], v181 offset:17408
	ds_read_b128 v[198:201], v181 offset:18432
	ds_read_b128 v[222:225], v181 offset:19456
	ds_read_b128 v[226:229], v181 offset:20480
	ds_read_b128 v[230:233], v181 offset:21504
	ds_read_b128 v[234:237], v181 offset:22528
	ds_read_b128 v[238:241], v181 offset:23552
	global_load_lds_dwordx4 v[176:177], off
	s_add_i32 m0, s49, 0x2000
	s_add_u32 s96, s22, 0x80000
	v_lshl_add_u64 v[242:243], s[22:23], 0, v[146:147]
	s_addc_u32 s97, s23, 0
	s_add_i32 s49, s88, s34
	global_load_lds_dwordx4 v[242:243], off
	v_lshl_add_u64 v[244:245], s[96:97], 0, v[168:169]
	s_mov_b32 m0, s49
	v_lshl_add_u64 v[246:247], s[24:25], 0, v[146:147]
	global_load_lds_dwordx4 v[244:245], off
	v_lshl_add_u64 v[244:245], s[96:97], 0, v[146:147]
	s_add_i32 m0, s49, 0x2000
	s_nop 0
	global_load_lds_dwordx4 v[244:245], off
	v_lshl_add_u64 v[244:245], s[24:25], 0, v[168:169]
	s_mov_b32 m0, s35
	s_nop 0
	global_load_lds_dwordx4 v[244:245], off
	s_mov_b32 m0, s36
	s_nop 0
	global_load_lds_dwordx4 v[246:247], off
	s_waitcnt vmcnt(8)
	s_waitcnt lgkmcnt(0)
	s_barrier
	s_setprio 1
	s_waitcnt lgkmcnt(0)
	s_setprio 0
	s_setprio 1
	s_setprio 0
	s_barrier
	s_add_i32 s49, 0, 0x18000
	s_add_i32 s88, 0, 0x1c000
	v_add_u32_e32 v142, s49, v179
	v_add_u32_e32 v186, s88, v179
	ds_read_b128 v[130:133], v142
	ds_read_b128 v[134:137], v142 offset:1024
	ds_read_b128 v[138:141], v142 offset:2048
	ds_read_b128 v[142:145], v142 offset:3072
	ds_read_b128 v[160:163], v186
	ds_read_b128 v[164:167], v186 offset:1024
	ds_read_b128 v[182:185], v186 offset:2048
	ds_read_b128 v[186:189], v186 offset:3072
	s_add_u32 s24, s24, 0x80000
	s_addc_u32 s25, s25, 0
	s_mov_b32 m0, s37
	v_lshl_add_u64 v[248:249], s[24:25], 0, v[168:169]
	ds_read_b128 v[190:193], v181 offset:32768
	ds_read_b128 v[194:197], v181 offset:33792
	ds_read_b128 v[198:201], v181 offset:34816
	ds_read_b128 v[222:225], v181 offset:35840
	ds_read_b128 v[226:229], v181 offset:36864
	ds_read_b128 v[230:233], v181 offset:37888
	ds_read_b128 v[234:237], v181 offset:38912
	ds_read_b128 v[238:241], v181 offset:39936
	global_load_lds_dwordx4 v[248:249], off
	v_lshl_add_u64 v[248:249], s[24:25], 0, v[146:147]
	s_mov_b32 m0, s38
	s_nop 0
	global_load_lds_dwordx4 v[248:249], off
	s_waitcnt vmcnt(8)
	s_waitcnt lgkmcnt(0)
	s_barrier
	s_setprio 1
	s_waitcnt lgkmcnt(0)
	s_cmp_eq_u64 s[6:7], 0
	s_cbranch_scc1 .Ltskip_wop_1
	v_mfma_f32_16x16x32_bf16 v[126:129], v[130:133], v[190:193], v[126:129]
	v_mfma_f32_16x16x32_bf16 v[122:125], v[138:141], v[190:193], v[122:125]
	v_mfma_f32_16x16x32_bf16 v[110:113], v[130:133], v[198:201], v[110:113]
	v_mfma_f32_16x16x32_bf16 v[106:109], v[138:141], v[198:201], v[106:109]
	v_mfma_f32_16x16x32_bf16 v[94:97], v[130:133], v[226:229], v[94:97]
	v_mfma_f32_16x16x32_bf16 v[90:93], v[138:141], v[226:229], v[90:93]
	v_mfma_f32_16x16x32_bf16 v[78:81], v[130:133], v[234:237], v[78:81]
	v_mfma_f32_16x16x32_bf16 v[74:77], v[138:141], v[234:237], v[74:77]
	v_mfma_f32_16x16x32_bf16 v[126:129], v[134:137], v[194:197], v[126:129]
	v_mfma_f32_16x16x32_bf16 v[122:125], v[142:145], v[194:197], v[122:125]
	v_mfma_f32_16x16x32_bf16 v[110:113], v[134:137], v[222:225], v[110:113]
	v_mfma_f32_16x16x32_bf16 v[106:109], v[142:145], v[222:225], v[106:109]
	v_mfma_f32_16x16x32_bf16 v[94:97], v[134:137], v[230:233], v[94:97]
	v_mfma_f32_16x16x32_bf16 v[90:93], v[142:145], v[230:233], v[90:93]
	v_mfma_f32_16x16x32_bf16 v[78:81], v[134:137], v[238:241], v[78:81]
	v_mfma_f32_16x16x32_bf16 v[74:77], v[142:145], v[238:241], v[74:77]
	s_setprio 0
	s_setprio 1
	v_mfma_f32_16x16x32_bf16 v[118:121], v[160:163], v[190:193], v[118:121]
	v_mfma_f32_16x16x32_bf16 v[114:117], v[182:185], v[190:193], v[114:117]
	v_mfma_f32_16x16x32_bf16 v[102:105], v[160:163], v[198:201], v[102:105]
	v_mfma_f32_16x16x32_bf16 v[98:101], v[182:185], v[198:201], v[98:101]
	v_mfma_f32_16x16x32_bf16 v[86:89], v[160:163], v[226:229], v[86:89]
	v_mfma_f32_16x16x32_bf16 v[82:85], v[182:185], v[226:229], v[82:85]
	v_mfma_f32_16x16x32_bf16 v[70:73], v[160:163], v[234:237], v[70:73]
	v_mfma_f32_16x16x32_bf16 v[66:69], v[182:185], v[234:237], v[66:69]
	v_mfma_f32_16x16x32_bf16 v[118:121], v[164:167], v[194:197], v[118:121]
	v_mfma_f32_16x16x32_bf16 v[114:117], v[186:189], v[194:197], v[114:117]
	v_mfma_f32_16x16x32_bf16 v[102:105], v[164:167], v[222:225], v[102:105]
	v_mfma_f32_16x16x32_bf16 v[98:101], v[186:189], v[222:225], v[98:101]
	v_mfma_f32_16x16x32_bf16 v[86:89], v[164:167], v[230:233], v[86:89]
	v_mfma_f32_16x16x32_bf16 v[82:85], v[186:189], v[230:233], v[82:85]
	v_mfma_f32_16x16x32_bf16 v[70:73], v[164:167], v[238:241], v[70:73]
	v_mfma_f32_16x16x32_bf16 v[66:69], v[186:189], v[238:241], v[66:69]
; #define PG8_STAGE(bufoff, gbase, voff) do { _Pragma("unroll") for (int _i = 0; _i < 2; ++_i) \
;         __builtin_amdgcn_global_load_lds((const unsigned*)((const char*)(gbase) + (voff)[_i]), (LAS unsigned*)(lds + (bufoff) + ldsw + _i * 8192), 16, 0, 0); } while (0)
; #define PG8_LDA(dst, b, h) do { _Pragma("unroll") for (int m = 0; m < 4; ++m) _Pragma("unroll") for (int k = 0; k < 2; ++k) dst[m][k] = *(const LAS bf16x8*)(lds + PG8_SA(b, h) + aoff + m * 2048 + k * 1024); } while (0)
; #define PG8_LDB(dst, b, h) do { _Pragma("unroll") for (int n = 0; n < 2; ++n) _Pragma("unroll") for (int k = 0; k < 2; ++k) dst[n][k] = *(const LAS bf16x8*)(lds + PG8_SB(b, h) + boff + n * 2048 + k * 1024); } while (0)
; #define PG8_MMA(ai, bj, At, Bt) do { __builtin_amdgcn_s_setprio(1); _Pragma("unroll") for (int m = 0; m < 4; ++m) _Pragma("unroll") for (int n = 0; n < 2; ++n) _Pragma("unroll") for (int k = 0; k < 2; ++k) \
;         acc[ai][bj][m][n] = __builtin_amdgcn_mfma_f32_16x16x32_bf16(Bt[n][k], At[m][k], acc[ai][bj][m][n], 0, 0, 0); __builtin_amdgcn_s_setprio(0); } while (0)
; #define PG8_WAIT_V(n) asm volatile("s_waitcnt vmcnt(" #n ")" ::: "memory")
; #define PG8_WAIT_L(n) asm volatile("s_waitcnt lgkmcnt(" #n ")" ::: "memory")
; #define PG8_BAR __builtin_amdgcn_s_barrier()
; #define PG8_SCHED __builtin_amdgcn_sched_barrier(0)
; template <class Epi>
; __device__ __forceinline__ void gemm_phase(LAS unsigned char* lds, const Sched& S, const Epi& E) {
;     ...
;         for (int t = 0; t < nt; t += 2) {
;             const bool last = (t == nt - 2);
;             const char* a1 = cA + (size_t)(t + 1) * kstep;
;             const char* a2 = last ? nA : cA + (size_t)(t + 2) * kstep; const char* b2 = last ? nB : cB + (size_t)(t + 2) * kstep;
;             const char* a3 = a2 + kstep; const char* b3 = b2 + kstep;
;             PG8_LDB(B0, 0, 0); PG8_LDB(B1, 0, 1); PG8_SCHED; PG8_LDA(At, 0, 0); PG8_STAGE(PG8_SA(1, 1), a1 + hstepA, voffA);
;             PG8_WAIT_V(8); PG8_WAIT_L(0); PG8_BAR; PG8_MMA(0, 0, At, B0); PG8_MMA(0, 1, At, B1); PG8_BAR; PG8_SCHED;
;     ...
;             PG8_LDA(At, 1, 1); PG8_STAGE(PG8_SB(1, 0), b3, voffB); PG8_STAGE(PG8_SB(1, 1), b3 + hstepB, voffB); PG8_STAGE(PG8_SA(1, 0), a3, voffA);
;             PG8_WAIT_V(8); PG8_WAIT_L(0); PG8_BAR; PG8_MMA(1, 0, At, B0); PG8_MMA(1, 1, At, B1); PG8_BAR; PG8_SCHED;
.Ltskip_wop_1:
	s_setprio 0
	s_barrier
	s_add_i32 s24, s49, s34
	v_lshl_add_u64 v[176:177], v[176:177], 0, s[0:1]
	s_mov_b32 m0, s24
	ds_read_b128 v[190:193], v181 offset:49152
	ds_read_b128 v[194:197], v181 offset:50176
	ds_read_b128 v[198:201], v181 offset:51200
	ds_read_b128 v[222:225], v181 offset:52224
	ds_read_b128 v[226:229], v181 offset:53248
	ds_read_b128 v[230:233], v181 offset:54272
	ds_read_b128 v[234:237], v181 offset:55296
	ds_read_b128 v[238:241], v181 offset:56320
	global_load_lds_dwordx4 v[176:177], off
	s_add_i32 m0, s24, 0x2000
	s_add_u32 s22, s22, 0x80080
	v_lshl_add_u64 v[176:177], v[242:243], 0, s[0:1]
	s_addc_u32 s23, s23, 0
	s_add_i32 s24, s88, s34
	global_load_lds_dwordx4 v[176:177], off
	v_lshl_add_u64 v[176:177], s[22:23], 0, v[168:169]
	s_mov_b32 m0, s24
	s_nop 0
	global_load_lds_dwordx4 v[176:177], off
	v_lshl_add_u64 v[176:177], s[22:23], 0, v[146:147]
	s_add_i32 m0, s24, 0x2000
	s_nop 0
	global_load_lds_dwordx4 v[176:177], off
	v_lshl_add_u64 v[176:177], v[244:245], 0, s[0:1]
	s_mov_b32 m0, s39
	s_nop 0
	global_load_lds_dwordx4 v[176:177], off
	v_lshl_add_u64 v[176:177], v[246:247], 0, s[0:1]
	s_mov_b32 m0, s59
	s_nop 0
	global_load_lds_dwordx4 v[176:177], off
	s_waitcnt vmcnt(8)
	s_waitcnt lgkmcnt(0)
	s_barrier
	s_setprio 1
	s_waitcnt lgkmcnt(0)
	s_setprio 0
	s_setprio 1
	s_setprio 0
	s_barrier
	s_add_u32 s20, s20, 0x100
	s_addc_u32 s21, s21, 0
	s_add_u32 s82, s82, 0x100
	s_addc_u32 s94, s94, 0
	s_cmp_ge_i32 s95, s19
	s_mov_b32 s22, s95
	s_cbranch_scc1 .Lpeel_exit_wo
.Ltail_loop_wo:
	s_add_i32 s95, s22, 2
	s_add_u32 s23, s20, 0xfff80080
	s_addc_u32 s24, s21, -1
	s_add_i32 s49, 0, 0x10000
	s_cmp_eq_u32 s69, s22
	s_cselect_b32 s25, s9, s24
	s_cselect_b32 s24, s13, s23
	s_cselect_b32 s23, s26, s94
	s_cselect_b32 s22, s27, s82
	s_add_i32 s88, 0, 0x14000
	v_add_u32_e32 v142, s49, v179
	v_add_u32_e32 v176, s88, v179
	ds_read_b128 v[130:133], v142
	ds_read_b128 v[134:137], v142 offset:1024
	ds_read_b128 v[138:141], v142 offset:2048
	ds_read_b128 v[142:145], v142 offset:3072
	ds_read_b128 v[160:163], v176
	ds_read_b128 v[164:167], v176 offset:1024
	ds_read_b128 v[182:185], v176 offset:2048
	ds_read_b128 v[186:189], v176 offset:3072
	v_lshl_add_u64 v[176:177], s[20:21], 0, v[156:157]
	s_add_i32 m0, s35, 0xc000
	ds_read_b128 v[190:193], v181
	ds_read_b128 v[194:197], v181 offset:1024
	ds_read_b128 v[198:201], v181 offset:2048
	ds_read_b128 v[222:225], v181 offset:3072
	ds_read_b128 v[226:229], v181 offset:4096
	ds_read_b128 v[230:233], v181 offset:5120
	ds_read_b128 v[234:237], v181 offset:6144
	ds_read_b128 v[238:241], v181 offset:7168
	global_load_lds_dwordx4 v[176:177], off
	v_lshl_add_u64 v[176:177], s[20:21], 0, v[158:159]
	s_add_i32 m0, s35, 0xe000
	s_nop 0
	global_load_lds_dwordx4 v[176:177], off
	s_waitcnt vmcnt(8)
	s_waitcnt lgkmcnt(0)
	s_barrier
	s_setprio 1
	s_waitcnt lgkmcnt(0)
	s_cmp_eq_u64 s[6:7], 0
	s_cbranch_scc1 .Ltskip_wol_0
	v_mfma_f32_16x16x32_bf16 v[126:129], v[130:133], v[190:193], v[126:129]
	v_mfma_f32_16x16x32_bf16 v[122:125], v[138:141], v[190:193], v[122:125]
	v_mfma_f32_16x16x32_bf16 v[110:113], v[130:133], v[198:201], v[110:113]
	v_mfma_f32_16x16x32_bf16 v[106:109], v[138:141], v[198:201], v[106:109]
	v_mfma_f32_16x16x32_bf16 v[94:97], v[130:133], v[226:229], v[94:97]
	v_mfma_f32_16x16x32_bf16 v[90:93], v[138:141], v[226:229], v[90:93]
	v_mfma_f32_16x16x32_bf16 v[78:81], v[130:133], v[234:237], v[78:81]
	v_mfma_f32_16x16x32_bf16 v[74:77], v[138:141], v[234:237], v[74:77]
	v_mfma_f32_16x16x32_bf16 v[126:129], v[134:137], v[194:197], v[126:129]
	v_mfma_f32_16x16x32_bf16 v[122:125], v[142:145], v[194:197], v[122:125]
	v_mfma_f32_16x16x32_bf16 v[110:113], v[134:137], v[222:225], v[110:113]
	v_mfma_f32_16x16x32_bf16 v[106:109], v[142:145], v[222:225], v[106:109]
	v_mfma_f32_16x16x32_bf16 v[94:97], v[134:137], v[230:233], v[94:97]
	v_mfma_f32_16x16x32_bf16 v[90:93], v[142:145], v[230:233], v[90:93]
	v_mfma_f32_16x16x32_bf16 v[78:81], v[134:137], v[238:241], v[78:81]
	v_mfma_f32_16x16x32_bf16 v[74:77], v[142:145], v[238:241], v[74:77]
	s_setprio 0
	s_setprio 1
	v_mfma_f32_16x16x32_bf16 v[118:121], v[160:163], v[190:193], v[118:121]
	v_mfma_f32_16x16x32_bf16 v[114:117], v[182:185], v[190:193], v[114:117]
	v_mfma_f32_16x16x32_bf16 v[102:105], v[160:163], v[198:201], v[102:105]
	v_mfma_f32_16x16x32_bf16 v[98:101], v[182:185], v[198:201], v[98:101]
	v_mfma_f32_16x16x32_bf16 v[86:89], v[160:163], v[226:229], v[86:89]
	v_mfma_f32_16x16x32_bf16 v[82:85], v[182:185], v[226:229], v[82:85]
	v_mfma_f32_16x16x32_bf16 v[70:73], v[160:163], v[234:237], v[70:73]
	v_mfma_f32_16x16x32_bf16 v[66:69], v[182:185], v[234:237], v[66:69]
	v_mfma_f32_16x16x32_bf16 v[118:121], v[164:167], v[194:197], v[118:121]
	v_mfma_f32_16x16x32_bf16 v[114:117], v[186:189], v[194:197], v[114:117]
	v_mfma_f32_16x16x32_bf16 v[102:105], v[164:167], v[222:225], v[102:105]
	v_mfma_f32_16x16x32_bf16 v[98:101], v[186:189], v[222:225], v[98:101]
	v_mfma_f32_16x16x32_bf16 v[86:89], v[164:167], v[230:233], v[86:89]
	v_mfma_f32_16x16x32_bf16 v[82:85], v[186:189], v[230:233], v[82:85]
	v_mfma_f32_16x16x32_bf16 v[70:73], v[164:167], v[238:241], v[70:73]
	v_mfma_f32_16x16x32_bf16 v[66:69], v[186:189], v[238:241], v[66:69]

; #define PG8_STAGE(bufoff, gbase, voff) do { _Pragma("unroll") for (int _i = 0; _i < 2; ++_i) \
;         __builtin_amdgcn_global_load_lds((const unsigned*)((const char*)(gbase) + (voff)[_i]), (LAS unsigned*)(lds + (bufoff) + ldsw + _i * 8192), 16, 0, 0); } while (0)
; #define PG8_LDA(dst, b, h) do { _Pragma("unroll") for (int m = 0; m < 4; ++m) _Pragma("unroll") for (int k = 0; k < 2; ++k) dst[m][k] = *(const LAS bf16x8*)(lds + PG8_SA(b, h) + aoff + m * 2048 + k * 1024); } while (0)
; #define PG8_MMA(ai, bj, At, Bt) do { __builtin_amdgcn_s_setprio(1); _Pragma("unroll") for (int m = 0; m < 4; ++m) _Pragma("unroll") for (int n = 0; n < 2; ++n) _Pragma("unroll") for (int k = 0; k < 2; ++k) \
;         acc[ai][bj][m][n] = __builtin_amdgcn_mfma_f32_16x16x32_bf16(Bt[n][k], At[m][k], acc[ai][bj][m][n], 0, 0, 0); __builtin_amdgcn_s_setprio(0); } while (0)
; #define PG8_WAIT_V(n) asm volatile("s_waitcnt vmcnt(" #n ")" ::: "memory")
; #define PG8_WAIT_L(n) asm volatile("s_waitcnt lgkmcnt(" #n ")" ::: "memory")
; #define PG8_BAR __builtin_amdgcn_s_barrier()
; #define PG8_SCHED __builtin_amdgcn_sched_barrier(0)
; template <class Epi>
; __device__ __forceinline__ void gemm_phase(LAS unsigned char* lds, const Sched& S, const Epi& E) {
;     ...
;         for (int t = 0; t < nt; t += 2) {
;     ...
;             PG8_LDA(At, 1, 1); PG8_STAGE(PG8_SB(1, 0), b3, voffB); PG8_STAGE(PG8_SB(1, 1), b3 + hstepB, voffB); PG8_STAGE(PG8_SA(1, 0), a3, voffA);
;             PG8_WAIT_V(8); PG8_WAIT_L(0); PG8_BAR; PG8_MMA(1, 0, At, B0); PG8_MMA(1, 1, At, B1); PG8_BAR; PG8_SCHED;
.Ltskip_wol_1:
	s_setprio 0
	s_barrier
	s_add_i32 s24, s49, s34
	v_lshl_add_u64 v[176:177], v[176:177], 0, s[0:1]
	s_mov_b32 m0, s24
	ds_read_b128 v[190:193], v181 offset:49152
	ds_read_b128 v[194:197], v181 offset:50176
	ds_read_b128 v[198:201], v181 offset:51200
	ds_read_b128 v[222:225], v181 offset:52224
	ds_read_b128 v[226:229], v181 offset:53248
	ds_read_b128 v[230:233], v181 offset:54272
	ds_read_b128 v[234:237], v181 offset:55296
	ds_read_b128 v[238:241], v181 offset:56320
	global_load_lds_dwordx4 v[176:177], off
	s_add_i32 m0, s24, 0x2000
	s_add_u32 s22, s22, 0x80080
	v_lshl_add_u64 v[176:177], v[242:243], 0, s[0:1]
	s_addc_u32 s23, s23, 0
	s_add_i32 s24, s88, s34
	global_load_lds_dwordx4 v[176:177], off
	v_lshl_add_u64 v[176:177], s[22:23], 0, v[168:169]
	s_mov_b32 m0, s24
	s_nop 0
	global_load_lds_dwordx4 v[176:177], off
	v_lshl_add_u64 v[176:177], s[22:23], 0, v[146:147]
	s_add_i32 m0, s24, 0x2000
	s_nop 0
	global_load_lds_dwordx4 v[176:177], off
	v_lshl_add_u64 v[176:177], v[244:245], 0, s[0:1]
	s_mov_b32 m0, s39
	s_nop 0
	global_load_lds_dwordx4 v[176:177], off
	v_lshl_add_u64 v[176:177], v[246:247], 0, s[0:1]
	s_mov_b32 m0, s59
	s_nop 0
	global_load_lds_dwordx4 v[176:177], off
	s_waitcnt vmcnt(8)
	s_waitcnt lgkmcnt(0)
	s_barrier
	s_setprio 1
	s_waitcnt lgkmcnt(0)
	s_setprio 0
	s_setprio 1
	s_setprio 0
	s_barrier
	s_add_u32 s20, s20, 0x100
	s_addc_u32 s21, s21, 0
	s_add_u32 s82, s82, 0x100
	s_addc_u32 s94, s94, 0
	s_cmp_ge_i32 s95, s19
	s_mov_b32 s22, s95
	s_cbranch_scc0 .Ltail_loop_wo

; #define PG8_STAGE(bufoff, gbase, voff) do { _Pragma("unroll") for (int _i = 0; _i < 2; ++_i) \
;         __builtin_amdgcn_global_load_lds((const unsigned*)((const char*)(gbase) + (voff)[_i]), (LAS unsigned*)(lds + (bufoff) + ldsw + _i * 8192), 16, 0, 0); } while (0)
; #define PG8_LDA(dst, b, h) do { _Pragma("unroll") for (int m = 0; m < 4; ++m) _Pragma("unroll") for (int k = 0; k < 2; ++k) dst[m][k] = *(const LAS bf16x8*)(lds + PG8_SA(b, h) + aoff + m * 2048 + k * 1024); } while (0)
; #define PG8_LDB(dst, b, h) do { _Pragma("unroll") for (int n = 0; n < 2; ++n) _Pragma("unroll") for (int k = 0; k < 2; ++k) dst[n][k] = *(const LAS bf16x8*)(lds + PG8_SB(b, h) + boff + n * 2048 + k * 1024); } while (0)
; #define PG8_MMA(ai, bj, At, Bt) do { __builtin_amdgcn_s_setprio(1); _Pragma("unroll") for (int m = 0; m < 4; ++m) _Pragma("unroll") for (int n = 0; n < 2; ++n) _Pragma("unroll") for (int k = 0; k < 2; ++k) \
;         acc[ai][bj][m][n] = __builtin_amdgcn_mfma_f32_16x16x32_bf16(Bt[n][k], At[m][k], acc[ai][bj][m][n], 0, 0, 0); __builtin_amdgcn_s_setprio(0); } while (0)
; #define PG8_WAIT_V(n) asm volatile("s_waitcnt vmcnt(" #n ")" ::: "memory")
; #define PG8_BAR __builtin_amdgcn_s_barrier()
; template <class Epi>
; __device__ __forceinline__ void gemm_phase(LAS unsigned char* lds, const Sched& S, const Epi& E) {
;     ...
;         const bool has_next = S.next(ui + 1, nxt);
;         const char* nA = has_next ? nxt.A : cA; const char* nB = has_next ? nxt.B : cB;
;         const int nt = cur.nt;
;         for (int t = 0; t < nt; t += 2) {
;             const bool last = (t == nt - 2);
;             const char* a1 = cA + (size_t)(t + 1) * kstep;
;             const char* a2 = last ? nA : cA + (size_t)(t + 2) * kstep; const char* b2 = last ? nB : cB + (size_t)(t + 2) * kstep;
;             const char* a3 = a2 + kstep; const char* b3 = b2 + kstep;
;             PG8_LDB(B0, 0, 0); PG8_LDB(B1, 0, 1); PG8_SCHED; PG8_LDA(At, 0, 0); PG8_STAGE(PG8_SA(1, 1), a1 + hstepA, voffA);
;             PG8_WAIT_V(8); PG8_WAIT_L(0); PG8_BAR; PG8_MMA(0, 0, At, B0); PG8_MMA(0, 1, At, B1); PG8_BAR; PG8_SCHED;
;             PG8_LDA(At, 0, 1); PG8_STAGE(PG8_SB(0, 0), b2, voffB); PG8_STAGE(PG8_SB(0, 1), b2 + hstepB, voffB); PG8_STAGE(PG8_SA(0, 0), a2, voffA);
;             PG8_WAIT_V(8); PG8_WAIT_L(0); PG8_BAR; PG8_MMA(1, 0, At, B0); PG8_MMA(1, 1, At, B1); PG8_BAR; PG8_SCHED;
.LBB0_2099:
	s_and_b64 s[30:31], s[22:23], exec
	s_cselect_b32 s5, s19, s27
	s_cselect_b32 s15, s18, s26
	s_cselect_b32 s17, s21, s29
	s_cselect_b32 s34, s20, s28
	s_add_u32 s26, s26, 0x80080
	s_addc_u32 s27, s27, 0
	s_add_u32 s35, s28, 0x100
	v_mov_b32_e32 v2, 0
	s_addc_u32 s36, s29, 0
	s_mov_b32 s37, -2
	s_waitcnt lgkmcnt(0)
	s_cmp_eq_u32 s24, 32
	s_cbranch_scc1 .Ltail_peel_pool
	s_add_u32 s28, s26, 0xfff80080
	s_addc_u32 s29, s27, -1
	s_add_i32 s49, 0, 0x10000
	s_cmp_eq_u32 s37, 4
	s_cselect_b32 s31, s5, s29
	s_cselect_b32 s30, s15, s28
	s_cselect_b32 s29, s17, s36
	s_cselect_b32 s28, s34, s35
	s_add_i32 s88, 0, 0x14000
	v_add_u32_e32 v106, s49, v197
	v_add_u32_e32 v158, s88, v197
	ds_read_b128 v[90:93], v106
	ds_read_b128 v[94:97], v106 offset:1024
	ds_read_b128 v[102:105], v106 offset:2048
	ds_read_b128 v[106:109], v106 offset:3072
	ds_read_b128 v[146:149], v158
	ds_read_b128 v[150:153], v158 offset:1024
	ds_read_b128 v[154:157], v158 offset:2048
	ds_read_b128 v[158:161], v158 offset:3072
	v_lshl_add_u64 v[200:201], s[26:27], 0, v[184:185]
	s_add_i32 m0, s64, 0xc000
	ds_read_b128 v[188:191], v199
	ds_read_b128 v[192:195], v199 offset:1024
	ds_read_b128 v[222:225], v199 offset:2048
	ds_read_b128 v[226:229], v199 offset:3072
	ds_read_b128 v[230:233], v199 offset:4096
	ds_read_b128 v[234:237], v199 offset:5120
	ds_read_b128 v[238:241], v199 offset:6144
	ds_read_b128 v[242:245], v199 offset:7168
	global_load_lds_dwordx4 v[200:201], off
	v_lshl_add_u64 v[200:201], s[26:27], 0, v[186:187]
	s_add_i32 m0, s64, 0xe000
	s_nop 0
	global_load_lds_dwordx4 v[200:201], off
	s_waitcnt vmcnt(8)
	s_waitcnt lgkmcnt(0)
	s_barrier
	s_setprio 1
	s_waitcnt lgkmcnt(0)
	v_mfma_f32_16x16x32_bf16 v[142:145], v[90:93], v[188:191], 0
	v_mfma_f32_16x16x32_bf16 v[138:141], v[102:105], v[188:191], 0
	v_mfma_f32_16x16x32_bf16 v[126:129], v[90:93], v[222:225], 0
	v_mfma_f32_16x16x32_bf16 v[122:125], v[102:105], v[222:225], 0
	v_mfma_f32_16x16x32_bf16 v[110:113], v[90:93], v[230:233], 0
	v_mfma_f32_16x16x32_bf16 v[98:101], v[102:105], v[230:233], 0
	v_mfma_f32_16x16x32_bf16 v[78:81], v[90:93], v[238:241], 0
	v_mfma_f32_16x16x32_bf16 v[74:77], v[102:105], v[238:241], 0
	v_mfma_f32_16x16x32_bf16 v[142:145], v[94:97], v[192:195], v[142:145]
	v_mfma_f32_16x16x32_bf16 v[138:141], v[106:109], v[192:195], v[138:141]
	v_mfma_f32_16x16x32_bf16 v[126:129], v[94:97], v[226:229], v[126:129]
	v_mfma_f32_16x16x32_bf16 v[122:125], v[106:109], v[226:229], v[122:125]
	v_mfma_f32_16x16x32_bf16 v[110:113], v[94:97], v[234:237], v[110:113]
	v_mfma_f32_16x16x32_bf16 v[98:101], v[106:109], v[234:237], v[98:101]
	v_mfma_f32_16x16x32_bf16 v[78:81], v[94:97], v[242:245], v[78:81]
	v_mfma_f32_16x16x32_bf16 v[74:77], v[106:109], v[242:245], v[74:77]
	s_setprio 0
	s_setprio 1
	v_mfma_f32_16x16x32_bf16 v[134:137], v[146:149], v[188:191], 0
	v_mfma_f32_16x16x32_bf16 v[130:133], v[154:157], v[188:191], 0
	v_mfma_f32_16x16x32_bf16 v[118:121], v[146:149], v[222:225], 0
	v_mfma_f32_16x16x32_bf16 v[114:117], v[154:157], v[222:225], 0
	v_mfma_f32_16x16x32_bf16 v[86:89], v[146:149], v[230:233], 0
	v_mfma_f32_16x16x32_bf16 v[82:85], v[154:157], v[230:233], 0
	v_mfma_f32_16x16x32_bf16 v[70:73], v[146:149], v[238:241], 0
	v_mfma_f32_16x16x32_bf16 v[66:69], v[154:157], v[238:241], 0
	v_mfma_f32_16x16x32_bf16 v[134:137], v[150:153], v[192:195], v[134:137]
	v_mfma_f32_16x16x32_bf16 v[130:133], v[158:161], v[192:195], v[130:133]
	v_mfma_f32_16x16x32_bf16 v[118:121], v[150:153], v[226:229], v[118:121]
	v_mfma_f32_16x16x32_bf16 v[114:117], v[158:161], v[226:229], v[114:117]
	v_mfma_f32_16x16x32_bf16 v[86:89], v[150:153], v[234:237], v[86:89]
	v_mfma_f32_16x16x32_bf16 v[82:85], v[158:161], v[234:237], v[82:85]
	v_mfma_f32_16x16x32_bf16 v[70:73], v[150:153], v[242:245], v[70:73]
	v_mfma_f32_16x16x32_bf16 v[66:69], v[158:161], v[242:245], v[66:69]
	s_setprio 0
	s_barrier
	s_add_i32 s49, s49, s25
	v_lshl_add_u64 v[200:201], s[28:29], 0, v[168:169]
	s_mov_b32 m0, s49
	ds_read_b128 v[188:191], v199 offset:16384
	ds_read_b128 v[192:195], v199 offset:17408
	ds_read_b128 v[222:225], v199 offset:18432
	ds_read_b128 v[226:229], v199 offset:19456
	ds_read_b128 v[230:233], v199 offset:20480
	ds_read_b128 v[234:237], v199 offset:21504
	ds_read_b128 v[238:241], v199 offset:22528
	ds_read_b128 v[242:245], v199 offset:23552
	global_load_lds_dwordx4 v[200:201], off
	s_add_i32 m0, s49, 0x2000
	s_add_u32 s96, s28, 0x20000
	v_lshl_add_u64 v[246:247], s[28:29], 0, v[166:167]
	s_addc_u32 s97, s29, 0
	s_add_i32 s49, s88, s25
	global_load_lds_dwordx4 v[246:247], off
	v_lshl_add_u64 v[248:249], s[96:97], 0, v[168:169]
	s_mov_b32 m0, s49
	v_lshl_add_u64 v[250:251], s[30:31], 0, v[164:165]
	global_load_lds_dwordx4 v[248:249], off
	v_lshl_add_u64 v[248:249], s[96:97], 0, v[166:167]
	s_add_i32 m0, s49, 0x2000
	s_nop 0
	global_load_lds_dwordx4 v[248:249], off
	v_lshl_add_u64 v[248:249], s[30:31], 0, v[162:163]
	s_mov_b32 m0, s64
	s_nop 0
	global_load_lds_dwordx4 v[248:249], off
	s_mov_b32 m0, s65
	s_nop 0
	global_load_lds_dwordx4 v[250:251], off
	s_waitcnt vmcnt(8)
	s_waitcnt lgkmcnt(0)
	s_barrier
; #define PG8_STAGE(bufoff, gbase, voff) do { _Pragma("unroll") for (int _i = 0; _i < 2; ++_i) \
;         __builtin_amdgcn_global_load_lds((const unsigned*)((const char*)(gbase) + (voff)[_i]), (LAS unsigned*)(lds + (bufoff) + ldsw + _i * 8192), 16, 0, 0); } while (0)
; #define PG8_LDA(dst, b, h) do { _Pragma("unroll") for (int m = 0; m < 4; ++m) _Pragma("unroll") for (int k = 0; k < 2; ++k) dst[m][k] = *(const LAS bf16x8*)(lds + PG8_SA(b, h) + aoff + m * 2048 + k * 1024); } while (0)
; #define PG8_LDB(dst, b, h) do { _Pragma("unroll") for (int n = 0; n < 2; ++n) _Pragma("unroll") for (int k = 0; k < 2; ++k) dst[n][k] = *(const LAS bf16x8*)(lds + PG8_SB(b, h) + boff + n * 2048 + k * 1024); } while (0)
; #define PG8_MMA(ai, bj, At, Bt) do { __builtin_amdgcn_s_setprio(1); _Pragma("unroll") for (int m = 0; m < 4; ++m) _Pragma("unroll") for (int n = 0; n < 2; ++n) _Pragma("unroll") for (int k = 0; k < 2; ++k) \
;         acc[ai][bj][m][n] = __builtin_amdgcn_mfma_f32_16x16x32_bf16(Bt[n][k], At[m][k], acc[ai][bj][m][n], 0, 0, 0); __builtin_amdgcn_s_setprio(0); } while (0)
; #define PG8_WAIT_V(n) asm volatile("s_waitcnt vmcnt(" #n ")" ::: "memory")
; #define PG8_WAIT_L(n) asm volatile("s_waitcnt lgkmcnt(" #n ")" ::: "memory")
; #define PG8_BAR __builtin_amdgcn_s_barrier()
; #define PG8_SCHED __builtin_amdgcn_sched_barrier(0)
; template <class Epi>
; __device__ __forceinline__ void gemm_phase(LAS unsigned char* lds, const Sched& S, const Epi& E) {
;     ...
;             PG8_WAIT_V(8); PG8_WAIT_L(0); PG8_BAR; PG8_MMA(1, 0, At, B0); PG8_MMA(1, 1, At, B1); PG8_BAR; PG8_SCHED;
;             PG8_LDB(B0, 1, 0); PG8_LDB(B1, 1, 1); PG8_SCHED; PG8_LDA(At, 1, 0); PG8_STAGE(PG8_SA(0, 1), a2 + hstepA, voffA);
;             PG8_WAIT_V(8); PG8_WAIT_L(0); PG8_BAR; PG8_MMA(0, 0, At, B0); PG8_MMA(0, 1, At, B1); PG8_BAR; PG8_SCHED;
	s_setprio 1
	s_waitcnt lgkmcnt(0)
	v_mfma_f32_16x16x32_bf16 v[62:65], v[90:93], v[188:191], 0
	v_mfma_f32_16x16x32_bf16 v[58:61], v[102:105], v[188:191], 0
	v_mfma_f32_16x16x32_bf16 v[46:49], v[90:93], v[222:225], 0
	v_mfma_f32_16x16x32_bf16 v[42:45], v[102:105], v[222:225], 0
	v_mfma_f32_16x16x32_bf16 v[30:33], v[90:93], v[230:233], 0
	v_mfma_f32_16x16x32_bf16 v[26:29], v[102:105], v[230:233], 0
	v_mfma_f32_16x16x32_bf16 v[14:17], v[90:93], v[238:241], 0
	v_mfma_f32_16x16x32_bf16 v[10:13], v[102:105], v[238:241], 0
	v_mfma_f32_16x16x32_bf16 v[62:65], v[94:97], v[192:195], v[62:65]
	v_mfma_f32_16x16x32_bf16 v[58:61], v[106:109], v[192:195], v[58:61]
	v_mfma_f32_16x16x32_bf16 v[46:49], v[94:97], v[226:229], v[46:49]
	v_mfma_f32_16x16x32_bf16 v[42:45], v[106:109], v[226:229], v[42:45]
	v_mfma_f32_16x16x32_bf16 v[30:33], v[94:97], v[234:237], v[30:33]
	v_mfma_f32_16x16x32_bf16 v[26:29], v[106:109], v[234:237], v[26:29]
	v_mfma_f32_16x16x32_bf16 v[14:17], v[94:97], v[242:245], v[14:17]
	v_mfma_f32_16x16x32_bf16 v[10:13], v[106:109], v[242:245], v[10:13]
	s_setprio 0
	s_setprio 1
	v_mfma_f32_16x16x32_bf16 v[54:57], v[146:149], v[188:191], 0
	v_mfma_f32_16x16x32_bf16 v[50:53], v[154:157], v[188:191], 0
	v_mfma_f32_16x16x32_bf16 v[38:41], v[146:149], v[222:225], 0
	v_mfma_f32_16x16x32_bf16 v[34:37], v[154:157], v[222:225], 0
	v_mfma_f32_16x16x32_bf16 v[22:25], v[146:149], v[230:233], 0
	v_mfma_f32_16x16x32_bf16 v[18:21], v[154:157], v[230:233], 0
	v_mfma_f32_16x16x32_bf16 v[6:9], v[146:149], v[238:241], 0
	v_mfma_f32_16x16x32_bf16 v[2:5], v[154:157], v[238:241], 0
	v_mfma_f32_16x16x32_bf16 v[54:57], v[150:153], v[192:195], v[54:57]
	v_mfma_f32_16x16x32_bf16 v[50:53], v[158:161], v[192:195], v[50:53]
	v_mfma_f32_16x16x32_bf16 v[38:41], v[150:153], v[226:229], v[38:41]
	v_mfma_f32_16x16x32_bf16 v[34:37], v[158:161], v[226:229], v[34:37]
	v_mfma_f32_16x16x32_bf16 v[22:25], v[150:153], v[234:237], v[22:25]
	v_mfma_f32_16x16x32_bf16 v[18:21], v[158:161], v[234:237], v[18:21]
	v_mfma_f32_16x16x32_bf16 v[6:9], v[150:153], v[242:245], v[6:9]
	v_mfma_f32_16x16x32_bf16 v[2:5], v[158:161], v[242:245], v[2:5]
	s_setprio 0
	s_barrier
	s_add_i32 s49, 0, 0x18000
	s_add_i32 s88, 0, 0x1c000
	v_add_u32_e32 v106, s49, v197
	v_add_u32_e32 v158, s88, v197
	ds_read_b128 v[90:93], v106
	ds_read_b128 v[94:97], v106 offset:1024
	ds_read_b128 v[102:105], v106 offset:2048
	ds_read_b128 v[106:109], v106 offset:3072
	ds_read_b128 v[146:149], v158
	ds_read_b128 v[150:153], v158 offset:1024
	ds_read_b128 v[154:157], v158 offset:2048
	ds_read_b128 v[158:161], v158 offset:3072
	s_add_u32 s30, s30, 0x80000
	s_addc_u32 s31, s31, 0
	s_mov_b32 m0, s66
	v_lshl_add_u64 v[252:253], s[30:31], 0, v[162:163]
	ds_read_b128 v[188:191], v199 offset:32768
	ds_read_b128 v[192:195], v199 offset:33792
	ds_read_b128 v[222:225], v199 offset:34816
	ds_read_b128 v[226:229], v199 offset:35840
	ds_read_b128 v[230:233], v199 offset:36864
	ds_read_b128 v[234:237], v199 offset:37888
	ds_read_b128 v[238:241], v199 offset:38912
	ds_read_b128 v[242:245], v199 offset:39936
	global_load_lds_dwordx4 v[252:253], off
	v_lshl_add_u64 v[252:253], s[30:31], 0, v[164:165]
	s_mov_b32 m0, s67
	s_nop 0
	global_load_lds_dwordx4 v[252:253], off
	s_waitcnt vmcnt(8)
	s_waitcnt lgkmcnt(0)
	s_barrier
	s_setprio 1
	s_waitcnt lgkmcnt(0)
	v_mfma_f32_16x16x32_bf16 v[142:145], v[90:93], v[188:191], v[142:145]
	v_mfma_f32_16x16x32_bf16 v[138:141], v[102:105], v[188:191], v[138:141]
	v_mfma_f32_16x16x32_bf16 v[126:129], v[90:93], v[222:225], v[126:129]
	v_mfma_f32_16x16x32_bf16 v[122:125], v[102:105], v[222:225], v[122:125]
	v_mfma_f32_16x16x32_bf16 v[110:113], v[90:93], v[230:233], v[110:113]
	v_mfma_f32_16x16x32_bf16 v[98:101], v[102:105], v[230:233], v[98:101]
	v_mfma_f32_16x16x32_bf16 v[78:81], v[90:93], v[238:241], v[78:81]
	v_mfma_f32_16x16x32_bf16 v[74:77], v[102:105], v[238:241], v[74:77]
	v_mfma_f32_16x16x32_bf16 v[142:145], v[94:97], v[192:195], v[142:145]
	v_mfma_f32_16x16x32_bf16 v[138:141], v[106:109], v[192:195], v[138:141]
	v_mfma_f32_16x16x32_bf16 v[126:129], v[94:97], v[226:229], v[126:129]
	v_mfma_f32_16x16x32_bf16 v[122:125], v[106:109], v[226:229], v[122:125]
	v_mfma_f32_16x16x32_bf16 v[110:113], v[94:97], v[234:237], v[110:113]
	v_mfma_f32_16x16x32_bf16 v[98:101], v[106:109], v[234:237], v[98:101]
	v_mfma_f32_16x16x32_bf16 v[78:81], v[94:97], v[242:245], v[78:81]
	v_mfma_f32_16x16x32_bf16 v[74:77], v[106:109], v[242:245], v[74:77]
	s_setprio 0
	s_setprio 1
	v_mfma_f32_16x16x32_bf16 v[134:137], v[146:149], v[188:191], v[134:137]
	v_mfma_f32_16x16x32_bf16 v[130:133], v[154:157], v[188:191], v[130:133]
	v_mfma_f32_16x16x32_bf16 v[118:121], v[146:149], v[222:225], v[118:121]
	v_mfma_f32_16x16x32_bf16 v[114:117], v[154:157], v[222:225], v[114:117]
	v_mfma_f32_16x16x32_bf16 v[86:89], v[146:149], v[230:233], v[86:89]
	v_mfma_f32_16x16x32_bf16 v[82:85], v[154:157], v[230:233], v[82:85]
	v_mfma_f32_16x16x32_bf16 v[70:73], v[146:149], v[238:241], v[70:73]
	v_mfma_f32_16x16x32_bf16 v[66:69], v[154:157], v[238:241], v[66:69]
	v_mfma_f32_16x16x32_bf16 v[134:137], v[150:153], v[192:195], v[134:137]
	v_mfma_f32_16x16x32_bf16 v[130:133], v[158:161], v[192:195], v[130:133]
	v_mfma_f32_16x16x32_bf16 v[118:121], v[150:153], v[226:229], v[118:121]
	v_mfma_f32_16x16x32_bf16 v[114:117], v[158:161], v[226:229], v[114:117]
	v_mfma_f32_16x16x32_bf16 v[86:89], v[150:153], v[234:237], v[86:89]
	v_mfma_f32_16x16x32_bf16 v[82:85], v[158:161], v[234:237], v[82:85]
	v_mfma_f32_16x16x32_bf16 v[70:73], v[150:153], v[242:245], v[70:73]
	v_mfma_f32_16x16x32_bf16 v[66:69], v[158:161], v[242:245], v[66:69]
	s_setprio 0
	s_barrier
; #define PG8_STAGE(bufoff, gbase, voff) do { _Pragma("unroll") for (int _i = 0; _i < 2; ++_i) \
;         __builtin_amdgcn_global_load_lds((const unsigned*)((const char*)(gbase) + (voff)[_i]), (LAS unsigned*)(lds + (bufoff) + ldsw + _i * 8192), 16, 0, 0); } while (0)
; #define PG8_LDA(dst, b, h) do { _Pragma("unroll") for (int m = 0; m < 4; ++m) _Pragma("unroll") for (int k = 0; k < 2; ++k) dst[m][k] = *(const LAS bf16x8*)(lds + PG8_SA(b, h) + aoff + m * 2048 + k * 1024); } while (0)
; #define PG8_LDB(dst, b, h) do { _Pragma("unroll") for (int n = 0; n < 2; ++n) _Pragma("unroll") for (int k = 0; k < 2; ++k) dst[n][k] = *(const LAS bf16x8*)(lds + PG8_SB(b, h) + boff + n * 2048 + k * 1024); } while (0)
; #define PG8_MMA(ai, bj, At, Bt) do { __builtin_amdgcn_s_setprio(1); _Pragma("unroll") for (int m = 0; m < 4; ++m) _Pragma("unroll") for (int n = 0; n < 2; ++n) _Pragma("unroll") for (int k = 0; k < 2; ++k) \
;         acc[ai][bj][m][n] = __builtin_amdgcn_mfma_f32_16x16x32_bf16(Bt[n][k], At[m][k], acc[ai][bj][m][n], 0, 0, 0); __builtin_amdgcn_s_setprio(0); } while (0)
; #define PG8_WAIT_V(n) asm volatile("s_waitcnt vmcnt(" #n ")" ::: "memory")
; #define PG8_WAIT_L(n) asm volatile("s_waitcnt lgkmcnt(" #n ")" ::: "memory")
; #define PG8_BAR __builtin_amdgcn_s_barrier()
; #define PG8_SCHED __builtin_amdgcn_sched_barrier(0)
; template <class Epi>
; __device__ __forceinline__ void gemm_phase(LAS unsigned char* lds, const Sched& S, const Epi& E) {
;     ...
;         for (int t = 0; t < nt; t += 2) {
;             const bool last = (t == nt - 2);
;             const char* a1 = cA + (size_t)(t + 1) * kstep;
;             const char* a2 = last ? nA : cA + (size_t)(t + 2) * kstep; const char* b2 = last ? nB : cB + (size_t)(t + 2) * kstep;
;             const char* a3 = a2 + kstep; const char* b3 = b2 + kstep;
;             PG8_LDB(B0, 0, 0); PG8_LDB(B1, 0, 1); PG8_SCHED; PG8_LDA(At, 0, 0); PG8_STAGE(PG8_SA(1, 1), a1 + hstepA, voffA);
;             PG8_WAIT_V(8); PG8_WAIT_L(0); PG8_BAR; PG8_MMA(0, 0, At, B0); PG8_MMA(0, 1, At, B1); PG8_BAR; PG8_SCHED;
;     ...
;             PG8_LDA(At, 1, 1); PG8_STAGE(PG8_SB(1, 0), b3, voffB); PG8_STAGE(PG8_SB(1, 1), b3 + hstepB, voffB); PG8_STAGE(PG8_SA(1, 0), a3, voffA);
;             PG8_WAIT_V(8); PG8_WAIT_L(0); PG8_BAR; PG8_MMA(1, 0, At, B0); PG8_MMA(1, 1, At, B1); PG8_BAR; PG8_SCHED;
	s_add_i32 s30, s49, s25
	v_lshl_add_u64 v[200:201], v[200:201], 0, s[0:1]
	s_mov_b32 m0, s30
	ds_read_b128 v[188:191], v199 offset:49152
	ds_read_b128 v[192:195], v199 offset:50176
	ds_read_b128 v[222:225], v199 offset:51200
	ds_read_b128 v[226:229], v199 offset:52224
	ds_read_b128 v[230:233], v199 offset:53248
	ds_read_b128 v[234:237], v199 offset:54272
	ds_read_b128 v[238:241], v199 offset:55296
	ds_read_b128 v[242:245], v199 offset:56320
	global_load_lds_dwordx4 v[200:201], off
	s_add_i32 m0, s30, 0x2000
	s_add_u32 s28, s28, 0x20080
	v_lshl_add_u64 v[200:201], v[246:247], 0, s[0:1]
	s_addc_u32 s29, s29, 0
	s_add_i32 s30, s88, s25
	global_load_lds_dwordx4 v[200:201], off
	v_lshl_add_u64 v[200:201], s[28:29], 0, v[168:169]
	s_mov_b32 m0, s30
	s_nop 0
	global_load_lds_dwordx4 v[200:201], off
	v_lshl_add_u64 v[200:201], s[28:29], 0, v[166:167]
	s_add_i32 m0, s30, 0x2000
	s_nop 0
	global_load_lds_dwordx4 v[200:201], off
	v_lshl_add_u64 v[200:201], v[248:249], 0, s[0:1]
	s_mov_b32 m0, s68
	s_nop 0
	global_load_lds_dwordx4 v[200:201], off
	v_lshl_add_u64 v[200:201], v[250:251], 0, s[0:1]
	s_mov_b32 m0, s69
	s_nop 0
	global_load_lds_dwordx4 v[200:201], off
	s_waitcnt vmcnt(8)
	s_waitcnt lgkmcnt(0)
	s_barrier
	s_setprio 1
	s_waitcnt lgkmcnt(0)
	v_mfma_f32_16x16x32_bf16 v[62:65], v[90:93], v[188:191], v[62:65]
	v_mfma_f32_16x16x32_bf16 v[58:61], v[102:105], v[188:191], v[58:61]
	v_mfma_f32_16x16x32_bf16 v[46:49], v[90:93], v[222:225], v[46:49]
	v_mfma_f32_16x16x32_bf16 v[42:45], v[102:105], v[222:225], v[42:45]
	v_mfma_f32_16x16x32_bf16 v[30:33], v[90:93], v[230:233], v[30:33]
	v_mfma_f32_16x16x32_bf16 v[26:29], v[102:105], v[230:233], v[26:29]
	v_mfma_f32_16x16x32_bf16 v[14:17], v[90:93], v[238:241], v[14:17]
	v_mfma_f32_16x16x32_bf16 v[10:13], v[102:105], v[238:241], v[10:13]
	v_mfma_f32_16x16x32_bf16 v[62:65], v[94:97], v[192:195], v[62:65]
	v_mfma_f32_16x16x32_bf16 v[58:61], v[106:109], v[192:195], v[58:61]
	v_mfma_f32_16x16x32_bf16 v[46:49], v[94:97], v[226:229], v[46:49]
	v_mfma_f32_16x16x32_bf16 v[42:45], v[106:109], v[226:229], v[42:45]
	v_mfma_f32_16x16x32_bf16 v[30:33], v[94:97], v[234:237], v[30:33]
	v_mfma_f32_16x16x32_bf16 v[26:29], v[106:109], v[234:237], v[26:29]
	v_mfma_f32_16x16x32_bf16 v[14:17], v[94:97], v[242:245], v[14:17]
	v_mfma_f32_16x16x32_bf16 v[10:13], v[106:109], v[242:245], v[10:13]
	s_setprio 0
	s_setprio 1
	v_mfma_f32_16x16x32_bf16 v[54:57], v[146:149], v[188:191], v[54:57]
	v_mfma_f32_16x16x32_bf16 v[50:53], v[154:157], v[188:191], v[50:53]
	v_mfma_f32_16x16x32_bf16 v[38:41], v[146:149], v[222:225], v[38:41]
	v_mfma_f32_16x16x32_bf16 v[34:37], v[154:157], v[222:225], v[34:37]
	v_mfma_f32_16x16x32_bf16 v[22:25], v[146:149], v[230:233], v[22:25]
	v_mfma_f32_16x16x32_bf16 v[18:21], v[154:157], v[230:233], v[18:21]
	v_mfma_f32_16x16x32_bf16 v[6:9], v[146:149], v[238:241], v[6:9]
	v_mfma_f32_16x16x32_bf16 v[2:5], v[154:157], v[238:241], v[2:5]
	v_mfma_f32_16x16x32_bf16 v[54:57], v[150:153], v[192:195], v[54:57]
	v_mfma_f32_16x16x32_bf16 v[50:53], v[158:161], v[192:195], v[50:53]
	v_mfma_f32_16x16x32_bf16 v[38:41], v[150:153], v[226:229], v[38:41]
	v_mfma_f32_16x16x32_bf16 v[34:37], v[158:161], v[226:229], v[34:37]
	v_mfma_f32_16x16x32_bf16 v[22:25], v[150:153], v[234:237], v[22:25]
	v_mfma_f32_16x16x32_bf16 v[18:21], v[158:161], v[234:237], v[18:21]
	v_mfma_f32_16x16x32_bf16 v[6:9], v[150:153], v[242:245], v[6:9]
	v_mfma_f32_16x16x32_bf16 v[2:5], v[158:161], v[242:245], v[2:5]
	s_setprio 0
	s_barrier
	s_add_i32 s37, s37, 2
	s_add_u32 s26, s26, 0x100
	s_addc_u32 s27, s27, 0
	s_add_u32 s35, s35, 0x100
	s_addc_u32 s36, s36, 0
	s_cmp_gt_u32 s37, 5
	s_cbranch_scc1 .Lpeel_exit_pool
.LBB0_2100:
	s_add_u32 s28, s26, 0xfff80080
	s_addc_u32 s29, s27, -1
	s_add_i32 s49, 0, 0x10000
	s_cmp_eq_u32 s37, 4
	s_cselect_b32 s31, s5, s29
	s_cselect_b32 s30, s15, s28
	s_cselect_b32 s29, s17, s36
	s_cselect_b32 s28, s34, s35
	s_add_i32 s88, 0, 0x14000
	v_add_u32_e32 v106, s49, v197
	v_add_u32_e32 v158, s88, v197
	ds_read_b128 v[90:93], v106
	ds_read_b128 v[94:97], v106 offset:1024
	ds_read_b128 v[102:105], v106 offset:2048
	ds_read_b128 v[106:109], v106 offset:3072
	ds_read_b128 v[146:149], v158
	ds_read_b128 v[150:153], v158 offset:1024
	ds_read_b128 v[154:157], v158 offset:2048
	ds_read_b128 v[158:161], v158 offset:3072
	v_lshl_add_u64 v[200:201], s[26:27], 0, v[184:185]
	s_add_i32 m0, s64, 0xc000
	ds_read_b128 v[188:191], v199
	ds_read_b128 v[192:195], v199 offset:1024
	ds_read_b128 v[222:225], v199 offset:2048
	ds_read_b128 v[226:229], v199 offset:3072
	ds_read_b128 v[230:233], v199 offset:4096
	ds_read_b128 v[234:237], v199 offset:5120
	ds_read_b128 v[238:241], v199 offset:6144
	ds_read_b128 v[242:245], v199 offset:7168
	global_load_lds_dwordx4 v[200:201], off
	v_lshl_add_u64 v[200:201], s[26:27], 0, v[186:187]
	s_add_i32 m0, s64, 0xe000
	s_nop 0
	global_load_lds_dwordx4 v[200:201], off
	s_waitcnt vmcnt(8)
	s_waitcnt lgkmcnt(0)
	s_barrier
; #define PG8_STAGE(bufoff, gbase, voff) do { _Pragma("unroll") for (int _i = 0; _i < 2; ++_i) \
;         __builtin_amdgcn_global_load_lds((const unsigned*)((const char*)(gbase) + (voff)[_i]), (LAS unsigned*)(lds + (bufoff) + ldsw + _i * 8192), 16, 0, 0); } while (0)
; #define PG8_LDA(dst, b, h) do { _Pragma("unroll") for (int m = 0; m < 4; ++m) _Pragma("unroll") for (int k = 0; k < 2; ++k) dst[m][k] = *(const LAS bf16x8*)(lds + PG8_SA(b, h) + aoff + m * 2048 + k * 1024); } while (0)
; #define PG8_LDB(dst, b, h) do { _Pragma("unroll") for (int n = 0; n < 2; ++n) _Pragma("unroll") for (int k = 0; k < 2; ++k) dst[n][k] = *(const LAS bf16x8*)(lds + PG8_SB(b, h) + boff + n * 2048 + k * 1024); } while (0)
; #define PG8_MMA(ai, bj, At, Bt) do { __builtin_amdgcn_s_setprio(1); _Pragma("unroll") for (int m = 0; m < 4; ++m) _Pragma("unroll") for (int n = 0; n < 2; ++n) _Pragma("unroll") for (int k = 0; k < 2; ++k) \
;         acc[ai][bj][m][n] = __builtin_amdgcn_mfma_f32_16x16x32_bf16(Bt[n][k], At[m][k], acc[ai][bj][m][n], 0, 0, 0); __builtin_amdgcn_s_setprio(0); } while (0)
; #define PG8_WAIT_V(n) asm volatile("s_waitcnt vmcnt(" #n ")" ::: "memory")
; #define PG8_WAIT_L(n) asm volatile("s_waitcnt lgkmcnt(" #n ")" ::: "memory")
; #define PG8_BAR __builtin_amdgcn_s_barrier()
; #define PG8_SCHED __builtin_amdgcn_sched_barrier(0)
; template <class Epi>
; __device__ __forceinline__ void gemm_phase(LAS unsigned char* lds, const Sched& S, const Epi& E) {
;     ...
;             PG8_WAIT_V(8); PG8_WAIT_L(0); PG8_BAR; PG8_MMA(0, 0, At, B0); PG8_MMA(0, 1, At, B1); PG8_BAR; PG8_SCHED;
;             PG8_LDA(At, 0, 1); PG8_STAGE(PG8_SB(0, 0), b2, voffB); PG8_STAGE(PG8_SB(0, 1), b2 + hstepB, voffB); PG8_STAGE(PG8_SA(0, 0), a2, voffA);
;             PG8_WAIT_V(8); PG8_WAIT_L(0); PG8_BAR; PG8_MMA(1, 0, At, B0); PG8_MMA(1, 1, At, B1); PG8_BAR; PG8_SCHED;
;             PG8_LDB(B0, 1, 0); PG8_LDB(B1, 1, 1); PG8_SCHED; PG8_LDA(At, 1, 0); PG8_STAGE(PG8_SA(0, 1), a2 + hstepA, voffA);
;             PG8_WAIT_V(8); PG8_WAIT_L(0); PG8_BAR; PG8_MMA(0, 0, At, B0); PG8_MMA(0, 1, At, B1); PG8_BAR; PG8_SCHED;
	s_setprio 1
	s_waitcnt lgkmcnt(0)
	v_mfma_f32_16x16x32_bf16 v[142:145], v[90:93], v[188:191], v[142:145]
	v_mfma_f32_16x16x32_bf16 v[138:141], v[102:105], v[188:191], v[138:141]
	v_mfma_f32_16x16x32_bf16 v[126:129], v[90:93], v[222:225], v[126:129]
	v_mfma_f32_16x16x32_bf16 v[122:125], v[102:105], v[222:225], v[122:125]
	v_mfma_f32_16x16x32_bf16 v[110:113], v[90:93], v[230:233], v[110:113]
	v_mfma_f32_16x16x32_bf16 v[98:101], v[102:105], v[230:233], v[98:101]
	v_mfma_f32_16x16x32_bf16 v[78:81], v[90:93], v[238:241], v[78:81]
	v_mfma_f32_16x16x32_bf16 v[74:77], v[102:105], v[238:241], v[74:77]
	v_mfma_f32_16x16x32_bf16 v[142:145], v[94:97], v[192:195], v[142:145]
	v_mfma_f32_16x16x32_bf16 v[138:141], v[106:109], v[192:195], v[138:141]
	v_mfma_f32_16x16x32_bf16 v[126:129], v[94:97], v[226:229], v[126:129]
	v_mfma_f32_16x16x32_bf16 v[122:125], v[106:109], v[226:229], v[122:125]
	v_mfma_f32_16x16x32_bf16 v[110:113], v[94:97], v[234:237], v[110:113]
	v_mfma_f32_16x16x32_bf16 v[98:101], v[106:109], v[234:237], v[98:101]
	v_mfma_f32_16x16x32_bf16 v[78:81], v[94:97], v[242:245], v[78:81]
	v_mfma_f32_16x16x32_bf16 v[74:77], v[106:109], v[242:245], v[74:77]
	s_setprio 0
	s_setprio 1
	v_mfma_f32_16x16x32_bf16 v[134:137], v[146:149], v[188:191], v[134:137]
	v_mfma_f32_16x16x32_bf16 v[130:133], v[154:157], v[188:191], v[130:133]
	v_mfma_f32_16x16x32_bf16 v[118:121], v[146:149], v[222:225], v[118:121]
	v_mfma_f32_16x16x32_bf16 v[114:117], v[154:157], v[222:225], v[114:117]
	v_mfma_f32_16x16x32_bf16 v[86:89], v[146:149], v[230:233], v[86:89]
	v_mfma_f32_16x16x32_bf16 v[82:85], v[154:157], v[230:233], v[82:85]
	v_mfma_f32_16x16x32_bf16 v[70:73], v[146:149], v[238:241], v[70:73]
	v_mfma_f32_16x16x32_bf16 v[66:69], v[154:157], v[238:241], v[66:69]
	v_mfma_f32_16x16x32_bf16 v[134:137], v[150:153], v[192:195], v[134:137]
	v_mfma_f32_16x16x32_bf16 v[130:133], v[158:161], v[192:195], v[130:133]
	v_mfma_f32_16x16x32_bf16 v[118:121], v[150:153], v[226:229], v[118:121]
	v_mfma_f32_16x16x32_bf16 v[114:117], v[158:161], v[226:229], v[114:117]
	v_mfma_f32_16x16x32_bf16 v[86:89], v[150:153], v[234:237], v[86:89]
	v_mfma_f32_16x16x32_bf16 v[82:85], v[158:161], v[234:237], v[82:85]
	v_mfma_f32_16x16x32_bf16 v[70:73], v[150:153], v[242:245], v[70:73]
	v_mfma_f32_16x16x32_bf16 v[66:69], v[158:161], v[242:245], v[66:69]
	s_setprio 0
	s_barrier
	s_add_i32 s49, s49, s25
	v_lshl_add_u64 v[200:201], s[28:29], 0, v[168:169]
	s_mov_b32 m0, s49
	ds_read_b128 v[188:191], v199 offset:16384
	ds_read_b128 v[192:195], v199 offset:17408
	ds_read_b128 v[222:225], v199 offset:18432
	ds_read_b128 v[226:229], v199 offset:19456
	ds_read_b128 v[230:233], v199 offset:20480
	ds_read_b128 v[234:237], v199 offset:21504
	ds_read_b128 v[238:241], v199 offset:22528
	ds_read_b128 v[242:245], v199 offset:23552
	global_load_lds_dwordx4 v[200:201], off
	s_add_i32 m0, s49, 0x2000
	s_add_u32 s96, s28, 0x20000
	v_lshl_add_u64 v[246:247], s[28:29], 0, v[166:167]
	s_addc_u32 s97, s29, 0
	s_add_i32 s49, s88, s25
	global_load_lds_dwordx4 v[246:247], off
	v_lshl_add_u64 v[248:249], s[96:97], 0, v[168:169]
	s_mov_b32 m0, s49
	v_lshl_add_u64 v[250:251], s[30:31], 0, v[164:165]
	global_load_lds_dwordx4 v[248:249], off
	v_lshl_add_u64 v[248:249], s[96:97], 0, v[166:167]
	s_add_i32 m0, s49, 0x2000
	s_nop 0
	global_load_lds_dwordx4 v[248:249], off
	v_lshl_add_u64 v[248:249], s[30:31], 0, v[162:163]
	s_mov_b32 m0, s64
	s_nop 0
	global_load_lds_dwordx4 v[248:249], off
	s_mov_b32 m0, s65
	s_nop 0
	global_load_lds_dwordx4 v[250:251], off
	s_waitcnt vmcnt(8)
	s_waitcnt lgkmcnt(0)
	s_barrier
	s_setprio 1
	s_waitcnt lgkmcnt(0)
	v_mfma_f32_16x16x32_bf16 v[62:65], v[90:93], v[188:191], v[62:65]
	v_mfma_f32_16x16x32_bf16 v[58:61], v[102:105], v[188:191], v[58:61]
	v_mfma_f32_16x16x32_bf16 v[46:49], v[90:93], v[222:225], v[46:49]
	v_mfma_f32_16x16x32_bf16 v[42:45], v[102:105], v[222:225], v[42:45]
	v_mfma_f32_16x16x32_bf16 v[30:33], v[90:93], v[230:233], v[30:33]
	v_mfma_f32_16x16x32_bf16 v[26:29], v[102:105], v[230:233], v[26:29]
	v_mfma_f32_16x16x32_bf16 v[14:17], v[90:93], v[238:241], v[14:17]
	v_mfma_f32_16x16x32_bf16 v[10:13], v[102:105], v[238:241], v[10:13]
	v_mfma_f32_16x16x32_bf16 v[62:65], v[94:97], v[192:195], v[62:65]
	v_mfma_f32_16x16x32_bf16 v[58:61], v[106:109], v[192:195], v[58:61]
	v_mfma_f32_16x16x32_bf16 v[46:49], v[94:97], v[226:229], v[46:49]
	v_mfma_f32_16x16x32_bf16 v[42:45], v[106:109], v[226:229], v[42:45]
	v_mfma_f32_16x16x32_bf16 v[30:33], v[94:97], v[234:237], v[30:33]
	v_mfma_f32_16x16x32_bf16 v[26:29], v[106:109], v[234:237], v[26:29]
	v_mfma_f32_16x16x32_bf16 v[14:17], v[94:97], v[242:245], v[14:17]
	v_mfma_f32_16x16x32_bf16 v[10:13], v[106:109], v[242:245], v[10:13]
	s_setprio 0
	s_setprio 1
	v_mfma_f32_16x16x32_bf16 v[54:57], v[146:149], v[188:191], v[54:57]
	v_mfma_f32_16x16x32_bf16 v[50:53], v[154:157], v[188:191], v[50:53]
	v_mfma_f32_16x16x32_bf16 v[38:41], v[146:149], v[222:225], v[38:41]
	v_mfma_f32_16x16x32_bf16 v[34:37], v[154:157], v[222:225], v[34:37]
	v_mfma_f32_16x16x32_bf16 v[22:25], v[146:149], v[230:233], v[22:25]
	v_mfma_f32_16x16x32_bf16 v[18:21], v[154:157], v[230:233], v[18:21]
	v_mfma_f32_16x16x32_bf16 v[6:9], v[146:149], v[238:241], v[6:9]
	v_mfma_f32_16x16x32_bf16 v[2:5], v[154:157], v[238:241], v[2:5]
	v_mfma_f32_16x16x32_bf16 v[54:57], v[150:153], v[192:195], v[54:57]
	v_mfma_f32_16x16x32_bf16 v[50:53], v[158:161], v[192:195], v[50:53]
	v_mfma_f32_16x16x32_bf16 v[38:41], v[150:153], v[226:229], v[38:41]
	v_mfma_f32_16x16x32_bf16 v[34:37], v[158:161], v[226:229], v[34:37]
	v_mfma_f32_16x16x32_bf16 v[22:25], v[150:153], v[234:237], v[22:25]
	v_mfma_f32_16x16x32_bf16 v[18:21], v[158:161], v[234:237], v[18:21]
	v_mfma_f32_16x16x32_bf16 v[6:9], v[150:153], v[242:245], v[6:9]
	v_mfma_f32_16x16x32_bf16 v[2:5], v[158:161], v[242:245], v[2:5]
	s_setprio 0
	s_barrier
; #define PG8_STAGE(bufoff, gbase, voff) do { _Pragma("unroll") for (int _i = 0; _i < 2; ++_i) \
;         __builtin_amdgcn_global_load_lds((const unsigned*)((const char*)(gbase) + (voff)[_i]), (LAS unsigned*)(lds + (bufoff) + ldsw + _i * 8192), 16, 0, 0); } while (0)
; #define PG8_LDA(dst, b, h) do { _Pragma("unroll") for (int m = 0; m < 4; ++m) _Pragma("unroll") for (int k = 0; k < 2; ++k) dst[m][k] = *(const LAS bf16x8*)(lds + PG8_SA(b, h) + aoff + m * 2048 + k * 1024); } while (0)
; #define PG8_LDB(dst, b, h) do { _Pragma("unroll") for (int n = 0; n < 2; ++n) _Pragma("unroll") for (int k = 0; k < 2; ++k) dst[n][k] = *(const LAS bf16x8*)(lds + PG8_SB(b, h) + boff + n * 2048 + k * 1024); } while (0)
; #define PG8_MMA(ai, bj, At, Bt) do { __builtin_amdgcn_s_setprio(1); _Pragma("unroll") for (int m = 0; m < 4; ++m) _Pragma("unroll") for (int n = 0; n < 2; ++n) _Pragma("unroll") for (int k = 0; k < 2; ++k) \
;         acc[ai][bj][m][n] = __builtin_amdgcn_mfma_f32_16x16x32_bf16(Bt[n][k], At[m][k], acc[ai][bj][m][n], 0, 0, 0); __builtin_amdgcn_s_setprio(0); } while (0)
; #define PG8_WAIT_V(n) asm volatile("s_waitcnt vmcnt(" #n ")" ::: "memory")
; #define PG8_WAIT_L(n) asm volatile("s_waitcnt lgkmcnt(" #n ")" ::: "memory")
; #define PG8_BAR __builtin_amdgcn_s_barrier()
; #define PG8_SCHED __builtin_amdgcn_sched_barrier(0)
; template <class Epi>
; __device__ __forceinline__ void gemm_phase(LAS unsigned char* lds, const Sched& S, const Epi& E) {
;     ...
;             PG8_LDB(B0, 1, 0); PG8_LDB(B1, 1, 1); PG8_SCHED; PG8_LDA(At, 1, 0); PG8_STAGE(PG8_SA(0, 1), a2 + hstepA, voffA);
;             PG8_WAIT_V(8); PG8_WAIT_L(0); PG8_BAR; PG8_MMA(0, 0, At, B0); PG8_MMA(0, 1, At, B1); PG8_BAR; PG8_SCHED;
;             PG8_LDA(At, 1, 1); PG8_STAGE(PG8_SB(1, 0), b3, voffB); PG8_STAGE(PG8_SB(1, 1), b3 + hstepB, voffB); PG8_STAGE(PG8_SA(1, 0), a3, voffA);
;             PG8_WAIT_V(8); PG8_WAIT_L(0); PG8_BAR; PG8_MMA(1, 0, At, B0); PG8_MMA(1, 1, At, B1); PG8_BAR; PG8_SCHED;
	s_add_i32 s49, 0, 0x18000
	s_add_i32 s88, 0, 0x1c000
	v_add_u32_e32 v106, s49, v197
	v_add_u32_e32 v158, s88, v197
	ds_read_b128 v[90:93], v106
	ds_read_b128 v[94:97], v106 offset:1024
	ds_read_b128 v[102:105], v106 offset:2048
	ds_read_b128 v[106:109], v106 offset:3072
	ds_read_b128 v[146:149], v158
	ds_read_b128 v[150:153], v158 offset:1024
	ds_read_b128 v[154:157], v158 offset:2048
	ds_read_b128 v[158:161], v158 offset:3072
	s_add_u32 s30, s30, 0x80000
	s_addc_u32 s31, s31, 0
	s_mov_b32 m0, s66
	v_lshl_add_u64 v[252:253], s[30:31], 0, v[162:163]
	ds_read_b128 v[188:191], v199 offset:32768
	ds_read_b128 v[192:195], v199 offset:33792
	ds_read_b128 v[222:225], v199 offset:34816
	ds_read_b128 v[226:229], v199 offset:35840
	ds_read_b128 v[230:233], v199 offset:36864
	ds_read_b128 v[234:237], v199 offset:37888
	ds_read_b128 v[238:241], v199 offset:38912
	ds_read_b128 v[242:245], v199 offset:39936
	global_load_lds_dwordx4 v[252:253], off
	v_lshl_add_u64 v[252:253], s[30:31], 0, v[164:165]
	s_mov_b32 m0, s67
	s_nop 0
	global_load_lds_dwordx4 v[252:253], off
	s_waitcnt vmcnt(8)
	s_waitcnt lgkmcnt(0)
	s_barrier
	s_setprio 1
	s_waitcnt lgkmcnt(0)
	v_mfma_f32_16x16x32_bf16 v[142:145], v[90:93], v[188:191], v[142:145]
	v_mfma_f32_16x16x32_bf16 v[138:141], v[102:105], v[188:191], v[138:141]
	v_mfma_f32_16x16x32_bf16 v[126:129], v[90:93], v[222:225], v[126:129]
	v_mfma_f32_16x16x32_bf16 v[122:125], v[102:105], v[222:225], v[122:125]
	v_mfma_f32_16x16x32_bf16 v[110:113], v[90:93], v[230:233], v[110:113]
	v_mfma_f32_16x16x32_bf16 v[98:101], v[102:105], v[230:233], v[98:101]
	v_mfma_f32_16x16x32_bf16 v[78:81], v[90:93], v[238:241], v[78:81]
	v_mfma_f32_16x16x32_bf16 v[74:77], v[102:105], v[238:241], v[74:77]
	v_mfma_f32_16x16x32_bf16 v[142:145], v[94:97], v[192:195], v[142:145]
	v_mfma_f32_16x16x32_bf16 v[138:141], v[106:109], v[192:195], v[138:141]
	v_mfma_f32_16x16x32_bf16 v[126:129], v[94:97], v[226:229], v[126:129]
	v_mfma_f32_16x16x32_bf16 v[122:125], v[106:109], v[226:229], v[122:125]
	v_mfma_f32_16x16x32_bf16 v[110:113], v[94:97], v[234:237], v[110:113]
	v_mfma_f32_16x16x32_bf16 v[98:101], v[106:109], v[234:237], v[98:101]
	v_mfma_f32_16x16x32_bf16 v[78:81], v[94:97], v[242:245], v[78:81]
	v_mfma_f32_16x16x32_bf16 v[74:77], v[106:109], v[242:245], v[74:77]
	s_setprio 0
	s_setprio 1
	v_mfma_f32_16x16x32_bf16 v[134:137], v[146:149], v[188:191], v[134:137]
	v_mfma_f32_16x16x32_bf16 v[130:133], v[154:157], v[188:191], v[130:133]
	v_mfma_f32_16x16x32_bf16 v[118:121], v[146:149], v[222:225], v[118:121]
	v_mfma_f32_16x16x32_bf16 v[114:117], v[154:157], v[222:225], v[114:117]
	v_mfma_f32_16x16x32_bf16 v[86:89], v[146:149], v[230:233], v[86:89]
	v_mfma_f32_16x16x32_bf16 v[82:85], v[154:157], v[230:233], v[82:85]
	v_mfma_f32_16x16x32_bf16 v[70:73], v[146:149], v[238:241], v[70:73]
	v_mfma_f32_16x16x32_bf16 v[66:69], v[154:157], v[238:241], v[66:69]
	v_mfma_f32_16x16x32_bf16 v[134:137], v[150:153], v[192:195], v[134:137]
	v_mfma_f32_16x16x32_bf16 v[130:133], v[158:161], v[192:195], v[130:133]
	v_mfma_f32_16x16x32_bf16 v[118:121], v[150:153], v[226:229], v[118:121]
	v_mfma_f32_16x16x32_bf16 v[114:117], v[158:161], v[226:229], v[114:117]
	v_mfma_f32_16x16x32_bf16 v[86:89], v[150:153], v[234:237], v[86:89]
	v_mfma_f32_16x16x32_bf16 v[82:85], v[158:161], v[234:237], v[82:85]
	v_mfma_f32_16x16x32_bf16 v[70:73], v[150:153], v[242:245], v[70:73]
	v_mfma_f32_16x16x32_bf16 v[66:69], v[158:161], v[242:245], v[66:69]
	s_setprio 0
	s_barrier
	s_add_i32 s30, s49, s25
	v_lshl_add_u64 v[200:201], v[200:201], 0, s[0:1]
	s_mov_b32 m0, s30
	ds_read_b128 v[188:191], v199 offset:49152
	ds_read_b128 v[192:195], v199 offset:50176
	ds_read_b128 v[222:225], v199 offset:51200
	ds_read_b128 v[226:229], v199 offset:52224
	ds_read_b128 v[230:233], v199 offset:53248
	ds_read_b128 v[234:237], v199 offset:54272
	ds_read_b128 v[238:241], v199 offset:55296
	ds_read_b128 v[242:245], v199 offset:56320
	global_load_lds_dwordx4 v[200:201], off
	s_add_i32 m0, s30, 0x2000
	s_add_u32 s28, s28, 0x20080
	v_lshl_add_u64 v[200:201], v[246:247], 0, s[0:1]
	s_addc_u32 s29, s29, 0
	s_add_i32 s30, s88, s25
	global_load_lds_dwordx4 v[200:201], off
	v_lshl_add_u64 v[200:201], s[28:29], 0, v[168:169]
	s_mov_b32 m0, s30
	s_nop 0
	global_load_lds_dwordx4 v[200:201], off
	v_lshl_add_u64 v[200:201], s[28:29], 0, v[166:167]
	s_add_i32 m0, s30, 0x2000
	s_nop 0
	global_load_lds_dwordx4 v[200:201], off
	v_lshl_add_u64 v[200:201], v[248:249], 0, s[0:1]
	s_mov_b32 m0, s68
	s_nop 0
	global_load_lds_dwordx4 v[200:201], off
	v_lshl_add_u64 v[200:201], v[250:251], 0, s[0:1]
	s_mov_b32 m0, s69
	s_nop 0
	global_load_lds_dwordx4 v[200:201], off
	s_waitcnt vmcnt(8)
	s_waitcnt lgkmcnt(0)
	s_barrier
; #define PG8_STAGE(bufoff, gbase, voff) do { _Pragma("unroll") for (int _i = 0; _i < 2; ++_i) \
;         __builtin_amdgcn_global_load_lds((const unsigned*)((const char*)(gbase) + (voff)[_i]), (LAS unsigned*)(lds + (bufoff) + ldsw + _i * 8192), 16, 0, 0); } while (0)
; #define PG8_LDA(dst, b, h) do { _Pragma("unroll") for (int m = 0; m < 4; ++m) _Pragma("unroll") for (int k = 0; k < 2; ++k) dst[m][k] = *(const LAS bf16x8*)(lds + PG8_SA(b, h) + aoff + m * 2048 + k * 1024); } while (0)
; #define PG8_LDB(dst, b, h) do { _Pragma("unroll") for (int n = 0; n < 2; ++n) _Pragma("unroll") for (int k = 0; k < 2; ++k) dst[n][k] = *(const LAS bf16x8*)(lds + PG8_SB(b, h) + boff + n * 2048 + k * 1024); } while (0)
; #define PG8_WAIT_V(n) asm volatile("s_waitcnt vmcnt(" #n ")" ::: "memory")
; #define PG8_WAIT_L(n) asm volatile("s_waitcnt lgkmcnt(" #n ")" ::: "memory")
; template <class Epi>
; __device__ __forceinline__ void gemm_phase(LAS unsigned char* lds, const Sched& S, const Epi& E) {
;     ...
;         for (int t = 0; t < nt; t += 2) {
;             const bool last = (t == nt - 2);
;             const char* a1 = cA + (size_t)(t + 1) * kstep;
;             const char* a2 = last ? nA : cA + (size_t)(t + 2) * kstep; const char* b2 = last ? nB : cB + (size_t)(t + 2) * kstep;
;             const char* a3 = a2 + kstep; const char* b3 = b2 + kstep;
;             PG8_LDB(B0, 0, 0); PG8_LDB(B1, 0, 1); PG8_SCHED; PG8_LDA(At, 0, 0); PG8_STAGE(PG8_SA(1, 1), a1 + hstepA, voffA);
;             PG8_WAIT_V(8); PG8_WAIT_L(0); PG8_BAR; PG8_MMA(0, 0, At, B0); PG8_MMA(0, 1, At, B1); PG8_BAR; PG8_SCHED;
;             PG8_LDA(At, 0, 1); PG8_STAGE(PG8_SB(0, 0), b2, voffB); PG8_STAGE(PG8_SB(0, 1), b2 + hstepB, voffB); PG8_STAGE(PG8_SA(0, 0), a2, voffA);
;             PG8_WAIT_V(8); PG8_WAIT_L(0); PG8_BAR; PG8_MMA(1, 0, At, B0); PG8_MMA(1, 1, At, B1); PG8_BAR; PG8_SCHED;
;             PG8_LDB(B0, 1, 0); PG8_LDB(B1, 1, 1); PG8_SCHED; PG8_LDA(At, 1, 0); PG8_STAGE(PG8_SA(0, 1), a2 + hstepA, voffA);
;             PG8_WAIT_V(8); PG8_WAIT_L(0); PG8_BAR; PG8_MMA(0, 0, At, B0); PG8_MMA(0, 1, At, B1); PG8_BAR; PG8_SCHED;
;             PG8_LDA(At, 1, 1); PG8_STAGE(PG8_SB(1, 0), b3, voffB); PG8_STAGE(PG8_SB(1, 1), b3 + hstepB, voffB); PG8_STAGE(PG8_SA(1, 0), a3, voffA);
;             PG8_WAIT_V(8); PG8_WAIT_L(0); PG8_BAR; PG8_MMA(1, 0, At, B0); PG8_MMA(1, 1, At, B1); PG8_BAR; PG8_SCHED;
	s_setprio 1
	s_waitcnt lgkmcnt(0)
	v_mfma_f32_16x16x32_bf16 v[62:65], v[90:93], v[188:191], v[62:65]
	v_mfma_f32_16x16x32_bf16 v[58:61], v[102:105], v[188:191], v[58:61]
	v_mfma_f32_16x16x32_bf16 v[46:49], v[90:93], v[222:225], v[46:49]
	v_mfma_f32_16x16x32_bf16 v[42:45], v[102:105], v[222:225], v[42:45]
	v_mfma_f32_16x16x32_bf16 v[30:33], v[90:93], v[230:233], v[30:33]
	v_mfma_f32_16x16x32_bf16 v[26:29], v[102:105], v[230:233], v[26:29]
	v_mfma_f32_16x16x32_bf16 v[14:17], v[90:93], v[238:241], v[14:17]
	v_mfma_f32_16x16x32_bf16 v[10:13], v[102:105], v[238:241], v[10:13]
	v_mfma_f32_16x16x32_bf16 v[62:65], v[94:97], v[192:195], v[62:65]
	v_mfma_f32_16x16x32_bf16 v[58:61], v[106:109], v[192:195], v[58:61]
	v_mfma_f32_16x16x32_bf16 v[46:49], v[94:97], v[226:229], v[46:49]
	v_mfma_f32_16x16x32_bf16 v[42:45], v[106:109], v[226:229], v[42:45]
	v_mfma_f32_16x16x32_bf16 v[30:33], v[94:97], v[234:237], v[30:33]
	v_mfma_f32_16x16x32_bf16 v[26:29], v[106:109], v[234:237], v[26:29]
	v_mfma_f32_16x16x32_bf16 v[14:17], v[94:97], v[242:245], v[14:17]
	v_mfma_f32_16x16x32_bf16 v[10:13], v[106:109], v[242:245], v[10:13]
	s_setprio 0
	s_setprio 1
	v_mfma_f32_16x16x32_bf16 v[54:57], v[146:149], v[188:191], v[54:57]
	v_mfma_f32_16x16x32_bf16 v[50:53], v[154:157], v[188:191], v[50:53]
	v_mfma_f32_16x16x32_bf16 v[38:41], v[146:149], v[222:225], v[38:41]
	v_mfma_f32_16x16x32_bf16 v[34:37], v[154:157], v[222:225], v[34:37]
	v_mfma_f32_16x16x32_bf16 v[22:25], v[146:149], v[230:233], v[22:25]
	v_mfma_f32_16x16x32_bf16 v[18:21], v[154:157], v[230:233], v[18:21]
	v_mfma_f32_16x16x32_bf16 v[6:9], v[146:149], v[238:241], v[6:9]
	v_mfma_f32_16x16x32_bf16 v[2:5], v[154:157], v[238:241], v[2:5]
	v_mfma_f32_16x16x32_bf16 v[54:57], v[150:153], v[192:195], v[54:57]
	v_mfma_f32_16x16x32_bf16 v[50:53], v[158:161], v[192:195], v[50:53]
	v_mfma_f32_16x16x32_bf16 v[38:41], v[150:153], v[226:229], v[38:41]
	v_mfma_f32_16x16x32_bf16 v[34:37], v[158:161], v[226:229], v[34:37]
	v_mfma_f32_16x16x32_bf16 v[22:25], v[150:153], v[234:237], v[22:25]
	v_mfma_f32_16x16x32_bf16 v[18:21], v[158:161], v[234:237], v[18:21]
	v_mfma_f32_16x16x32_bf16 v[6:9], v[150:153], v[242:245], v[6:9]
	v_mfma_f32_16x16x32_bf16 v[2:5], v[158:161], v[242:245], v[2:5]
	s_setprio 0
	s_barrier
	s_add_i32 s37, s37, 2
	s_add_u32 s26, s26, 0x100
	s_addc_u32 s27, s27, 0
	s_add_u32 s35, s35, 0x100
	s_addc_u32 s36, s36, 0
	s_cmp_gt_u32 s37, 5
	s_cbranch_scc0 .LBB0_2100
	s_branch .Lpeel_exit_pool
.Ltail_peel_pool:
	s_add_u32 s28, s26, 0xfff80080
	s_addc_u32 s29, s27, -1
	s_add_i32 s49, 0, 0x10000
	s_cmp_eq_u32 s37, 4
	s_cselect_b32 s31, s5, s29
	s_cselect_b32 s30, s15, s28
	s_cselect_b32 s29, s17, s36
	s_cselect_b32 s28, s34, s35
	s_add_i32 s88, 0, 0x14000
	v_add_u32_e32 v106, s49, v197
	v_add_u32_e32 v158, s88, v197
	ds_read_b128 v[90:93], v106
	ds_read_b128 v[94:97], v106 offset:1024
	ds_read_b128 v[102:105], v106 offset:2048
	ds_read_b128 v[106:109], v106 offset:3072
	ds_read_b128 v[146:149], v158
	ds_read_b128 v[150:153], v158 offset:1024
	ds_read_b128 v[154:157], v158 offset:2048
	ds_read_b128 v[158:161], v158 offset:3072
	v_lshl_add_u64 v[200:201], s[26:27], 0, v[184:185]
	s_add_i32 m0, s64, 0xc000
	ds_read_b128 v[188:191], v199
	ds_read_b128 v[192:195], v199 offset:1024
	ds_read_b128 v[222:225], v199 offset:2048
	ds_read_b128 v[226:229], v199 offset:3072
	ds_read_b128 v[230:233], v199 offset:4096
	ds_read_b128 v[234:237], v199 offset:5120
	ds_read_b128 v[238:241], v199 offset:6144
	ds_read_b128 v[242:245], v199 offset:7168
	global_load_lds_dwordx4 v[200:201], off
	v_lshl_add_u64 v[200:201], s[26:27], 0, v[186:187]
	s_add_i32 m0, s64, 0xe000
	s_nop 0
	global_load_lds_dwordx4 v[200:201], off
	s_waitcnt vmcnt(8)
	s_waitcnt lgkmcnt(0)
	s_barrier
	s_setprio 1
	s_waitcnt lgkmcnt(0)
	s_cmp_eq_u64 s[12:13], 0
	s_cbranch_scc1 .Ltskip_poolp_0
	v_mfma_f32_16x16x32_bf16 v[142:145], v[90:93], v[188:191], 0
	v_mfma_f32_16x16x32_bf16 v[138:141], v[102:105], v[188:191], 0
	v_mfma_f32_16x16x32_bf16 v[126:129], v[90:93], v[222:225], 0
	v_mfma_f32_16x16x32_bf16 v[122:125], v[102:105], v[222:225], 0
	v_mfma_f32_16x16x32_bf16 v[110:113], v[90:93], v[230:233], 0
	v_mfma_f32_16x16x32_bf16 v[98:101], v[102:105], v[230:233], 0
	v_mfma_f32_16x16x32_bf16 v[78:81], v[90:93], v[238:241], 0
	v_mfma_f32_16x16x32_bf16 v[74:77], v[102:105], v[238:241], 0
	v_mfma_f32_16x16x32_bf16 v[142:145], v[94:97], v[192:195], v[142:145]
	v_mfma_f32_16x16x32_bf16 v[138:141], v[106:109], v[192:195], v[138:141]
	v_mfma_f32_16x16x32_bf16 v[126:129], v[94:97], v[226:229], v[126:129]
	v_mfma_f32_16x16x32_bf16 v[122:125], v[106:109], v[226:229], v[122:125]
	v_mfma_f32_16x16x32_bf16 v[110:113], v[94:97], v[234:237], v[110:113]
	v_mfma_f32_16x16x32_bf16 v[98:101], v[106:109], v[234:237], v[98:101]
	v_mfma_f32_16x16x32_bf16 v[78:81], v[94:97], v[242:245], v[78:81]
	v_mfma_f32_16x16x32_bf16 v[74:77], v[106:109], v[242:245], v[74:77]
	s_setprio 0
	s_setprio 1
	v_mfma_f32_16x16x32_bf16 v[134:137], v[146:149], v[188:191], 0
	v_mfma_f32_16x16x32_bf16 v[130:133], v[154:157], v[188:191], 0
	v_mfma_f32_16x16x32_bf16 v[118:121], v[146:149], v[222:225], 0
	v_mfma_f32_16x16x32_bf16 v[114:117], v[154:157], v[222:225], 0
	v_mfma_f32_16x16x32_bf16 v[86:89], v[146:149], v[230:233], 0
	v_mfma_f32_16x16x32_bf16 v[82:85], v[154:157], v[230:233], 0
	v_mfma_f32_16x16x32_bf16 v[70:73], v[146:149], v[238:241], 0
	v_mfma_f32_16x16x32_bf16 v[66:69], v[154:157], v[238:241], 0
	v_mfma_f32_16x16x32_bf16 v[134:137], v[150:153], v[192:195], v[134:137]
	v_mfma_f32_16x16x32_bf16 v[130:133], v[158:161], v[192:195], v[130:133]
	v_mfma_f32_16x16x32_bf16 v[118:121], v[150:153], v[226:229], v[118:121]
	v_mfma_f32_16x16x32_bf16 v[114:117], v[158:161], v[226:229], v[114:117]
	v_mfma_f32_16x16x32_bf16 v[86:89], v[150:153], v[234:237], v[86:89]
	v_mfma_f32_16x16x32_bf16 v[82:85], v[158:161], v[234:237], v[82:85]
	v_mfma_f32_16x16x32_bf16 v[70:73], v[150:153], v[242:245], v[70:73]
	v_mfma_f32_16x16x32_bf16 v[66:69], v[158:161], v[242:245], v[66:69]
; #define PG8_STAGE(bufoff, gbase, voff) do { _Pragma("unroll") for (int _i = 0; _i < 2; ++_i) \
;         __builtin_amdgcn_global_load_lds((const unsigned*)((const char*)(gbase) + (voff)[_i]), (LAS unsigned*)(lds + (bufoff) + ldsw + _i * 8192), 16, 0, 0); } while (0)
; #define PG8_LDA(dst, b, h) do { _Pragma("unroll") for (int m = 0; m < 4; ++m) _Pragma("unroll") for (int k = 0; k < 2; ++k) dst[m][k] = *(const LAS bf16x8*)(lds + PG8_SA(b, h) + aoff + m * 2048 + k * 1024); } while (0)
; #define PG8_LDB(dst, b, h) do { _Pragma("unroll") for (int n = 0; n < 2; ++n) _Pragma("unroll") for (int k = 0; k < 2; ++k) dst[n][k] = *(const LAS bf16x8*)(lds + PG8_SB(b, h) + boff + n * 2048 + k * 1024); } while (0)
; #define PG8_MMA(ai, bj, At, Bt) do { __builtin_amdgcn_s_setprio(1); _Pragma("unroll") for (int m = 0; m < 4; ++m) _Pragma("unroll") for (int n = 0; n < 2; ++n) _Pragma("unroll") for (int k = 0; k < 2; ++k) \
;         acc[ai][bj][m][n] = __builtin_amdgcn_mfma_f32_16x16x32_bf16(Bt[n][k], At[m][k], acc[ai][bj][m][n], 0, 0, 0); __builtin_amdgcn_s_setprio(0); } while (0)
; #define PG8_WAIT_V(n) asm volatile("s_waitcnt vmcnt(" #n ")" ::: "memory")
; #define PG8_WAIT_L(n) asm volatile("s_waitcnt lgkmcnt(" #n ")" ::: "memory")
; #define PG8_BAR __builtin_amdgcn_s_barrier()
; #define PG8_SCHED __builtin_amdgcn_sched_barrier(0)
; template <class Epi>
; __device__ __forceinline__ void gemm_phase(LAS unsigned char* lds, const Sched& S, const Epi& E) {
;     ...
;             PG8_LDA(At, 0, 1); PG8_STAGE(PG8_SB(0, 0), b2, voffB); PG8_STAGE(PG8_SB(0, 1), b2 + hstepB, voffB); PG8_STAGE(PG8_SA(0, 0), a2, voffA);
;             PG8_WAIT_V(8); PG8_WAIT_L(0); PG8_BAR; PG8_MMA(1, 0, At, B0); PG8_MMA(1, 1, At, B1); PG8_BAR; PG8_SCHED;
;             PG8_LDB(B0, 1, 0); PG8_LDB(B1, 1, 1); PG8_SCHED; PG8_LDA(At, 1, 0); PG8_STAGE(PG8_SA(0, 1), a2 + hstepA, voffA);
;             PG8_WAIT_V(8); PG8_WAIT_L(0); PG8_BAR; PG8_MMA(0, 0, At, B0); PG8_MMA(0, 1, At, B1); PG8_BAR; PG8_SCHED;
.Ltskip_poolp_0:
	s_setprio 0
	s_barrier
	s_add_i32 s49, s49, s25
	v_lshl_add_u64 v[200:201], s[28:29], 0, v[168:169]
	s_mov_b32 m0, s49
	ds_read_b128 v[188:191], v199 offset:16384
	ds_read_b128 v[192:195], v199 offset:17408
	ds_read_b128 v[222:225], v199 offset:18432
	ds_read_b128 v[226:229], v199 offset:19456
	ds_read_b128 v[230:233], v199 offset:20480
	ds_read_b128 v[234:237], v199 offset:21504
	ds_read_b128 v[238:241], v199 offset:22528
	ds_read_b128 v[242:245], v199 offset:23552
	global_load_lds_dwordx4 v[200:201], off
	s_add_i32 m0, s49, 0x2000
	s_add_u32 s96, s28, 0x20000
	v_lshl_add_u64 v[246:247], s[28:29], 0, v[166:167]
	s_addc_u32 s97, s29, 0
	s_add_i32 s49, s88, s25
	global_load_lds_dwordx4 v[246:247], off
	v_lshl_add_u64 v[248:249], s[96:97], 0, v[168:169]
	s_mov_b32 m0, s49
	v_lshl_add_u64 v[250:251], s[30:31], 0, v[164:165]
	global_load_lds_dwordx4 v[248:249], off
	v_lshl_add_u64 v[248:249], s[96:97], 0, v[166:167]
	s_add_i32 m0, s49, 0x2000
	s_nop 0
	global_load_lds_dwordx4 v[248:249], off
	v_lshl_add_u64 v[248:249], s[30:31], 0, v[162:163]
	s_mov_b32 m0, s64
	s_nop 0
	global_load_lds_dwordx4 v[248:249], off
	s_mov_b32 m0, s65
	s_nop 0
	global_load_lds_dwordx4 v[250:251], off
	s_waitcnt vmcnt(8)
	s_waitcnt lgkmcnt(0)
	s_barrier
	s_setprio 1
	s_waitcnt lgkmcnt(0)
	s_setprio 0
	s_setprio 1
	s_setprio 0
	s_barrier
	s_add_i32 s49, 0, 0x18000
	s_add_i32 s88, 0, 0x1c000
	v_add_u32_e32 v106, s49, v197
	v_add_u32_e32 v158, s88, v197
	ds_read_b128 v[90:93], v106
	ds_read_b128 v[94:97], v106 offset:1024
	ds_read_b128 v[102:105], v106 offset:2048
	ds_read_b128 v[106:109], v106 offset:3072
	ds_read_b128 v[146:149], v158
	ds_read_b128 v[150:153], v158 offset:1024
	ds_read_b128 v[154:157], v158 offset:2048
	ds_read_b128 v[158:161], v158 offset:3072
	s_add_u32 s30, s30, 0x80000
	s_addc_u32 s31, s31, 0
	s_mov_b32 m0, s66
	v_lshl_add_u64 v[252:253], s[30:31], 0, v[162:163]
	ds_read_b128 v[188:191], v199 offset:32768
	ds_read_b128 v[192:195], v199 offset:33792
	ds_read_b128 v[222:225], v199 offset:34816
	ds_read_b128 v[226:229], v199 offset:35840
	ds_read_b128 v[230:233], v199 offset:36864
	ds_read_b128 v[234:237], v199 offset:37888
	ds_read_b128 v[238:241], v199 offset:38912
	ds_read_b128 v[242:245], v199 offset:39936
	global_load_lds_dwordx4 v[252:253], off
	v_lshl_add_u64 v[252:253], s[30:31], 0, v[164:165]
	s_mov_b32 m0, s67
	s_nop 0
	global_load_lds_dwordx4 v[252:253], off
	s_waitcnt vmcnt(8)
	s_waitcnt lgkmcnt(0)
	s_barrier
	s_setprio 1
	s_waitcnt lgkmcnt(0)
	s_cmp_eq_u64 s[12:13], 0
	s_cbranch_scc1 .Ltskip_poolp_1
	v_mfma_f32_16x16x32_bf16 v[142:145], v[90:93], v[188:191], v[142:145]
	v_mfma_f32_16x16x32_bf16 v[138:141], v[102:105], v[188:191], v[138:141]
	v_mfma_f32_16x16x32_bf16 v[126:129], v[90:93], v[222:225], v[126:129]
	v_mfma_f32_16x16x32_bf16 v[122:125], v[102:105], v[222:225], v[122:125]
	v_mfma_f32_16x16x32_bf16 v[110:113], v[90:93], v[230:233], v[110:113]
	v_mfma_f32_16x16x32_bf16 v[98:101], v[102:105], v[230:233], v[98:101]
	v_mfma_f32_16x16x32_bf16 v[78:81], v[90:93], v[238:241], v[78:81]
	v_mfma_f32_16x16x32_bf16 v[74:77], v[102:105], v[238:241], v[74:77]
	v_mfma_f32_16x16x32_bf16 v[142:145], v[94:97], v[192:195], v[142:145]
	v_mfma_f32_16x16x32_bf16 v[138:141], v[106:109], v[192:195], v[138:141]
	v_mfma_f32_16x16x32_bf16 v[126:129], v[94:97], v[226:229], v[126:129]
	v_mfma_f32_16x16x32_bf16 v[122:125], v[106:109], v[226:229], v[122:125]
	v_mfma_f32_16x16x32_bf16 v[110:113], v[94:97], v[234:237], v[110:113]
	v_mfma_f32_16x16x32_bf16 v[98:101], v[106:109], v[234:237], v[98:101]
	v_mfma_f32_16x16x32_bf16 v[78:81], v[94:97], v[242:245], v[78:81]
	v_mfma_f32_16x16x32_bf16 v[74:77], v[106:109], v[242:245], v[74:77]
	s_setprio 0
	s_setprio 1
	v_mfma_f32_16x16x32_bf16 v[134:137], v[146:149], v[188:191], v[134:137]
	v_mfma_f32_16x16x32_bf16 v[130:133], v[154:157], v[188:191], v[130:133]
	v_mfma_f32_16x16x32_bf16 v[118:121], v[146:149], v[222:225], v[118:121]
	v_mfma_f32_16x16x32_bf16 v[114:117], v[154:157], v[222:225], v[114:117]
	v_mfma_f32_16x16x32_bf16 v[86:89], v[146:149], v[230:233], v[86:89]
	v_mfma_f32_16x16x32_bf16 v[82:85], v[154:157], v[230:233], v[82:85]
	v_mfma_f32_16x16x32_bf16 v[70:73], v[146:149], v[238:241], v[70:73]
	v_mfma_f32_16x16x32_bf16 v[66:69], v[154:157], v[238:241], v[66:69]
	v_mfma_f32_16x16x32_bf16 v[134:137], v[150:153], v[192:195], v[134:137]
	v_mfma_f32_16x16x32_bf16 v[130:133], v[158:161], v[192:195], v[130:133]
	v_mfma_f32_16x16x32_bf16 v[118:121], v[150:153], v[226:229], v[118:121]
	v_mfma_f32_16x16x32_bf16 v[114:117], v[158:161], v[226:229], v[114:117]
	v_mfma_f32_16x16x32_bf16 v[86:89], v[150:153], v[234:237], v[86:89]
	v_mfma_f32_16x16x32_bf16 v[82:85], v[158:161], v[234:237], v[82:85]
	v_mfma_f32_16x16x32_bf16 v[70:73], v[150:153], v[242:245], v[70:73]
	v_mfma_f32_16x16x32_bf16 v[66:69], v[158:161], v[242:245], v[66:69]
; #define PG8_STAGE(bufoff, gbase, voff) do { _Pragma("unroll") for (int _i = 0; _i < 2; ++_i) \
;         __builtin_amdgcn_global_load_lds((const unsigned*)((const char*)(gbase) + (voff)[_i]), (LAS unsigned*)(lds + (bufoff) + ldsw + _i * 8192), 16, 0, 0); } while (0)
; #define PG8_LDA(dst, b, h) do { _Pragma("unroll") for (int m = 0; m < 4; ++m) _Pragma("unroll") for (int k = 0; k < 2; ++k) dst[m][k] = *(const LAS bf16x8*)(lds + PG8_SA(b, h) + aoff + m * 2048 + k * 1024); } while (0)
; #define PG8_LDB(dst, b, h) do { _Pragma("unroll") for (int n = 0; n < 2; ++n) _Pragma("unroll") for (int k = 0; k < 2; ++k) dst[n][k] = *(const LAS bf16x8*)(lds + PG8_SB(b, h) + boff + n * 2048 + k * 1024); } while (0)
; #define PG8_MMA(ai, bj, At, Bt) do { __builtin_amdgcn_s_setprio(1); _Pragma("unroll") for (int m = 0; m < 4; ++m) _Pragma("unroll") for (int n = 0; n < 2; ++n) _Pragma("unroll") for (int k = 0; k < 2; ++k) \
;         acc[ai][bj][m][n] = __builtin_amdgcn_mfma_f32_16x16x32_bf16(Bt[n][k], At[m][k], acc[ai][bj][m][n], 0, 0, 0); __builtin_amdgcn_s_setprio(0); } while (0)
; #define PG8_WAIT_V(n) asm volatile("s_waitcnt vmcnt(" #n ")" ::: "memory")
; #define PG8_WAIT_L(n) asm volatile("s_waitcnt lgkmcnt(" #n ")" ::: "memory")
; #define PG8_BAR __builtin_amdgcn_s_barrier()
; #define PG8_SCHED __builtin_amdgcn_sched_barrier(0)
; template <class Epi>
; __device__ __forceinline__ void gemm_phase(LAS unsigned char* lds, const Sched& S, const Epi& E) {
;     ...
;         for (int t = 0; t < nt; t += 2) {
;             const bool last = (t == nt - 2);
;             const char* a1 = cA + (size_t)(t + 1) * kstep;
;             const char* a2 = last ? nA : cA + (size_t)(t + 2) * kstep; const char* b2 = last ? nB : cB + (size_t)(t + 2) * kstep;
;             const char* a3 = a2 + kstep; const char* b3 = b2 + kstep;
;             PG8_LDB(B0, 0, 0); PG8_LDB(B1, 0, 1); PG8_SCHED; PG8_LDA(At, 0, 0); PG8_STAGE(PG8_SA(1, 1), a1 + hstepA, voffA);
;             PG8_WAIT_V(8); PG8_WAIT_L(0); PG8_BAR; PG8_MMA(0, 0, At, B0); PG8_MMA(0, 1, At, B1); PG8_BAR; PG8_SCHED;
;     ...
;             PG8_LDA(At, 1, 1); PG8_STAGE(PG8_SB(1, 0), b3, voffB); PG8_STAGE(PG8_SB(1, 1), b3 + hstepB, voffB); PG8_STAGE(PG8_SA(1, 0), a3, voffA);
;             PG8_WAIT_V(8); PG8_WAIT_L(0); PG8_BAR; PG8_MMA(1, 0, At, B0); PG8_MMA(1, 1, At, B1); PG8_BAR; PG8_SCHED;
.Ltskip_poolp_1:
	s_setprio 0
	s_barrier
	s_add_i32 s30, s49, s25
	v_lshl_add_u64 v[200:201], v[200:201], 0, s[0:1]
	s_mov_b32 m0, s30
	ds_read_b128 v[188:191], v199 offset:49152
	ds_read_b128 v[192:195], v199 offset:50176
	ds_read_b128 v[222:225], v199 offset:51200
	ds_read_b128 v[226:229], v199 offset:52224
	ds_read_b128 v[230:233], v199 offset:53248
	ds_read_b128 v[234:237], v199 offset:54272
	ds_read_b128 v[238:241], v199 offset:55296
	ds_read_b128 v[242:245], v199 offset:56320
	global_load_lds_dwordx4 v[200:201], off
	s_add_i32 m0, s30, 0x2000
	s_add_u32 s28, s28, 0x20080
	v_lshl_add_u64 v[200:201], v[246:247], 0, s[0:1]
	s_addc_u32 s29, s29, 0
	s_add_i32 s30, s88, s25
	global_load_lds_dwordx4 v[200:201], off
	v_lshl_add_u64 v[200:201], s[28:29], 0, v[168:169]
	s_mov_b32 m0, s30
	s_nop 0
	global_load_lds_dwordx4 v[200:201], off
	v_lshl_add_u64 v[200:201], s[28:29], 0, v[166:167]
	s_add_i32 m0, s30, 0x2000
	s_nop 0
	global_load_lds_dwordx4 v[200:201], off
	v_lshl_add_u64 v[200:201], v[248:249], 0, s[0:1]
	s_mov_b32 m0, s68
	s_nop 0
	global_load_lds_dwordx4 v[200:201], off
	v_lshl_add_u64 v[200:201], v[250:251], 0, s[0:1]
	s_mov_b32 m0, s69
	s_nop 0
	global_load_lds_dwordx4 v[200:201], off
	s_waitcnt vmcnt(8)
	s_waitcnt lgkmcnt(0)
	s_barrier
	s_setprio 1
	s_waitcnt lgkmcnt(0)
	s_setprio 0
	s_setprio 1
	s_setprio 0
	s_barrier
	s_add_i32 s37, s37, 2
	s_add_u32 s26, s26, 0x100
	s_addc_u32 s27, s27, 0
	s_add_u32 s35, s35, 0x100
	s_addc_u32 s36, s36, 0
	s_cmp_gt_u32 s37, 5
	s_cbranch_scc1 .Lpeel_exit_pool
.Ltail_loop_pool:
	s_add_u32 s28, s26, 0xfff80080
	s_addc_u32 s29, s27, -1
	s_add_i32 s49, 0, 0x10000
	s_cmp_eq_u32 s37, 4
	s_cselect_b32 s31, s5, s29
	s_cselect_b32 s30, s15, s28
	s_cselect_b32 s29, s17, s36
	s_cselect_b32 s28, s34, s35
	s_add_i32 s88, 0, 0x14000
	v_add_u32_e32 v106, s49, v197
	v_add_u32_e32 v158, s88, v197
	ds_read_b128 v[90:93], v106
	ds_read_b128 v[94:97], v106 offset:1024
	ds_read_b128 v[102:105], v106 offset:2048
	ds_read_b128 v[106:109], v106 offset:3072
	ds_read_b128 v[146:149], v158
	ds_read_b128 v[150:153], v158 offset:1024
	ds_read_b128 v[154:157], v158 offset:2048
	ds_read_b128 v[158:161], v158 offset:3072
	v_lshl_add_u64 v[200:201], s[26:27], 0, v[184:185]
	s_add_i32 m0, s64, 0xc000
	ds_read_b128 v[188:191], v199
	ds_read_b128 v[192:195], v199 offset:1024
	ds_read_b128 v[222:225], v199 offset:2048
	ds_read_b128 v[226:229], v199 offset:3072
	ds_read_b128 v[230:233], v199 offset:4096
	ds_read_b128 v[234:237], v199 offset:5120
	ds_read_b128 v[238:241], v199 offset:6144
	ds_read_b128 v[242:245], v199 offset:7168
	global_load_lds_dwordx4 v[200:201], off
	v_lshl_add_u64 v[200:201], s[26:27], 0, v[186:187]
	s_add_i32 m0, s64, 0xe000
	s_nop 0
	global_load_lds_dwordx4 v[200:201], off
	s_waitcnt vmcnt(8)
	s_waitcnt lgkmcnt(0)
	s_barrier
	s_setprio 1
	s_waitcnt lgkmcnt(0)
	s_cmp_eq_u64 s[12:13], 0
	s_cbranch_scc1 .Ltskip_pooll_0
	v_mfma_f32_16x16x32_bf16 v[142:145], v[90:93], v[188:191], v[142:145]
	v_mfma_f32_16x16x32_bf16 v[138:141], v[102:105], v[188:191], v[138:141]
	v_mfma_f32_16x16x32_bf16 v[126:129], v[90:93], v[222:225], v[126:129]
	v_mfma_f32_16x16x32_bf16 v[122:125], v[102:105], v[222:225], v[122:125]
	v_mfma_f32_16x16x32_bf16 v[110:113], v[90:93], v[230:233], v[110:113]
	v_mfma_f32_16x16x32_bf16 v[98:101], v[102:105], v[230:233], v[98:101]
	v_mfma_f32_16x16x32_bf16 v[78:81], v[90:93], v[238:241], v[78:81]
	v_mfma_f32_16x16x32_bf16 v[74:77], v[102:105], v[238:241], v[74:77]
	v_mfma_f32_16x16x32_bf16 v[142:145], v[94:97], v[192:195], v[142:145]
	v_mfma_f32_16x16x32_bf16 v[138:141], v[106:109], v[192:195], v[138:141]
	v_mfma_f32_16x16x32_bf16 v[126:129], v[94:97], v[226:229], v[126:129]
	v_mfma_f32_16x16x32_bf16 v[122:125], v[106:109], v[226:229], v[122:125]
	v_mfma_f32_16x16x32_bf16 v[110:113], v[94:97], v[234:237], v[110:113]
	v_mfma_f32_16x16x32_bf16 v[98:101], v[106:109], v[234:237], v[98:101]
	v_mfma_f32_16x16x32_bf16 v[78:81], v[94:97], v[242:245], v[78:81]
	v_mfma_f32_16x16x32_bf16 v[74:77], v[106:109], v[242:245], v[74:77]
	s_setprio 0
	s_setprio 1
	v_mfma_f32_16x16x32_bf16 v[134:137], v[146:149], v[188:191], v[134:137]
	v_mfma_f32_16x16x32_bf16 v[130:133], v[154:157], v[188:191], v[130:133]
	v_mfma_f32_16x16x32_bf16 v[118:121], v[146:149], v[222:225], v[118:121]
	v_mfma_f32_16x16x32_bf16 v[114:117], v[154:157], v[222:225], v[114:117]
	v_mfma_f32_16x16x32_bf16 v[86:89], v[146:149], v[230:233], v[86:89]
	v_mfma_f32_16x16x32_bf16 v[82:85], v[154:157], v[230:233], v[82:85]
	v_mfma_f32_16x16x32_bf16 v[70:73], v[146:149], v[238:241], v[70:73]
	v_mfma_f32_16x16x32_bf16 v[66:69], v[154:157], v[238:241], v[66:69]
	v_mfma_f32_16x16x32_bf16 v[134:137], v[150:153], v[192:195], v[134:137]
	v_mfma_f32_16x16x32_bf16 v[130:133], v[158:161], v[192:195], v[130:133]
	v_mfma_f32_16x16x32_bf16 v[118:121], v[150:153], v[226:229], v[118:121]
	v_mfma_f32_16x16x32_bf16 v[114:117], v[158:161], v[226:229], v[114:117]
	v_mfma_f32_16x16x32_bf16 v[86:89], v[150:153], v[234:237], v[86:89]
	v_mfma_f32_16x16x32_bf16 v[82:85], v[158:161], v[234:237], v[82:85]
	v_mfma_f32_16x16x32_bf16 v[70:73], v[150:153], v[242:245], v[70:73]
	v_mfma_f32_16x16x32_bf16 v[66:69], v[158:161], v[242:245], v[66:69]

; #define PG8_STAGE(bufoff, gbase, voff) do { _Pragma("unroll") for (int _i = 0; _i < 2; ++_i) \
;         __builtin_amdgcn_global_load_lds((const unsigned*)((const char*)(gbase) + (voff)[_i]), (LAS unsigned*)(lds + (bufoff) + ldsw + _i * 8192), 16, 0, 0); } while (0)
; #define PG8_LDA(dst, b, h) do { _Pragma("unroll") for (int m = 0; m < 4; ++m) _Pragma("unroll") for (int k = 0; k < 2; ++k) dst[m][k] = *(const LAS bf16x8*)(lds + PG8_SA(b, h) + aoff + m * 2048 + k * 1024); } while (0)
; #define PG8_MMA(ai, bj, At, Bt) do { __builtin_amdgcn_s_setprio(1); _Pragma("unroll") for (int m = 0; m < 4; ++m) _Pragma("unroll") for (int n = 0; n < 2; ++n) _Pragma("unroll") for (int k = 0; k < 2; ++k) \
;         acc[ai][bj][m][n] = __builtin_amdgcn_mfma_f32_16x16x32_bf16(Bt[n][k], At[m][k], acc[ai][bj][m][n], 0, 0, 0); __builtin_amdgcn_s_setprio(0); } while (0)
; #define PG8_WAIT_V(n) asm volatile("s_waitcnt vmcnt(" #n ")" ::: "memory")
; #define PG8_WAIT_L(n) asm volatile("s_waitcnt lgkmcnt(" #n ")" ::: "memory")
; #define PG8_BAR __builtin_amdgcn_s_barrier()
; #define PG8_SCHED __builtin_amdgcn_sched_barrier(0)
; template <class Epi>
; __device__ __forceinline__ void gemm_phase(LAS unsigned char* lds, const Sched& S, const Epi& E) {
;     ...
;         for (int t = 0; t < nt; t += 2) {
;     ...
;             PG8_LDA(At, 1, 1); PG8_STAGE(PG8_SB(1, 0), b3, voffB); PG8_STAGE(PG8_SB(1, 1), b3 + hstepB, voffB); PG8_STAGE(PG8_SA(1, 0), a3, voffA);
;             PG8_WAIT_V(8); PG8_WAIT_L(0); PG8_BAR; PG8_MMA(1, 0, At, B0); PG8_MMA(1, 1, At, B1); PG8_BAR; PG8_SCHED;
.Ltskip_pooll_1:
	s_setprio 0
	s_barrier
	s_add_i32 s30, s49, s25
	v_lshl_add_u64 v[200:201], v[200:201], 0, s[0:1]
	s_mov_b32 m0, s30
	ds_read_b128 v[188:191], v199 offset:49152
	ds_read_b128 v[192:195], v199 offset:50176
	ds_read_b128 v[222:225], v199 offset:51200
	ds_read_b128 v[226:229], v199 offset:52224
	ds_read_b128 v[230:233], v199 offset:53248
	ds_read_b128 v[234:237], v199 offset:54272
	ds_read_b128 v[238:241], v199 offset:55296
	ds_read_b128 v[242:245], v199 offset:56320
	global_load_lds_dwordx4 v[200:201], off
	s_add_i32 m0, s30, 0x2000
	s_add_u32 s28, s28, 0x20080
	v_lshl_add_u64 v[200:201], v[246:247], 0, s[0:1]
	s_addc_u32 s29, s29, 0
	s_add_i32 s30, s88, s25
	global_load_lds_dwordx4 v[200:201], off
	v_lshl_add_u64 v[200:201], s[28:29], 0, v[168:169]
	s_mov_b32 m0, s30
	s_nop 0
	global_load_lds_dwordx4 v[200:201], off
	v_lshl_add_u64 v[200:201], s[28:29], 0, v[166:167]
	s_add_i32 m0, s30, 0x2000
	s_nop 0
	global_load_lds_dwordx4 v[200:201], off
	v_lshl_add_u64 v[200:201], v[248:249], 0, s[0:1]
	s_mov_b32 m0, s68
	s_nop 0
	global_load_lds_dwordx4 v[200:201], off
	v_lshl_add_u64 v[200:201], v[250:251], 0, s[0:1]
	s_mov_b32 m0, s69
	s_nop 0
	global_load_lds_dwordx4 v[200:201], off
	s_waitcnt vmcnt(8)
	s_waitcnt lgkmcnt(0)
	s_barrier
	s_setprio 1
	s_waitcnt lgkmcnt(0)
	s_setprio 0
	s_setprio 1
	s_setprio 0
	s_barrier
	s_add_i32 s37, s37, 2
	s_add_u32 s26, s26, 0x100
	s_addc_u32 s27, s27, 0
	s_add_u32 s35, s35, 0x100
	s_addc_u32 s36, s36, 0
	s_cmp_gt_u32 s37, 5
	s_cbranch_scc0 .Ltail_loop_pool

; #define PG8_STAGE(bufoff, gbase, voff) do { _Pragma("unroll") for (int _i = 0; _i < 2; ++_i) \
;         __builtin_amdgcn_global_load_lds((const unsigned*)((const char*)(gbase) + (voff)[_i]), (LAS unsigned*)(lds + (bufoff) + ldsw + _i * 8192), 16, 0, 0); } while (0)
; #define PG8_LDA(dst, b, h) do { _Pragma("unroll") for (int m = 0; m < 4; ++m) _Pragma("unroll") for (int k = 0; k < 2; ++k) dst[m][k] = *(const LAS bf16x8*)(lds + PG8_SA(b, h) + aoff + m * 2048 + k * 1024); } while (0)
; #define PG8_LDB(dst, b, h) do { _Pragma("unroll") for (int n = 0; n < 2; ++n) _Pragma("unroll") for (int k = 0; k < 2; ++k) dst[n][k] = *(const LAS bf16x8*)(lds + PG8_SB(b, h) + boff + n * 2048 + k * 1024); } while (0)
; #define PG8_MMA(ai, bj, At, Bt) do { __builtin_amdgcn_s_setprio(1); _Pragma("unroll") for (int m = 0; m < 4; ++m) _Pragma("unroll") for (int n = 0; n < 2; ++n) _Pragma("unroll") for (int k = 0; k < 2; ++k) \
;         acc[ai][bj][m][n] = __builtin_amdgcn_mfma_f32_16x16x32_bf16(Bt[n][k], At[m][k], acc[ai][bj][m][n], 0, 0, 0); __builtin_amdgcn_s_setprio(0); } while (0)
; #define PG8_WAIT_V(n) asm volatile("s_waitcnt vmcnt(" #n ")" ::: "memory")
; #define PG8_BAR __builtin_amdgcn_s_barrier()
; template <class Epi>
; __device__ __forceinline__ void gemm_phase(LAS unsigned char* lds, const Sched& S, const Epi& E) {
;     ...
;         const bool has_next = S.next(ui + 1, nxt);
;         const char* nA = has_next ? nxt.A : cA; const char* nB = has_next ? nxt.B : cB;
;         const int nt = cur.nt;
;         for (int t = 0; t < nt; t += 2) {
;             const bool last = (t == nt - 2);
;             const char* a1 = cA + (size_t)(t + 1) * kstep;
;             const char* a2 = last ? nA : cA + (size_t)(t + 2) * kstep; const char* b2 = last ? nB : cB + (size_t)(t + 2) * kstep;
;             const char* a3 = a2 + kstep; const char* b3 = b2 + kstep;
;             PG8_LDB(B0, 0, 0); PG8_LDB(B1, 0, 1); PG8_SCHED; PG8_LDA(At, 0, 0); PG8_STAGE(PG8_SA(1, 1), a1 + hstepA, voffA);
;             PG8_WAIT_V(8); PG8_WAIT_L(0); PG8_BAR; PG8_MMA(0, 0, At, B0); PG8_MMA(0, 1, At, B1); PG8_BAR; PG8_SCHED;
;             PG8_LDA(At, 0, 1); PG8_STAGE(PG8_SB(0, 0), b2, voffB); PG8_STAGE(PG8_SB(0, 1), b2 + hstepB, voffB); PG8_STAGE(PG8_SA(0, 0), a2, voffA);
;             PG8_WAIT_V(8); PG8_WAIT_L(0); PG8_BAR; PG8_MMA(1, 0, At, B0); PG8_MMA(1, 1, At, B1); PG8_BAR; PG8_SCHED;
.LBB0_2390:
	s_and_b64 s[24:25], s[18:19], exec
	s_cselect_b32 s26, s15, s5
	s_cselect_b32 s27, s14, s4
	s_cselect_b32 s95, s17, s23
	s_cselect_b32 s96, s16, s22
	s_add_i32 s97, s94, -2
	s_add_u32 s4, s4, 0x160080
	s_addc_u32 s5, s5, 0
	s_add_u32 vcc_lo, s22, 0x100
	v_mov_b32_e32 v2, 0
	s_mov_b64 s[52:53], s[72:73]
	s_addc_u32 vcc_hi, s23, 0
	s_mov_b32 s22, 0
	s_waitcnt lgkmcnt(0)
	s_cmp_eq_u32 s69, 32
	s_cbranch_scc1 .Ltail_peel_down
	s_add_i32 s49, s22, 2
	s_add_u32 s23, s4, 0xffea0080
	s_addc_u32 s24, s5, -1
	s_add_i32 s88, 0, 0x10000
	s_cmp_eq_u32 s97, s22
	s_cselect_b32 s25, s26, s24
	s_cselect_b32 s24, s27, s23
	s_cselect_b32 s23, s95, vcc_hi
	s_cselect_b32 s22, s96, vcc_lo
	s_add_i32 s72, 0, 0x14000
	v_add_u32_e32 v142, s88, v222
	v_add_u32_e32 v158, s72, v222
	ds_read_b128 v[130:133], v142
	ds_read_b128 v[134:137], v142 offset:1024
	ds_read_b128 v[138:141], v142 offset:2048
	ds_read_b128 v[142:145], v142 offset:3072
	ds_read_b128 v[146:149], v158
	ds_read_b128 v[150:153], v158 offset:1024
	ds_read_b128 v[154:157], v158 offset:2048
	ds_read_b128 v[158:161], v158 offset:3072
	v_lshl_add_u64 v[166:167], s[4:5], 0, v[186:187]
	s_add_i32 m0, s35, 0xc000
	ds_read_b128 v[162:165], v224
	ds_read_b128 v[190:193], v224 offset:1024
	ds_read_b128 v[194:197], v224 offset:2048
	ds_read_b128 v[198:201], v224 offset:3072
	ds_read_b128 v[226:229], v224 offset:4096
	ds_read_b128 v[230:233], v224 offset:5120
	ds_read_b128 v[234:237], v224 offset:6144
	ds_read_b128 v[238:241], v224 offset:7168
	global_load_lds_dwordx4 v[166:167], off
	v_lshl_add_u64 v[166:167], s[4:5], 0, v[188:189]
	s_add_i32 m0, s35, 0xe000
	s_nop 0
	global_load_lds_dwordx4 v[166:167], off
	s_waitcnt vmcnt(8)
	s_waitcnt lgkmcnt(0)
	s_barrier
	s_setprio 1
	s_waitcnt lgkmcnt(0)
	v_mfma_f32_16x16x32_bf16 v[126:129], v[130:133], v[162:165], 0
	v_mfma_f32_16x16x32_bf16 v[122:125], v[138:141], v[162:165], 0
	v_mfma_f32_16x16x32_bf16 v[118:121], v[130:133], v[194:197], 0
	v_mfma_f32_16x16x32_bf16 v[106:109], v[138:141], v[194:197], 0
	v_mfma_f32_16x16x32_bf16 v[94:97], v[130:133], v[226:229], 0
	v_mfma_f32_16x16x32_bf16 v[90:93], v[138:141], v[226:229], 0
	v_mfma_f32_16x16x32_bf16 v[86:89], v[130:133], v[234:237], 0
	v_mfma_f32_16x16x32_bf16 v[74:77], v[138:141], v[234:237], 0
	v_mfma_f32_16x16x32_bf16 v[126:129], v[134:137], v[190:193], v[126:129]
	v_mfma_f32_16x16x32_bf16 v[122:125], v[142:145], v[190:193], v[122:125]
	v_mfma_f32_16x16x32_bf16 v[118:121], v[134:137], v[198:201], v[118:121]
	v_mfma_f32_16x16x32_bf16 v[106:109], v[142:145], v[198:201], v[106:109]
	v_mfma_f32_16x16x32_bf16 v[94:97], v[134:137], v[230:233], v[94:97]
	v_mfma_f32_16x16x32_bf16 v[90:93], v[142:145], v[230:233], v[90:93]
	v_mfma_f32_16x16x32_bf16 v[86:89], v[134:137], v[238:241], v[86:89]
	v_mfma_f32_16x16x32_bf16 v[74:77], v[142:145], v[238:241], v[74:77]
	s_setprio 0
	s_setprio 1
	v_mfma_f32_16x16x32_bf16 v[114:117], v[146:149], v[162:165], 0
	v_mfma_f32_16x16x32_bf16 v[110:113], v[154:157], v[162:165], 0
	v_mfma_f32_16x16x32_bf16 v[102:105], v[146:149], v[194:197], 0
	v_mfma_f32_16x16x32_bf16 v[98:101], v[154:157], v[194:197], 0
	v_mfma_f32_16x16x32_bf16 v[82:85], v[146:149], v[226:229], 0
	v_mfma_f32_16x16x32_bf16 v[78:81], v[154:157], v[226:229], 0
	v_mfma_f32_16x16x32_bf16 v[70:73], v[146:149], v[234:237], 0
	v_mfma_f32_16x16x32_bf16 v[66:69], v[154:157], v[234:237], 0
	v_mfma_f32_16x16x32_bf16 v[114:117], v[150:153], v[190:193], v[114:117]
	v_mfma_f32_16x16x32_bf16 v[110:113], v[158:161], v[190:193], v[110:113]
	v_mfma_f32_16x16x32_bf16 v[102:105], v[150:153], v[198:201], v[102:105]
	v_mfma_f32_16x16x32_bf16 v[98:101], v[158:161], v[198:201], v[98:101]
	v_mfma_f32_16x16x32_bf16 v[82:85], v[150:153], v[230:233], v[82:85]
	v_mfma_f32_16x16x32_bf16 v[78:81], v[158:161], v[230:233], v[78:81]
	v_mfma_f32_16x16x32_bf16 v[70:73], v[150:153], v[238:241], v[70:73]
	v_mfma_f32_16x16x32_bf16 v[66:69], v[158:161], v[238:241], v[66:69]
	s_setprio 0
	s_barrier
	s_add_i32 s73, s88, s34
	v_lshl_add_u64 v[166:167], s[22:23], 0, v[168:169]
	s_mov_b32 m0, s73
	ds_read_b128 v[162:165], v224 offset:16384
	ds_read_b128 v[190:193], v224 offset:17408
	ds_read_b128 v[194:197], v224 offset:18432
	ds_read_b128 v[198:201], v224 offset:19456
	ds_read_b128 v[226:229], v224 offset:20480
	ds_read_b128 v[230:233], v224 offset:21504
	ds_read_b128 v[234:237], v224 offset:22528
	ds_read_b128 v[238:241], v224 offset:23552
	global_load_lds_dwordx4 v[166:167], off
	s_add_i32 m0, s73, 0x2000
	s_add_u32 s88, s22, 0x160000
	v_lshl_add_u64 v[242:243], s[22:23], 0, v[176:177]
	s_addc_u32 s89, s23, 0
	s_add_i32 s72, s72, s34
	global_load_lds_dwordx4 v[242:243], off
	v_lshl_add_u64 v[244:245], s[88:89], 0, v[168:169]
	s_mov_b32 m0, s72
	v_lshl_add_u64 v[246:247], s[24:25], 0, v[176:177]
	global_load_lds_dwordx4 v[244:245], off
	v_lshl_add_u64 v[244:245], s[88:89], 0, v[176:177]
	s_add_i32 m0, s72, 0x2000
	s_nop 0
	global_load_lds_dwordx4 v[244:245], off
	v_lshl_add_u64 v[244:245], s[24:25], 0, v[168:169]
	s_mov_b32 m0, s35
	s_nop 0
	global_load_lds_dwordx4 v[244:245], off
	s_mov_b32 m0, s36
	s_nop 0
	global_load_lds_dwordx4 v[246:247], off
	s_waitcnt vmcnt(8)
	s_waitcnt lgkmcnt(0)
	s_barrier
; #define PG8_STAGE(bufoff, gbase, voff) do { _Pragma("unroll") for (int _i = 0; _i < 2; ++_i) \
;         __builtin_amdgcn_global_load_lds((const unsigned*)((const char*)(gbase) + (voff)[_i]), (LAS unsigned*)(lds + (bufoff) + ldsw + _i * 8192), 16, 0, 0); } while (0)
; #define PG8_LDA(dst, b, h) do { _Pragma("unroll") for (int m = 0; m < 4; ++m) _Pragma("unroll") for (int k = 0; k < 2; ++k) dst[m][k] = *(const LAS bf16x8*)(lds + PG8_SA(b, h) + aoff + m * 2048 + k * 1024); } while (0)
; #define PG8_LDB(dst, b, h) do { _Pragma("unroll") for (int n = 0; n < 2; ++n) _Pragma("unroll") for (int k = 0; k < 2; ++k) dst[n][k] = *(const LAS bf16x8*)(lds + PG8_SB(b, h) + boff + n * 2048 + k * 1024); } while (0)
; #define PG8_MMA(ai, bj, At, Bt) do { __builtin_amdgcn_s_setprio(1); _Pragma("unroll") for (int m = 0; m < 4; ++m) _Pragma("unroll") for (int n = 0; n < 2; ++n) _Pragma("unroll") for (int k = 0; k < 2; ++k) \
;         acc[ai][bj][m][n] = __builtin_amdgcn_mfma_f32_16x16x32_bf16(Bt[n][k], At[m][k], acc[ai][bj][m][n], 0, 0, 0); __builtin_amdgcn_s_setprio(0); } while (0)
; #define PG8_WAIT_V(n) asm volatile("s_waitcnt vmcnt(" #n ")" ::: "memory")
; #define PG8_WAIT_L(n) asm volatile("s_waitcnt lgkmcnt(" #n ")" ::: "memory")
; #define PG8_BAR __builtin_amdgcn_s_barrier()
; #define PG8_SCHED __builtin_amdgcn_sched_barrier(0)
; template <class Epi>
; __device__ __forceinline__ void gemm_phase(LAS unsigned char* lds, const Sched& S, const Epi& E) {
;     ...
;             PG8_WAIT_V(8); PG8_WAIT_L(0); PG8_BAR; PG8_MMA(1, 0, At, B0); PG8_MMA(1, 1, At, B1); PG8_BAR; PG8_SCHED;
;             PG8_LDB(B0, 1, 0); PG8_LDB(B1, 1, 1); PG8_SCHED; PG8_LDA(At, 1, 0); PG8_STAGE(PG8_SA(0, 1), a2 + hstepA, voffA);
;             PG8_WAIT_V(8); PG8_WAIT_L(0); PG8_BAR; PG8_MMA(0, 0, At, B0); PG8_MMA(0, 1, At, B1); PG8_BAR; PG8_SCHED;
	s_setprio 1
	s_waitcnt lgkmcnt(0)
	v_mfma_f32_16x16x32_bf16 v[62:65], v[130:133], v[162:165], 0
	v_mfma_f32_16x16x32_bf16 v[58:61], v[138:141], v[162:165], 0
	v_mfma_f32_16x16x32_bf16 v[54:57], v[130:133], v[194:197], 0
	v_mfma_f32_16x16x32_bf16 v[42:45], v[138:141], v[194:197], 0
	v_mfma_f32_16x16x32_bf16 v[30:33], v[130:133], v[226:229], 0
	v_mfma_f32_16x16x32_bf16 v[26:29], v[138:141], v[226:229], 0
	v_mfma_f32_16x16x32_bf16 v[22:25], v[130:133], v[234:237], 0
	v_mfma_f32_16x16x32_bf16 v[10:13], v[138:141], v[234:237], 0
	v_mfma_f32_16x16x32_bf16 v[62:65], v[134:137], v[190:193], v[62:65]
	v_mfma_f32_16x16x32_bf16 v[58:61], v[142:145], v[190:193], v[58:61]
	v_mfma_f32_16x16x32_bf16 v[54:57], v[134:137], v[198:201], v[54:57]
	v_mfma_f32_16x16x32_bf16 v[42:45], v[142:145], v[198:201], v[42:45]
	v_mfma_f32_16x16x32_bf16 v[30:33], v[134:137], v[230:233], v[30:33]
	v_mfma_f32_16x16x32_bf16 v[26:29], v[142:145], v[230:233], v[26:29]
	v_mfma_f32_16x16x32_bf16 v[22:25], v[134:137], v[238:241], v[22:25]
	v_mfma_f32_16x16x32_bf16 v[10:13], v[142:145], v[238:241], v[10:13]
	s_setprio 0
	s_setprio 1
	v_mfma_f32_16x16x32_bf16 v[50:53], v[146:149], v[162:165], 0
	v_mfma_f32_16x16x32_bf16 v[46:49], v[154:157], v[162:165], 0
	v_mfma_f32_16x16x32_bf16 v[38:41], v[146:149], v[194:197], 0
	v_mfma_f32_16x16x32_bf16 v[34:37], v[154:157], v[194:197], 0
	v_mfma_f32_16x16x32_bf16 v[18:21], v[146:149], v[226:229], 0
	v_mfma_f32_16x16x32_bf16 v[14:17], v[154:157], v[226:229], 0
	v_mfma_f32_16x16x32_bf16 v[6:9], v[146:149], v[234:237], 0
	v_mfma_f32_16x16x32_bf16 v[2:5], v[154:157], v[234:237], 0
	v_mfma_f32_16x16x32_bf16 v[50:53], v[150:153], v[190:193], v[50:53]
	v_mfma_f32_16x16x32_bf16 v[46:49], v[158:161], v[190:193], v[46:49]
	v_mfma_f32_16x16x32_bf16 v[38:41], v[150:153], v[198:201], v[38:41]
	v_mfma_f32_16x16x32_bf16 v[34:37], v[158:161], v[198:201], v[34:37]
	v_mfma_f32_16x16x32_bf16 v[18:21], v[150:153], v[230:233], v[18:21]
	v_mfma_f32_16x16x32_bf16 v[14:17], v[158:161], v[230:233], v[14:17]
	v_mfma_f32_16x16x32_bf16 v[6:9], v[150:153], v[238:241], v[6:9]
	v_mfma_f32_16x16x32_bf16 v[2:5], v[158:161], v[238:241], v[2:5]
	s_setprio 0
	s_barrier
	s_add_i32 s72, 0, 0x18000
	s_add_i32 s73, 0, 0x1c000
	v_add_u32_e32 v142, s72, v222
	v_add_u32_e32 v158, s73, v222
	ds_read_b128 v[130:133], v142
	ds_read_b128 v[134:137], v142 offset:1024
	ds_read_b128 v[138:141], v142 offset:2048
	ds_read_b128 v[142:145], v142 offset:3072
	ds_read_b128 v[146:149], v158
	ds_read_b128 v[150:153], v158 offset:1024
	ds_read_b128 v[154:157], v158 offset:2048
	ds_read_b128 v[158:161], v158 offset:3072
	s_add_u32 s24, s24, 0x160000
	s_addc_u32 s25, s25, 0
	s_mov_b32 m0, s37
	v_lshl_add_u64 v[248:249], s[24:25], 0, v[168:169]
	ds_read_b128 v[162:165], v224 offset:32768
	ds_read_b128 v[190:193], v224 offset:33792
	ds_read_b128 v[194:197], v224 offset:34816
	ds_read_b128 v[198:201], v224 offset:35840
	ds_read_b128 v[226:229], v224 offset:36864
	ds_read_b128 v[230:233], v224 offset:37888
	ds_read_b128 v[234:237], v224 offset:38912
	ds_read_b128 v[238:241], v224 offset:39936
	global_load_lds_dwordx4 v[248:249], off
	v_lshl_add_u64 v[248:249], s[24:25], 0, v[176:177]
	s_mov_b32 m0, s38
	s_nop 0
	global_load_lds_dwordx4 v[248:249], off
	s_waitcnt vmcnt(8)
	s_waitcnt lgkmcnt(0)
	s_barrier
	s_setprio 1
	s_waitcnt lgkmcnt(0)
	v_mfma_f32_16x16x32_bf16 v[126:129], v[130:133], v[162:165], v[126:129]
	v_mfma_f32_16x16x32_bf16 v[122:125], v[138:141], v[162:165], v[122:125]
	v_mfma_f32_16x16x32_bf16 v[118:121], v[130:133], v[194:197], v[118:121]
	v_mfma_f32_16x16x32_bf16 v[106:109], v[138:141], v[194:197], v[106:109]
	v_mfma_f32_16x16x32_bf16 v[94:97], v[130:133], v[226:229], v[94:97]
	v_mfma_f32_16x16x32_bf16 v[90:93], v[138:141], v[226:229], v[90:93]
	v_mfma_f32_16x16x32_bf16 v[86:89], v[130:133], v[234:237], v[86:89]
	v_mfma_f32_16x16x32_bf16 v[74:77], v[138:141], v[234:237], v[74:77]
	v_mfma_f32_16x16x32_bf16 v[126:129], v[134:137], v[190:193], v[126:129]
	v_mfma_f32_16x16x32_bf16 v[122:125], v[142:145], v[190:193], v[122:125]
	v_mfma_f32_16x16x32_bf16 v[118:121], v[134:137], v[198:201], v[118:121]
	v_mfma_f32_16x16x32_bf16 v[106:109], v[142:145], v[198:201], v[106:109]
	v_mfma_f32_16x16x32_bf16 v[94:97], v[134:137], v[230:233], v[94:97]
	v_mfma_f32_16x16x32_bf16 v[90:93], v[142:145], v[230:233], v[90:93]
	v_mfma_f32_16x16x32_bf16 v[86:89], v[134:137], v[238:241], v[86:89]
	v_mfma_f32_16x16x32_bf16 v[74:77], v[142:145], v[238:241], v[74:77]
	s_setprio 0
	s_setprio 1
	v_mfma_f32_16x16x32_bf16 v[114:117], v[146:149], v[162:165], v[114:117]
	v_mfma_f32_16x16x32_bf16 v[110:113], v[154:157], v[162:165], v[110:113]
	v_mfma_f32_16x16x32_bf16 v[102:105], v[146:149], v[194:197], v[102:105]
	v_mfma_f32_16x16x32_bf16 v[98:101], v[154:157], v[194:197], v[98:101]
	v_mfma_f32_16x16x32_bf16 v[82:85], v[146:149], v[226:229], v[82:85]
	v_mfma_f32_16x16x32_bf16 v[78:81], v[154:157], v[226:229], v[78:81]
	v_mfma_f32_16x16x32_bf16 v[70:73], v[146:149], v[234:237], v[70:73]
	v_mfma_f32_16x16x32_bf16 v[66:69], v[154:157], v[234:237], v[66:69]
	v_mfma_f32_16x16x32_bf16 v[114:117], v[150:153], v[190:193], v[114:117]
	v_mfma_f32_16x16x32_bf16 v[110:113], v[158:161], v[190:193], v[110:113]
	v_mfma_f32_16x16x32_bf16 v[102:105], v[150:153], v[198:201], v[102:105]
	v_mfma_f32_16x16x32_bf16 v[98:101], v[158:161], v[198:201], v[98:101]
	v_mfma_f32_16x16x32_bf16 v[82:85], v[150:153], v[230:233], v[82:85]
	v_mfma_f32_16x16x32_bf16 v[78:81], v[158:161], v[230:233], v[78:81]
	v_mfma_f32_16x16x32_bf16 v[70:73], v[150:153], v[238:241], v[70:73]
	v_mfma_f32_16x16x32_bf16 v[66:69], v[158:161], v[238:241], v[66:69]
	s_setprio 0
	s_barrier
; #define PG8_STAGE(bufoff, gbase, voff) do { _Pragma("unroll") for (int _i = 0; _i < 2; ++_i) \
;         __builtin_amdgcn_global_load_lds((const unsigned*)((const char*)(gbase) + (voff)[_i]), (LAS unsigned*)(lds + (bufoff) + ldsw + _i * 8192), 16, 0, 0); } while (0)
; #define PG8_LDA(dst, b, h) do { _Pragma("unroll") for (int m = 0; m < 4; ++m) _Pragma("unroll") for (int k = 0; k < 2; ++k) dst[m][k] = *(const LAS bf16x8*)(lds + PG8_SA(b, h) + aoff + m * 2048 + k * 1024); } while (0)
; #define PG8_LDB(dst, b, h) do { _Pragma("unroll") for (int n = 0; n < 2; ++n) _Pragma("unroll") for (int k = 0; k < 2; ++k) dst[n][k] = *(const LAS bf16x8*)(lds + PG8_SB(b, h) + boff + n * 2048 + k * 1024); } while (0)
; #define PG8_MMA(ai, bj, At, Bt) do { __builtin_amdgcn_s_setprio(1); _Pragma("unroll") for (int m = 0; m < 4; ++m) _Pragma("unroll") for (int n = 0; n < 2; ++n) _Pragma("unroll") for (int k = 0; k < 2; ++k) \
;         acc[ai][bj][m][n] = __builtin_amdgcn_mfma_f32_16x16x32_bf16(Bt[n][k], At[m][k], acc[ai][bj][m][n], 0, 0, 0); __builtin_amdgcn_s_setprio(0); } while (0)
; #define PG8_WAIT_V(n) asm volatile("s_waitcnt vmcnt(" #n ")" ::: "memory")
; #define PG8_WAIT_L(n) asm volatile("s_waitcnt lgkmcnt(" #n ")" ::: "memory")
; #define PG8_BAR __builtin_amdgcn_s_barrier()
; #define PG8_SCHED __builtin_amdgcn_sched_barrier(0)
; template <class Epi>
; __device__ __forceinline__ void gemm_phase(LAS unsigned char* lds, const Sched& S, const Epi& E) {
;     ...
;         for (int t = 0; t < nt; t += 2) {
;             const bool last = (t == nt - 2);
;             const char* a1 = cA + (size_t)(t + 1) * kstep;
;             const char* a2 = last ? nA : cA + (size_t)(t + 2) * kstep; const char* b2 = last ? nB : cB + (size_t)(t + 2) * kstep;
;             const char* a3 = a2 + kstep; const char* b3 = b2 + kstep;
;             PG8_LDB(B0, 0, 0); PG8_LDB(B1, 0, 1); PG8_SCHED; PG8_LDA(At, 0, 0); PG8_STAGE(PG8_SA(1, 1), a1 + hstepA, voffA);
;             PG8_WAIT_V(8); PG8_WAIT_L(0); PG8_BAR; PG8_MMA(0, 0, At, B0); PG8_MMA(0, 1, At, B1); PG8_BAR; PG8_SCHED;
;     ...
;             PG8_LDA(At, 1, 1); PG8_STAGE(PG8_SB(1, 0), b3, voffB); PG8_STAGE(PG8_SB(1, 1), b3 + hstepB, voffB); PG8_STAGE(PG8_SA(1, 0), a3, voffA);
;             PG8_WAIT_V(8); PG8_WAIT_L(0); PG8_BAR; PG8_MMA(1, 0, At, B0); PG8_MMA(1, 1, At, B1); PG8_BAR; PG8_SCHED;
	s_add_i32 s24, s72, s34
	v_lshl_add_u64 v[166:167], v[166:167], 0, s[0:1]
	s_mov_b32 m0, s24
	ds_read_b128 v[162:165], v224 offset:49152
	ds_read_b128 v[190:193], v224 offset:50176
	ds_read_b128 v[194:197], v224 offset:51200
	ds_read_b128 v[198:201], v224 offset:52224
	ds_read_b128 v[226:229], v224 offset:53248
	ds_read_b128 v[230:233], v224 offset:54272
	ds_read_b128 v[234:237], v224 offset:55296
	ds_read_b128 v[238:241], v224 offset:56320
	global_load_lds_dwordx4 v[166:167], off
	s_add_i32 m0, s24, 0x2000
	s_add_u32 s22, s22, 0x160080
	v_lshl_add_u64 v[166:167], v[242:243], 0, s[0:1]
	s_addc_u32 s23, s23, 0
	s_add_i32 s24, s73, s34
	global_load_lds_dwordx4 v[166:167], off
	v_lshl_add_u64 v[166:167], s[22:23], 0, v[168:169]
	s_mov_b32 m0, s24
	s_nop 0
	global_load_lds_dwordx4 v[166:167], off
	v_lshl_add_u64 v[166:167], s[22:23], 0, v[176:177]
	s_add_i32 m0, s24, 0x2000
	s_nop 0
	global_load_lds_dwordx4 v[166:167], off
	v_lshl_add_u64 v[166:167], v[244:245], 0, s[0:1]
	s_mov_b32 m0, s39
	s_nop 0
	global_load_lds_dwordx4 v[166:167], off
	v_lshl_add_u64 v[166:167], v[246:247], 0, s[0:1]
	s_mov_b32 m0, s58
	s_nop 0
	global_load_lds_dwordx4 v[166:167], off
	s_waitcnt vmcnt(8)
	s_waitcnt lgkmcnt(0)
	s_barrier
	s_setprio 1
	s_waitcnt lgkmcnt(0)
	v_mfma_f32_16x16x32_bf16 v[62:65], v[130:133], v[162:165], v[62:65]
	v_mfma_f32_16x16x32_bf16 v[58:61], v[138:141], v[162:165], v[58:61]
	v_mfma_f32_16x16x32_bf16 v[54:57], v[130:133], v[194:197], v[54:57]
	v_mfma_f32_16x16x32_bf16 v[42:45], v[138:141], v[194:197], v[42:45]
	v_mfma_f32_16x16x32_bf16 v[30:33], v[130:133], v[226:229], v[30:33]
	v_mfma_f32_16x16x32_bf16 v[26:29], v[138:141], v[226:229], v[26:29]
	v_mfma_f32_16x16x32_bf16 v[22:25], v[130:133], v[234:237], v[22:25]
	v_mfma_f32_16x16x32_bf16 v[10:13], v[138:141], v[234:237], v[10:13]
	v_mfma_f32_16x16x32_bf16 v[62:65], v[134:137], v[190:193], v[62:65]
	v_mfma_f32_16x16x32_bf16 v[58:61], v[142:145], v[190:193], v[58:61]
	v_mfma_f32_16x16x32_bf16 v[54:57], v[134:137], v[198:201], v[54:57]
	v_mfma_f32_16x16x32_bf16 v[42:45], v[142:145], v[198:201], v[42:45]
	v_mfma_f32_16x16x32_bf16 v[30:33], v[134:137], v[230:233], v[30:33]
	v_mfma_f32_16x16x32_bf16 v[26:29], v[142:145], v[230:233], v[26:29]
	v_mfma_f32_16x16x32_bf16 v[22:25], v[134:137], v[238:241], v[22:25]
	v_mfma_f32_16x16x32_bf16 v[10:13], v[142:145], v[238:241], v[10:13]
	s_setprio 0
	s_setprio 1
	v_mfma_f32_16x16x32_bf16 v[50:53], v[146:149], v[162:165], v[50:53]
	v_mfma_f32_16x16x32_bf16 v[46:49], v[154:157], v[162:165], v[46:49]
	v_mfma_f32_16x16x32_bf16 v[38:41], v[146:149], v[194:197], v[38:41]
	v_mfma_f32_16x16x32_bf16 v[34:37], v[154:157], v[194:197], v[34:37]
	v_mfma_f32_16x16x32_bf16 v[18:21], v[146:149], v[226:229], v[18:21]
	v_mfma_f32_16x16x32_bf16 v[14:17], v[154:157], v[226:229], v[14:17]
	v_mfma_f32_16x16x32_bf16 v[6:9], v[146:149], v[234:237], v[6:9]
	v_mfma_f32_16x16x32_bf16 v[2:5], v[154:157], v[234:237], v[2:5]
	v_mfma_f32_16x16x32_bf16 v[50:53], v[150:153], v[190:193], v[50:53]
	v_mfma_f32_16x16x32_bf16 v[46:49], v[158:161], v[190:193], v[46:49]
	v_mfma_f32_16x16x32_bf16 v[38:41], v[150:153], v[198:201], v[38:41]
	v_mfma_f32_16x16x32_bf16 v[34:37], v[158:161], v[198:201], v[34:37]
	v_mfma_f32_16x16x32_bf16 v[18:21], v[150:153], v[230:233], v[18:21]
	v_mfma_f32_16x16x32_bf16 v[14:17], v[158:161], v[230:233], v[14:17]
	v_mfma_f32_16x16x32_bf16 v[6:9], v[150:153], v[238:241], v[6:9]
	v_mfma_f32_16x16x32_bf16 v[2:5], v[158:161], v[238:241], v[2:5]
	s_setprio 0
	s_barrier
	s_add_u32 s4, s4, 0x100
	s_addc_u32 s5, s5, 0
	s_add_u32 vcc_lo, vcc_lo, 0x100
	s_addc_u32 vcc_hi, vcc_hi, 0
	s_cmp_ge_i32 s49, s94
	s_mov_b32 s22, s49
	s_cbranch_scc1 .Lpeel_exit_down
.LBB0_2391:
	s_add_i32 s49, s22, 2
	s_add_u32 s23, s4, 0xffea0080
	s_addc_u32 s24, s5, -1
	s_add_i32 s88, 0, 0x10000
	s_cmp_eq_u32 s97, s22
	s_cselect_b32 s25, s26, s24
	s_cselect_b32 s24, s27, s23
	s_cselect_b32 s23, s95, vcc_hi
	s_cselect_b32 s22, s96, vcc_lo
	s_add_i32 s72, 0, 0x14000
	v_add_u32_e32 v142, s88, v222
	v_add_u32_e32 v158, s72, v222
	ds_read_b128 v[130:133], v142
	ds_read_b128 v[134:137], v142 offset:1024
	ds_read_b128 v[138:141], v142 offset:2048
	ds_read_b128 v[142:145], v142 offset:3072
	ds_read_b128 v[146:149], v158
	ds_read_b128 v[150:153], v158 offset:1024
	ds_read_b128 v[154:157], v158 offset:2048
	ds_read_b128 v[158:161], v158 offset:3072
	v_lshl_add_u64 v[166:167], s[4:5], 0, v[186:187]
	s_add_i32 m0, s35, 0xc000
	ds_read_b128 v[162:165], v224
	ds_read_b128 v[190:193], v224 offset:1024
	ds_read_b128 v[194:197], v224 offset:2048
	ds_read_b128 v[198:201], v224 offset:3072
	ds_read_b128 v[226:229], v224 offset:4096
	ds_read_b128 v[230:233], v224 offset:5120
	ds_read_b128 v[234:237], v224 offset:6144
	ds_read_b128 v[238:241], v224 offset:7168
	global_load_lds_dwordx4 v[166:167], off
	v_lshl_add_u64 v[166:167], s[4:5], 0, v[188:189]
	s_add_i32 m0, s35, 0xe000
	s_nop 0
	global_load_lds_dwordx4 v[166:167], off
	s_waitcnt vmcnt(8)
	s_waitcnt lgkmcnt(0)
	s_barrier
; #define PG8_STAGE(bufoff, gbase, voff) do { _Pragma("unroll") for (int _i = 0; _i < 2; ++_i) \
;         __builtin_amdgcn_global_load_lds((const unsigned*)((const char*)(gbase) + (voff)[_i]), (LAS unsigned*)(lds + (bufoff) + ldsw + _i * 8192), 16, 0, 0); } while (0)
; #define PG8_LDA(dst, b, h) do { _Pragma("unroll") for (int m = 0; m < 4; ++m) _Pragma("unroll") for (int k = 0; k < 2; ++k) dst[m][k] = *(const LAS bf16x8*)(lds + PG8_SA(b, h) + aoff + m * 2048 + k * 1024); } while (0)
; #define PG8_LDB(dst, b, h) do { _Pragma("unroll") for (int n = 0; n < 2; ++n) _Pragma("unroll") for (int k = 0; k < 2; ++k) dst[n][k] = *(const LAS bf16x8*)(lds + PG8_SB(b, h) + boff + n * 2048 + k * 1024); } while (0)
; #define PG8_MMA(ai, bj, At, Bt) do { __builtin_amdgcn_s_setprio(1); _Pragma("unroll") for (int m = 0; m < 4; ++m) _Pragma("unroll") for (int n = 0; n < 2; ++n) _Pragma("unroll") for (int k = 0; k < 2; ++k) \
;         acc[ai][bj][m][n] = __builtin_amdgcn_mfma_f32_16x16x32_bf16(Bt[n][k], At[m][k], acc[ai][bj][m][n], 0, 0, 0); __builtin_amdgcn_s_setprio(0); } while (0)
; #define PG8_WAIT_V(n) asm volatile("s_waitcnt vmcnt(" #n ")" ::: "memory")
; #define PG8_WAIT_L(n) asm volatile("s_waitcnt lgkmcnt(" #n ")" ::: "memory")
; #define PG8_BAR __builtin_amdgcn_s_barrier()
; #define PG8_SCHED __builtin_amdgcn_sched_barrier(0)
; template <class Epi>
; __device__ __forceinline__ void gemm_phase(LAS unsigned char* lds, const Sched& S, const Epi& E) {
;     ...
;             PG8_WAIT_V(8); PG8_WAIT_L(0); PG8_BAR; PG8_MMA(0, 0, At, B0); PG8_MMA(0, 1, At, B1); PG8_BAR; PG8_SCHED;
;             PG8_LDA(At, 0, 1); PG8_STAGE(PG8_SB(0, 0), b2, voffB); PG8_STAGE(PG8_SB(0, 1), b2 + hstepB, voffB); PG8_STAGE(PG8_SA(0, 0), a2, voffA);
;             PG8_WAIT_V(8); PG8_WAIT_L(0); PG8_BAR; PG8_MMA(1, 0, At, B0); PG8_MMA(1, 1, At, B1); PG8_BAR; PG8_SCHED;
;             PG8_LDB(B0, 1, 0); PG8_LDB(B1, 1, 1); PG8_SCHED; PG8_LDA(At, 1, 0); PG8_STAGE(PG8_SA(0, 1), a2 + hstepA, voffA);
;             PG8_WAIT_V(8); PG8_WAIT_L(0); PG8_BAR; PG8_MMA(0, 0, At, B0); PG8_MMA(0, 1, At, B1); PG8_BAR; PG8_SCHED;
	s_setprio 1
	s_waitcnt lgkmcnt(0)
	v_mfma_f32_16x16x32_bf16 v[126:129], v[130:133], v[162:165], v[126:129]
	v_mfma_f32_16x16x32_bf16 v[122:125], v[138:141], v[162:165], v[122:125]
	v_mfma_f32_16x16x32_bf16 v[118:121], v[130:133], v[194:197], v[118:121]
	v_mfma_f32_16x16x32_bf16 v[106:109], v[138:141], v[194:197], v[106:109]
	v_mfma_f32_16x16x32_bf16 v[94:97], v[130:133], v[226:229], v[94:97]
	v_mfma_f32_16x16x32_bf16 v[90:93], v[138:141], v[226:229], v[90:93]
	v_mfma_f32_16x16x32_bf16 v[86:89], v[130:133], v[234:237], v[86:89]
	v_mfma_f32_16x16x32_bf16 v[74:77], v[138:141], v[234:237], v[74:77]
	v_mfma_f32_16x16x32_bf16 v[126:129], v[134:137], v[190:193], v[126:129]
	v_mfma_f32_16x16x32_bf16 v[122:125], v[142:145], v[190:193], v[122:125]
	v_mfma_f32_16x16x32_bf16 v[118:121], v[134:137], v[198:201], v[118:121]
	v_mfma_f32_16x16x32_bf16 v[106:109], v[142:145], v[198:201], v[106:109]
	v_mfma_f32_16x16x32_bf16 v[94:97], v[134:137], v[230:233], v[94:97]
	v_mfma_f32_16x16x32_bf16 v[90:93], v[142:145], v[230:233], v[90:93]
	v_mfma_f32_16x16x32_bf16 v[86:89], v[134:137], v[238:241], v[86:89]
	v_mfma_f32_16x16x32_bf16 v[74:77], v[142:145], v[238:241], v[74:77]
	s_setprio 0
	s_setprio 1
	v_mfma_f32_16x16x32_bf16 v[114:117], v[146:149], v[162:165], v[114:117]
	v_mfma_f32_16x16x32_bf16 v[110:113], v[154:157], v[162:165], v[110:113]
	v_mfma_f32_16x16x32_bf16 v[102:105], v[146:149], v[194:197], v[102:105]
	v_mfma_f32_16x16x32_bf16 v[98:101], v[154:157], v[194:197], v[98:101]
	v_mfma_f32_16x16x32_bf16 v[82:85], v[146:149], v[226:229], v[82:85]
	v_mfma_f32_16x16x32_bf16 v[78:81], v[154:157], v[226:229], v[78:81]
	v_mfma_f32_16x16x32_bf16 v[70:73], v[146:149], v[234:237], v[70:73]
	v_mfma_f32_16x16x32_bf16 v[66:69], v[154:157], v[234:237], v[66:69]
	v_mfma_f32_16x16x32_bf16 v[114:117], v[150:153], v[190:193], v[114:117]
	v_mfma_f32_16x16x32_bf16 v[110:113], v[158:161], v[190:193], v[110:113]
	v_mfma_f32_16x16x32_bf16 v[102:105], v[150:153], v[198:201], v[102:105]
	v_mfma_f32_16x16x32_bf16 v[98:101], v[158:161], v[198:201], v[98:101]
	v_mfma_f32_16x16x32_bf16 v[82:85], v[150:153], v[230:233], v[82:85]
	v_mfma_f32_16x16x32_bf16 v[78:81], v[158:161], v[230:233], v[78:81]
	v_mfma_f32_16x16x32_bf16 v[70:73], v[150:153], v[238:241], v[70:73]
	v_mfma_f32_16x16x32_bf16 v[66:69], v[158:161], v[238:241], v[66:69]
	s_setprio 0
	s_barrier
	s_add_i32 s73, s88, s34
	v_lshl_add_u64 v[166:167], s[22:23], 0, v[168:169]
	s_mov_b32 m0, s73
	ds_read_b128 v[162:165], v224 offset:16384
	ds_read_b128 v[190:193], v224 offset:17408
	ds_read_b128 v[194:197], v224 offset:18432
	ds_read_b128 v[198:201], v224 offset:19456
	ds_read_b128 v[226:229], v224 offset:20480
	ds_read_b128 v[230:233], v224 offset:21504
	ds_read_b128 v[234:237], v224 offset:22528
	ds_read_b128 v[238:241], v224 offset:23552
	global_load_lds_dwordx4 v[166:167], off
	s_add_i32 m0, s73, 0x2000
	s_add_u32 s88, s22, 0x160000
	v_lshl_add_u64 v[242:243], s[22:23], 0, v[176:177]
	s_addc_u32 s89, s23, 0
	s_add_i32 s72, s72, s34
	global_load_lds_dwordx4 v[242:243], off
	v_lshl_add_u64 v[244:245], s[88:89], 0, v[168:169]
	s_mov_b32 m0, s72
	v_lshl_add_u64 v[246:247], s[24:25], 0, v[176:177]
	global_load_lds_dwordx4 v[244:245], off
	v_lshl_add_u64 v[244:245], s[88:89], 0, v[176:177]
	s_add_i32 m0, s72, 0x2000
	s_nop 0
	global_load_lds_dwordx4 v[244:245], off
	v_lshl_add_u64 v[244:245], s[24:25], 0, v[168:169]
	s_mov_b32 m0, s35
	s_nop 0
	global_load_lds_dwordx4 v[244:245], off
	s_mov_b32 m0, s36
	s_nop 0
	global_load_lds_dwordx4 v[246:247], off
	s_waitcnt vmcnt(8)
	s_waitcnt lgkmcnt(0)
	s_barrier
	s_setprio 1
	s_waitcnt lgkmcnt(0)
	v_mfma_f32_16x16x32_bf16 v[62:65], v[130:133], v[162:165], v[62:65]
	v_mfma_f32_16x16x32_bf16 v[58:61], v[138:141], v[162:165], v[58:61]
	v_mfma_f32_16x16x32_bf16 v[54:57], v[130:133], v[194:197], v[54:57]
	v_mfma_f32_16x16x32_bf16 v[42:45], v[138:141], v[194:197], v[42:45]
	v_mfma_f32_16x16x32_bf16 v[30:33], v[130:133], v[226:229], v[30:33]
	v_mfma_f32_16x16x32_bf16 v[26:29], v[138:141], v[226:229], v[26:29]
	v_mfma_f32_16x16x32_bf16 v[22:25], v[130:133], v[234:237], v[22:25]
	v_mfma_f32_16x16x32_bf16 v[10:13], v[138:141], v[234:237], v[10:13]
	v_mfma_f32_16x16x32_bf16 v[62:65], v[134:137], v[190:193], v[62:65]
	v_mfma_f32_16x16x32_bf16 v[58:61], v[142:145], v[190:193], v[58:61]
	v_mfma_f32_16x16x32_bf16 v[54:57], v[134:137], v[198:201], v[54:57]
	v_mfma_f32_16x16x32_bf16 v[42:45], v[142:145], v[198:201], v[42:45]
	v_mfma_f32_16x16x32_bf16 v[30:33], v[134:137], v[230:233], v[30:33]
	v_mfma_f32_16x16x32_bf16 v[26:29], v[142:145], v[230:233], v[26:29]
	v_mfma_f32_16x16x32_bf16 v[22:25], v[134:137], v[238:241], v[22:25]
	v_mfma_f32_16x16x32_bf16 v[10:13], v[142:145], v[238:241], v[10:13]
	s_setprio 0
	s_setprio 1
	v_mfma_f32_16x16x32_bf16 v[50:53], v[146:149], v[162:165], v[50:53]
	v_mfma_f32_16x16x32_bf16 v[46:49], v[154:157], v[162:165], v[46:49]
	v_mfma_f32_16x16x32_bf16 v[38:41], v[146:149], v[194:197], v[38:41]
	v_mfma_f32_16x16x32_bf16 v[34:37], v[154:157], v[194:197], v[34:37]
	v_mfma_f32_16x16x32_bf16 v[18:21], v[146:149], v[226:229], v[18:21]
	v_mfma_f32_16x16x32_bf16 v[14:17], v[154:157], v[226:229], v[14:17]
	v_mfma_f32_16x16x32_bf16 v[6:9], v[146:149], v[234:237], v[6:9]
	v_mfma_f32_16x16x32_bf16 v[2:5], v[154:157], v[234:237], v[2:5]
	v_mfma_f32_16x16x32_bf16 v[50:53], v[150:153], v[190:193], v[50:53]
	v_mfma_f32_16x16x32_bf16 v[46:49], v[158:161], v[190:193], v[46:49]
	v_mfma_f32_16x16x32_bf16 v[38:41], v[150:153], v[198:201], v[38:41]
	v_mfma_f32_16x16x32_bf16 v[34:37], v[158:161], v[198:201], v[34:37]
	v_mfma_f32_16x16x32_bf16 v[18:21], v[150:153], v[230:233], v[18:21]
	v_mfma_f32_16x16x32_bf16 v[14:17], v[158:161], v[230:233], v[14:17]
	v_mfma_f32_16x16x32_bf16 v[6:9], v[150:153], v[238:241], v[6:9]
	v_mfma_f32_16x16x32_bf16 v[2:5], v[158:161], v[238:241], v[2:5]
	s_setprio 0
	s_barrier
; #define PG8_STAGE(bufoff, gbase, voff) do { _Pragma("unroll") for (int _i = 0; _i < 2; ++_i) \
;         __builtin_amdgcn_global_load_lds((const unsigned*)((const char*)(gbase) + (voff)[_i]), (LAS unsigned*)(lds + (bufoff) + ldsw + _i * 8192), 16, 0, 0); } while (0)
; #define PG8_LDA(dst, b, h) do { _Pragma("unroll") for (int m = 0; m < 4; ++m) _Pragma("unroll") for (int k = 0; k < 2; ++k) dst[m][k] = *(const LAS bf16x8*)(lds + PG8_SA(b, h) + aoff + m * 2048 + k * 1024); } while (0)
; #define PG8_LDB(dst, b, h) do { _Pragma("unroll") for (int n = 0; n < 2; ++n) _Pragma("unroll") for (int k = 0; k < 2; ++k) dst[n][k] = *(const LAS bf16x8*)(lds + PG8_SB(b, h) + boff + n * 2048 + k * 1024); } while (0)
; #define PG8_MMA(ai, bj, At, Bt) do { __builtin_amdgcn_s_setprio(1); _Pragma("unroll") for (int m = 0; m < 4; ++m) _Pragma("unroll") for (int n = 0; n < 2; ++n) _Pragma("unroll") for (int k = 0; k < 2; ++k) \
;         acc[ai][bj][m][n] = __builtin_amdgcn_mfma_f32_16x16x32_bf16(Bt[n][k], At[m][k], acc[ai][bj][m][n], 0, 0, 0); __builtin_amdgcn_s_setprio(0); } while (0)
; #define PG8_WAIT_V(n) asm volatile("s_waitcnt vmcnt(" #n ")" ::: "memory")
; #define PG8_WAIT_L(n) asm volatile("s_waitcnt lgkmcnt(" #n ")" ::: "memory")
; #define PG8_BAR __builtin_amdgcn_s_barrier()
; #define PG8_SCHED __builtin_amdgcn_sched_barrier(0)
; template <class Epi>
; __device__ __forceinline__ void gemm_phase(LAS unsigned char* lds, const Sched& S, const Epi& E) {
;     ...
;             PG8_LDB(B0, 1, 0); PG8_LDB(B1, 1, 1); PG8_SCHED; PG8_LDA(At, 1, 0); PG8_STAGE(PG8_SA(0, 1), a2 + hstepA, voffA);
;             PG8_WAIT_V(8); PG8_WAIT_L(0); PG8_BAR; PG8_MMA(0, 0, At, B0); PG8_MMA(0, 1, At, B1); PG8_BAR; PG8_SCHED;
;             PG8_LDA(At, 1, 1); PG8_STAGE(PG8_SB(1, 0), b3, voffB); PG8_STAGE(PG8_SB(1, 1), b3 + hstepB, voffB); PG8_STAGE(PG8_SA(1, 0), a3, voffA);
;             PG8_WAIT_V(8); PG8_WAIT_L(0); PG8_BAR; PG8_MMA(1, 0, At, B0); PG8_MMA(1, 1, At, B1); PG8_BAR; PG8_SCHED;
	s_add_i32 s72, 0, 0x18000
	s_add_i32 s73, 0, 0x1c000
	v_add_u32_e32 v142, s72, v222
	v_add_u32_e32 v158, s73, v222
	ds_read_b128 v[130:133], v142
	ds_read_b128 v[134:137], v142 offset:1024
	ds_read_b128 v[138:141], v142 offset:2048
	ds_read_b128 v[142:145], v142 offset:3072
	ds_read_b128 v[146:149], v158
	ds_read_b128 v[150:153], v158 offset:1024
	ds_read_b128 v[154:157], v158 offset:2048
	ds_read_b128 v[158:161], v158 offset:3072
	s_add_u32 s24, s24, 0x160000
	s_addc_u32 s25, s25, 0
	s_mov_b32 m0, s37
	v_lshl_add_u64 v[248:249], s[24:25], 0, v[168:169]
	ds_read_b128 v[162:165], v224 offset:32768
	ds_read_b128 v[190:193], v224 offset:33792
	ds_read_b128 v[194:197], v224 offset:34816
	ds_read_b128 v[198:201], v224 offset:35840
	ds_read_b128 v[226:229], v224 offset:36864
	ds_read_b128 v[230:233], v224 offset:37888
	ds_read_b128 v[234:237], v224 offset:38912
	ds_read_b128 v[238:241], v224 offset:39936
	global_load_lds_dwordx4 v[248:249], off
	v_lshl_add_u64 v[248:249], s[24:25], 0, v[176:177]
	s_mov_b32 m0, s38
	s_nop 0
	global_load_lds_dwordx4 v[248:249], off
	s_waitcnt vmcnt(8)
	s_waitcnt lgkmcnt(0)
	s_barrier
	s_setprio 1
	s_waitcnt lgkmcnt(0)
	v_mfma_f32_16x16x32_bf16 v[126:129], v[130:133], v[162:165], v[126:129]
	v_mfma_f32_16x16x32_bf16 v[122:125], v[138:141], v[162:165], v[122:125]
	v_mfma_f32_16x16x32_bf16 v[118:121], v[130:133], v[194:197], v[118:121]
	v_mfma_f32_16x16x32_bf16 v[106:109], v[138:141], v[194:197], v[106:109]
	v_mfma_f32_16x16x32_bf16 v[94:97], v[130:133], v[226:229], v[94:97]
	v_mfma_f32_16x16x32_bf16 v[90:93], v[138:141], v[226:229], v[90:93]
	v_mfma_f32_16x16x32_bf16 v[86:89], v[130:133], v[234:237], v[86:89]
	v_mfma_f32_16x16x32_bf16 v[74:77], v[138:141], v[234:237], v[74:77]
	v_mfma_f32_16x16x32_bf16 v[126:129], v[134:137], v[190:193], v[126:129]
	v_mfma_f32_16x16x32_bf16 v[122:125], v[142:145], v[190:193], v[122:125]
	v_mfma_f32_16x16x32_bf16 v[118:121], v[134:137], v[198:201], v[118:121]
	v_mfma_f32_16x16x32_bf16 v[106:109], v[142:145], v[198:201], v[106:109]
	v_mfma_f32_16x16x32_bf16 v[94:97], v[134:137], v[230:233], v[94:97]
	v_mfma_f32_16x16x32_bf16 v[90:93], v[142:145], v[230:233], v[90:93]
	v_mfma_f32_16x16x32_bf16 v[86:89], v[134:137], v[238:241], v[86:89]
	v_mfma_f32_16x16x32_bf16 v[74:77], v[142:145], v[238:241], v[74:77]
	s_setprio 0
	s_setprio 1
	v_mfma_f32_16x16x32_bf16 v[114:117], v[146:149], v[162:165], v[114:117]
	v_mfma_f32_16x16x32_bf16 v[110:113], v[154:157], v[162:165], v[110:113]
	v_mfma_f32_16x16x32_bf16 v[102:105], v[146:149], v[194:197], v[102:105]
	v_mfma_f32_16x16x32_bf16 v[98:101], v[154:157], v[194:197], v[98:101]
	v_mfma_f32_16x16x32_bf16 v[82:85], v[146:149], v[226:229], v[82:85]
	v_mfma_f32_16x16x32_bf16 v[78:81], v[154:157], v[226:229], v[78:81]
	v_mfma_f32_16x16x32_bf16 v[70:73], v[146:149], v[234:237], v[70:73]
	v_mfma_f32_16x16x32_bf16 v[66:69], v[154:157], v[234:237], v[66:69]
	v_mfma_f32_16x16x32_bf16 v[114:117], v[150:153], v[190:193], v[114:117]
	v_mfma_f32_16x16x32_bf16 v[110:113], v[158:161], v[190:193], v[110:113]
	v_mfma_f32_16x16x32_bf16 v[102:105], v[150:153], v[198:201], v[102:105]
	v_mfma_f32_16x16x32_bf16 v[98:101], v[158:161], v[198:201], v[98:101]
	v_mfma_f32_16x16x32_bf16 v[82:85], v[150:153], v[230:233], v[82:85]
	v_mfma_f32_16x16x32_bf16 v[78:81], v[158:161], v[230:233], v[78:81]
	v_mfma_f32_16x16x32_bf16 v[70:73], v[150:153], v[238:241], v[70:73]
	v_mfma_f32_16x16x32_bf16 v[66:69], v[158:161], v[238:241], v[66:69]
	s_setprio 0
	s_barrier
	s_add_i32 s24, s72, s34
	v_lshl_add_u64 v[166:167], v[166:167], 0, s[0:1]
	s_mov_b32 m0, s24
	ds_read_b128 v[162:165], v224 offset:49152
	ds_read_b128 v[190:193], v224 offset:50176
	ds_read_b128 v[194:197], v224 offset:51200
	ds_read_b128 v[198:201], v224 offset:52224
	ds_read_b128 v[226:229], v224 offset:53248
	ds_read_b128 v[230:233], v224 offset:54272
	ds_read_b128 v[234:237], v224 offset:55296
	ds_read_b128 v[238:241], v224 offset:56320
	global_load_lds_dwordx4 v[166:167], off
	s_add_i32 m0, s24, 0x2000
	s_add_u32 s22, s22, 0x160080
	v_lshl_add_u64 v[166:167], v[242:243], 0, s[0:1]
	s_addc_u32 s23, s23, 0
	s_add_i32 s24, s73, s34
	global_load_lds_dwordx4 v[166:167], off
	v_lshl_add_u64 v[166:167], s[22:23], 0, v[168:169]
	s_mov_b32 m0, s24
	s_nop 0
	global_load_lds_dwordx4 v[166:167], off
	v_lshl_add_u64 v[166:167], s[22:23], 0, v[176:177]
	s_add_i32 m0, s24, 0x2000
	s_nop 0
	global_load_lds_dwordx4 v[166:167], off
	v_lshl_add_u64 v[166:167], v[244:245], 0, s[0:1]
	s_mov_b32 m0, s39
	s_nop 0
	global_load_lds_dwordx4 v[166:167], off
	v_lshl_add_u64 v[166:167], v[246:247], 0, s[0:1]
	s_mov_b32 m0, s58
	s_nop 0
	global_load_lds_dwordx4 v[166:167], off
	s_waitcnt vmcnt(8)
	s_waitcnt lgkmcnt(0)
	s_barrier
; #define PG8_STAGE(bufoff, gbase, voff) do { _Pragma("unroll") for (int _i = 0; _i < 2; ++_i) \
;         __builtin_amdgcn_global_load_lds((const unsigned*)((const char*)(gbase) + (voff)[_i]), (LAS unsigned*)(lds + (bufoff) + ldsw + _i * 8192), 16, 0, 0); } while (0)
; #define PG8_LDA(dst, b, h) do { _Pragma("unroll") for (int m = 0; m < 4; ++m) _Pragma("unroll") for (int k = 0; k < 2; ++k) dst[m][k] = *(const LAS bf16x8*)(lds + PG8_SA(b, h) + aoff + m * 2048 + k * 1024); } while (0)
; #define PG8_LDB(dst, b, h) do { _Pragma("unroll") for (int n = 0; n < 2; ++n) _Pragma("unroll") for (int k = 0; k < 2; ++k) dst[n][k] = *(const LAS bf16x8*)(lds + PG8_SB(b, h) + boff + n * 2048 + k * 1024); } while (0)
; #define PG8_MMA(ai, bj, At, Bt) do { __builtin_amdgcn_s_setprio(1); _Pragma("unroll") for (int m = 0; m < 4; ++m) _Pragma("unroll") for (int n = 0; n < 2; ++n) _Pragma("unroll") for (int k = 0; k < 2; ++k) \
;         acc[ai][bj][m][n] = __builtin_amdgcn_mfma_f32_16x16x32_bf16(Bt[n][k], At[m][k], acc[ai][bj][m][n], 0, 0, 0); __builtin_amdgcn_s_setprio(0); } while (0)
; #define PG8_WAIT_V(n) asm volatile("s_waitcnt vmcnt(" #n ")" ::: "memory")
; #define PG8_BAR __builtin_amdgcn_s_barrier()
; template <class Epi>
; __device__ __forceinline__ void gemm_phase(LAS unsigned char* lds, const Sched& S, const Epi& E) {
;     ...
;             PG8_LDB(B0, 0, 0); PG8_LDB(B1, 0, 1); PG8_SCHED; PG8_LDA(At, 0, 0); PG8_STAGE(PG8_SA(1, 1), a1 + hstepA, voffA);
;             PG8_WAIT_V(8); PG8_WAIT_L(0); PG8_BAR; PG8_MMA(0, 0, At, B0); PG8_MMA(0, 1, At, B1); PG8_BAR; PG8_SCHED;
;             PG8_LDA(At, 0, 1); PG8_STAGE(PG8_SB(0, 0), b2, voffB); PG8_STAGE(PG8_SB(0, 1), b2 + hstepB, voffB); PG8_STAGE(PG8_SA(0, 0), a2, voffA);
;             PG8_WAIT_V(8); PG8_WAIT_L(0); PG8_BAR; PG8_MMA(1, 0, At, B0); PG8_MMA(1, 1, At, B1); PG8_BAR; PG8_SCHED;
;             PG8_LDB(B0, 1, 0); PG8_LDB(B1, 1, 1); PG8_SCHED; PG8_LDA(At, 1, 0); PG8_STAGE(PG8_SA(0, 1), a2 + hstepA, voffA);
;             PG8_WAIT_V(8); PG8_WAIT_L(0); PG8_BAR; PG8_MMA(0, 0, At, B0); PG8_MMA(0, 1, At, B1); PG8_BAR; PG8_SCHED;
;             PG8_LDA(At, 1, 1); PG8_STAGE(PG8_SB(1, 0), b3, voffB); PG8_STAGE(PG8_SB(1, 1), b3 + hstepB, voffB); PG8_STAGE(PG8_SA(1, 0), a3, voffA);
;             PG8_WAIT_V(8); PG8_WAIT_L(0); PG8_BAR; PG8_MMA(1, 0, At, B0); PG8_MMA(1, 1, At, B1); PG8_BAR; PG8_SCHED;
;         }
	s_setprio 1
	s_waitcnt lgkmcnt(0)
	v_mfma_f32_16x16x32_bf16 v[62:65], v[130:133], v[162:165], v[62:65]
	v_mfma_f32_16x16x32_bf16 v[58:61], v[138:141], v[162:165], v[58:61]
	v_mfma_f32_16x16x32_bf16 v[54:57], v[130:133], v[194:197], v[54:57]
	v_mfma_f32_16x16x32_bf16 v[42:45], v[138:141], v[194:197], v[42:45]
	v_mfma_f32_16x16x32_bf16 v[30:33], v[130:133], v[226:229], v[30:33]
	v_mfma_f32_16x16x32_bf16 v[26:29], v[138:141], v[226:229], v[26:29]
	v_mfma_f32_16x16x32_bf16 v[22:25], v[130:133], v[234:237], v[22:25]
	v_mfma_f32_16x16x32_bf16 v[10:13], v[138:141], v[234:237], v[10:13]
	v_mfma_f32_16x16x32_bf16 v[62:65], v[134:137], v[190:193], v[62:65]
	v_mfma_f32_16x16x32_bf16 v[58:61], v[142:145], v[190:193], v[58:61]
	v_mfma_f32_16x16x32_bf16 v[54:57], v[134:137], v[198:201], v[54:57]
	v_mfma_f32_16x16x32_bf16 v[42:45], v[142:145], v[198:201], v[42:45]
	v_mfma_f32_16x16x32_bf16 v[30:33], v[134:137], v[230:233], v[30:33]
	v_mfma_f32_16x16x32_bf16 v[26:29], v[142:145], v[230:233], v[26:29]
	v_mfma_f32_16x16x32_bf16 v[22:25], v[134:137], v[238:241], v[22:25]
	v_mfma_f32_16x16x32_bf16 v[10:13], v[142:145], v[238:241], v[10:13]
	s_setprio 0
	s_setprio 1
	v_mfma_f32_16x16x32_bf16 v[50:53], v[146:149], v[162:165], v[50:53]
	v_mfma_f32_16x16x32_bf16 v[46:49], v[154:157], v[162:165], v[46:49]
	v_mfma_f32_16x16x32_bf16 v[38:41], v[146:149], v[194:197], v[38:41]
	v_mfma_f32_16x16x32_bf16 v[34:37], v[154:157], v[194:197], v[34:37]
	v_mfma_f32_16x16x32_bf16 v[18:21], v[146:149], v[226:229], v[18:21]
	v_mfma_f32_16x16x32_bf16 v[14:17], v[154:157], v[226:229], v[14:17]
	v_mfma_f32_16x16x32_bf16 v[6:9], v[146:149], v[234:237], v[6:9]
	v_mfma_f32_16x16x32_bf16 v[2:5], v[154:157], v[234:237], v[2:5]
	v_mfma_f32_16x16x32_bf16 v[50:53], v[150:153], v[190:193], v[50:53]
	v_mfma_f32_16x16x32_bf16 v[46:49], v[158:161], v[190:193], v[46:49]
	v_mfma_f32_16x16x32_bf16 v[38:41], v[150:153], v[198:201], v[38:41]
	v_mfma_f32_16x16x32_bf16 v[34:37], v[158:161], v[198:201], v[34:37]
	v_mfma_f32_16x16x32_bf16 v[18:21], v[150:153], v[230:233], v[18:21]
	v_mfma_f32_16x16x32_bf16 v[14:17], v[158:161], v[230:233], v[14:17]
	v_mfma_f32_16x16x32_bf16 v[6:9], v[150:153], v[238:241], v[6:9]
	v_mfma_f32_16x16x32_bf16 v[2:5], v[158:161], v[238:241], v[2:5]
	s_setprio 0
	s_barrier
	s_add_u32 s4, s4, 0x100
	s_addc_u32 s5, s5, 0
	s_add_u32 vcc_lo, vcc_lo, 0x100
	s_addc_u32 vcc_hi, vcc_hi, 0
	s_cmp_ge_i32 s49, s94
	s_mov_b32 s22, s49
	s_cbranch_scc0 .LBB0_2391
	s_branch .Lpeel_exit_down
.Ltail_peel_down:
	s_add_i32 s49, s22, 2
	s_add_u32 s23, s4, 0xffea0080
	s_addc_u32 s24, s5, -1
	s_add_i32 s88, 0, 0x10000
	s_cmp_eq_u32 s97, s22
	s_cselect_b32 s25, s26, s24
	s_cselect_b32 s24, s27, s23
	s_cselect_b32 s23, s95, vcc_hi
	s_cselect_b32 s22, s96, vcc_lo
	s_add_i32 s72, 0, 0x14000
	v_add_u32_e32 v142, s88, v222
	v_add_u32_e32 v158, s72, v222
	ds_read_b128 v[130:133], v142
	ds_read_b128 v[134:137], v142 offset:1024
	ds_read_b128 v[138:141], v142 offset:2048
	ds_read_b128 v[142:145], v142 offset:3072
	ds_read_b128 v[146:149], v158
	ds_read_b128 v[150:153], v158 offset:1024
	ds_read_b128 v[154:157], v158 offset:2048
	ds_read_b128 v[158:161], v158 offset:3072
	v_lshl_add_u64 v[166:167], s[4:5], 0, v[186:187]
	s_add_i32 m0, s35, 0xc000
	ds_read_b128 v[162:165], v224
	ds_read_b128 v[190:193], v224 offset:1024
	ds_read_b128 v[194:197], v224 offset:2048
	ds_read_b128 v[198:201], v224 offset:3072
	ds_read_b128 v[226:229], v224 offset:4096
	ds_read_b128 v[230:233], v224 offset:5120
	ds_read_b128 v[234:237], v224 offset:6144
	ds_read_b128 v[238:241], v224 offset:7168
	global_load_lds_dwordx4 v[166:167], off
	v_lshl_add_u64 v[166:167], s[4:5], 0, v[188:189]
	s_add_i32 m0, s35, 0xe000
	s_nop 0
	global_load_lds_dwordx4 v[166:167], off
	s_waitcnt vmcnt(8)
	s_waitcnt lgkmcnt(0)
	s_barrier
	s_setprio 1
	s_waitcnt lgkmcnt(0)
	s_cmp_eq_u64 s[10:11], 0
	s_cbranch_scc1 .Ltskip_downp_0
	v_mfma_f32_16x16x32_bf16 v[126:129], v[130:133], v[162:165], 0
	v_mfma_f32_16x16x32_bf16 v[122:125], v[138:141], v[162:165], 0
	v_mfma_f32_16x16x32_bf16 v[118:121], v[130:133], v[194:197], 0
	v_mfma_f32_16x16x32_bf16 v[106:109], v[138:141], v[194:197], 0
	v_mfma_f32_16x16x32_bf16 v[94:97], v[130:133], v[226:229], 0
	v_mfma_f32_16x16x32_bf16 v[90:93], v[138:141], v[226:229], 0
	v_mfma_f32_16x16x32_bf16 v[86:89], v[130:133], v[234:237], 0
	v_mfma_f32_16x16x32_bf16 v[74:77], v[138:141], v[234:237], 0
	v_mfma_f32_16x16x32_bf16 v[126:129], v[134:137], v[190:193], v[126:129]
	v_mfma_f32_16x16x32_bf16 v[122:125], v[142:145], v[190:193], v[122:125]
	v_mfma_f32_16x16x32_bf16 v[118:121], v[134:137], v[198:201], v[118:121]
	v_mfma_f32_16x16x32_bf16 v[106:109], v[142:145], v[198:201], v[106:109]
	v_mfma_f32_16x16x32_bf16 v[94:97], v[134:137], v[230:233], v[94:97]
	v_mfma_f32_16x16x32_bf16 v[90:93], v[142:145], v[230:233], v[90:93]
	v_mfma_f32_16x16x32_bf16 v[86:89], v[134:137], v[238:241], v[86:89]
	v_mfma_f32_16x16x32_bf16 v[74:77], v[142:145], v[238:241], v[74:77]
	s_setprio 0
	s_setprio 1
	v_mfma_f32_16x16x32_bf16 v[114:117], v[146:149], v[162:165], 0
	v_mfma_f32_16x16x32_bf16 v[110:113], v[154:157], v[162:165], 0
	v_mfma_f32_16x16x32_bf16 v[102:105], v[146:149], v[194:197], 0
	v_mfma_f32_16x16x32_bf16 v[98:101], v[154:157], v[194:197], 0
	v_mfma_f32_16x16x32_bf16 v[82:85], v[146:149], v[226:229], 0
	v_mfma_f32_16x16x32_bf16 v[78:81], v[154:157], v[226:229], 0
	v_mfma_f32_16x16x32_bf16 v[70:73], v[146:149], v[234:237], 0
	v_mfma_f32_16x16x32_bf16 v[66:69], v[154:157], v[234:237], 0
	v_mfma_f32_16x16x32_bf16 v[114:117], v[150:153], v[190:193], v[114:117]
	v_mfma_f32_16x16x32_bf16 v[110:113], v[158:161], v[190:193], v[110:113]
	v_mfma_f32_16x16x32_bf16 v[102:105], v[150:153], v[198:201], v[102:105]
	v_mfma_f32_16x16x32_bf16 v[98:101], v[158:161], v[198:201], v[98:101]
	v_mfma_f32_16x16x32_bf16 v[82:85], v[150:153], v[230:233], v[82:85]
	v_mfma_f32_16x16x32_bf16 v[78:81], v[158:161], v[230:233], v[78:81]
	v_mfma_f32_16x16x32_bf16 v[70:73], v[150:153], v[238:241], v[70:73]
	v_mfma_f32_16x16x32_bf16 v[66:69], v[158:161], v[238:241], v[66:69]
; #define PG8_STAGE(bufoff, gbase, voff) do { _Pragma("unroll") for (int _i = 0; _i < 2; ++_i) \
;         __builtin_amdgcn_global_load_lds((const unsigned*)((const char*)(gbase) + (voff)[_i]), (LAS unsigned*)(lds + (bufoff) + ldsw + _i * 8192), 16, 0, 0); } while (0)
; #define PG8_LDA(dst, b, h) do { _Pragma("unroll") for (int m = 0; m < 4; ++m) _Pragma("unroll") for (int k = 0; k < 2; ++k) dst[m][k] = *(const LAS bf16x8*)(lds + PG8_SA(b, h) + aoff + m * 2048 + k * 1024); } while (0)
; #define PG8_LDB(dst, b, h) do { _Pragma("unroll") for (int n = 0; n < 2; ++n) _Pragma("unroll") for (int k = 0; k < 2; ++k) dst[n][k] = *(const LAS bf16x8*)(lds + PG8_SB(b, h) + boff + n * 2048 + k * 1024); } while (0)
; #define PG8_MMA(ai, bj, At, Bt) do { __builtin_amdgcn_s_setprio(1); _Pragma("unroll") for (int m = 0; m < 4; ++m) _Pragma("unroll") for (int n = 0; n < 2; ++n) _Pragma("unroll") for (int k = 0; k < 2; ++k) \
;         acc[ai][bj][m][n] = __builtin_amdgcn_mfma_f32_16x16x32_bf16(Bt[n][k], At[m][k], acc[ai][bj][m][n], 0, 0, 0); __builtin_amdgcn_s_setprio(0); } while (0)
; #define PG8_WAIT_V(n) asm volatile("s_waitcnt vmcnt(" #n ")" ::: "memory")
; #define PG8_WAIT_L(n) asm volatile("s_waitcnt lgkmcnt(" #n ")" ::: "memory")
; #define PG8_BAR __builtin_amdgcn_s_barrier()
; #define PG8_SCHED __builtin_amdgcn_sched_barrier(0)
; template <class Epi>
; __device__ __forceinline__ void gemm_phase(LAS unsigned char* lds, const Sched& S, const Epi& E) {
;     ...
;             PG8_LDA(At, 0, 1); PG8_STAGE(PG8_SB(0, 0), b2, voffB); PG8_STAGE(PG8_SB(0, 1), b2 + hstepB, voffB); PG8_STAGE(PG8_SA(0, 0), a2, voffA);
;             PG8_WAIT_V(8); PG8_WAIT_L(0); PG8_BAR; PG8_MMA(1, 0, At, B0); PG8_MMA(1, 1, At, B1); PG8_BAR; PG8_SCHED;
;             PG8_LDB(B0, 1, 0); PG8_LDB(B1, 1, 1); PG8_SCHED; PG8_LDA(At, 1, 0); PG8_STAGE(PG8_SA(0, 1), a2 + hstepA, voffA);
;             PG8_WAIT_V(8); PG8_WAIT_L(0); PG8_BAR; PG8_MMA(0, 0, At, B0); PG8_MMA(0, 1, At, B1); PG8_BAR; PG8_SCHED;
.Ltskip_downp_0:
	s_setprio 0
	s_barrier
	s_add_i32 s73, s88, s34
	v_lshl_add_u64 v[166:167], s[22:23], 0, v[168:169]
	s_mov_b32 m0, s73
	ds_read_b128 v[162:165], v224 offset:16384
	ds_read_b128 v[190:193], v224 offset:17408
	ds_read_b128 v[194:197], v224 offset:18432
	ds_read_b128 v[198:201], v224 offset:19456
	ds_read_b128 v[226:229], v224 offset:20480
	ds_read_b128 v[230:233], v224 offset:21504
	ds_read_b128 v[234:237], v224 offset:22528
	ds_read_b128 v[238:241], v224 offset:23552
	global_load_lds_dwordx4 v[166:167], off
	s_add_i32 m0, s73, 0x2000
	s_add_u32 s88, s22, 0x160000
	v_lshl_add_u64 v[242:243], s[22:23], 0, v[176:177]
	s_addc_u32 s89, s23, 0
	s_add_i32 s72, s72, s34
	global_load_lds_dwordx4 v[242:243], off
	v_lshl_add_u64 v[244:245], s[88:89], 0, v[168:169]
	s_mov_b32 m0, s72
	v_lshl_add_u64 v[246:247], s[24:25], 0, v[176:177]
	global_load_lds_dwordx4 v[244:245], off
	v_lshl_add_u64 v[244:245], s[88:89], 0, v[176:177]
	s_add_i32 m0, s72, 0x2000
	s_nop 0
	global_load_lds_dwordx4 v[244:245], off
	v_lshl_add_u64 v[244:245], s[24:25], 0, v[168:169]
	s_mov_b32 m0, s35
	s_nop 0
	global_load_lds_dwordx4 v[244:245], off
	s_mov_b32 m0, s36
	s_nop 0
	global_load_lds_dwordx4 v[246:247], off
	s_waitcnt vmcnt(8)
	s_waitcnt lgkmcnt(0)
	s_barrier
	s_setprio 1
	s_waitcnt lgkmcnt(0)
	s_setprio 0
	s_setprio 1
	s_setprio 0
	s_barrier
	s_add_i32 s72, 0, 0x18000
	s_add_i32 s73, 0, 0x1c000
	v_add_u32_e32 v142, s72, v222
	v_add_u32_e32 v158, s73, v222
	ds_read_b128 v[130:133], v142
	ds_read_b128 v[134:137], v142 offset:1024
	ds_read_b128 v[138:141], v142 offset:2048
	ds_read_b128 v[142:145], v142 offset:3072
	ds_read_b128 v[146:149], v158
	ds_read_b128 v[150:153], v158 offset:1024
	ds_read_b128 v[154:157], v158 offset:2048
	ds_read_b128 v[158:161], v158 offset:3072
	s_add_u32 s24, s24, 0x160000
	s_addc_u32 s25, s25, 0
	s_mov_b32 m0, s37
	v_lshl_add_u64 v[248:249], s[24:25], 0, v[168:169]
	ds_read_b128 v[162:165], v224 offset:32768
	ds_read_b128 v[190:193], v224 offset:33792
	ds_read_b128 v[194:197], v224 offset:34816
	ds_read_b128 v[198:201], v224 offset:35840
	ds_read_b128 v[226:229], v224 offset:36864
	ds_read_b128 v[230:233], v224 offset:37888
	ds_read_b128 v[234:237], v224 offset:38912
	ds_read_b128 v[238:241], v224 offset:39936
	global_load_lds_dwordx4 v[248:249], off
	v_lshl_add_u64 v[248:249], s[24:25], 0, v[176:177]
	s_mov_b32 m0, s38
	s_nop 0
	global_load_lds_dwordx4 v[248:249], off
	s_waitcnt vmcnt(8)
	s_waitcnt lgkmcnt(0)
	s_barrier
	s_setprio 1
	s_waitcnt lgkmcnt(0)
	s_cmp_eq_u64 s[10:11], 0
	s_cbranch_scc1 .Ltskip_downp_1
	v_mfma_f32_16x16x32_bf16 v[126:129], v[130:133], v[162:165], v[126:129]
	v_mfma_f32_16x16x32_bf16 v[122:125], v[138:141], v[162:165], v[122:125]
	v_mfma_f32_16x16x32_bf16 v[118:121], v[130:133], v[194:197], v[118:121]
	v_mfma_f32_16x16x32_bf16 v[106:109], v[138:141], v[194:197], v[106:109]
	v_mfma_f32_16x16x32_bf16 v[94:97], v[130:133], v[226:229], v[94:97]
	v_mfma_f32_16x16x32_bf16 v[90:93], v[138:141], v[226:229], v[90:93]
	v_mfma_f32_16x16x32_bf16 v[86:89], v[130:133], v[234:237], v[86:89]
	v_mfma_f32_16x16x32_bf16 v[74:77], v[138:141], v[234:237], v[74:77]
	v_mfma_f32_16x16x32_bf16 v[126:129], v[134:137], v[190:193], v[126:129]
	v_mfma_f32_16x16x32_bf16 v[122:125], v[142:145], v[190:193], v[122:125]
	v_mfma_f32_16x16x32_bf16 v[118:121], v[134:137], v[198:201], v[118:121]
	v_mfma_f32_16x16x32_bf16 v[106:109], v[142:145], v[198:201], v[106:109]
	v_mfma_f32_16x16x32_bf16 v[94:97], v[134:137], v[230:233], v[94:97]
	v_mfma_f32_16x16x32_bf16 v[90:93], v[142:145], v[230:233], v[90:93]
	v_mfma_f32_16x16x32_bf16 v[86:89], v[134:137], v[238:241], v[86:89]
	v_mfma_f32_16x16x32_bf16 v[74:77], v[142:145], v[238:241], v[74:77]
	s_setprio 0
	s_setprio 1
	v_mfma_f32_16x16x32_bf16 v[114:117], v[146:149], v[162:165], v[114:117]
	v_mfma_f32_16x16x32_bf16 v[110:113], v[154:157], v[162:165], v[110:113]
	v_mfma_f32_16x16x32_bf16 v[102:105], v[146:149], v[194:197], v[102:105]
	v_mfma_f32_16x16x32_bf16 v[98:101], v[154:157], v[194:197], v[98:101]
	v_mfma_f32_16x16x32_bf16 v[82:85], v[146:149], v[226:229], v[82:85]
	v_mfma_f32_16x16x32_bf16 v[78:81], v[154:157], v[226:229], v[78:81]
	v_mfma_f32_16x16x32_bf16 v[70:73], v[146:149], v[234:237], v[70:73]
	v_mfma_f32_16x16x32_bf16 v[66:69], v[154:157], v[234:237], v[66:69]
	v_mfma_f32_16x16x32_bf16 v[114:117], v[150:153], v[190:193], v[114:117]
	v_mfma_f32_16x16x32_bf16 v[110:113], v[158:161], v[190:193], v[110:113]
	v_mfma_f32_16x16x32_bf16 v[102:105], v[150:153], v[198:201], v[102:105]
	v_mfma_f32_16x16x32_bf16 v[98:101], v[158:161], v[198:201], v[98:101]
	v_mfma_f32_16x16x32_bf16 v[82:85], v[150:153], v[230:233], v[82:85]
	v_mfma_f32_16x16x32_bf16 v[78:81], v[158:161], v[230:233], v[78:81]
	v_mfma_f32_16x16x32_bf16 v[70:73], v[150:153], v[238:241], v[70:73]
	v_mfma_f32_16x16x32_bf16 v[66:69], v[158:161], v[238:241], v[66:69]
; #define PG8_STAGE(bufoff, gbase, voff) do { _Pragma("unroll") for (int _i = 0; _i < 2; ++_i) \
;         __builtin_amdgcn_global_load_lds((const unsigned*)((const char*)(gbase) + (voff)[_i]), (LAS unsigned*)(lds + (bufoff) + ldsw + _i * 8192), 16, 0, 0); } while (0)
; #define PG8_LDA(dst, b, h) do { _Pragma("unroll") for (int m = 0; m < 4; ++m) _Pragma("unroll") for (int k = 0; k < 2; ++k) dst[m][k] = *(const LAS bf16x8*)(lds + PG8_SA(b, h) + aoff + m * 2048 + k * 1024); } while (0)
; #define PG8_LDB(dst, b, h) do { _Pragma("unroll") for (int n = 0; n < 2; ++n) _Pragma("unroll") for (int k = 0; k < 2; ++k) dst[n][k] = *(const LAS bf16x8*)(lds + PG8_SB(b, h) + boff + n * 2048 + k * 1024); } while (0)
; #define PG8_MMA(ai, bj, At, Bt) do { __builtin_amdgcn_s_setprio(1); _Pragma("unroll") for (int m = 0; m < 4; ++m) _Pragma("unroll") for (int n = 0; n < 2; ++n) _Pragma("unroll") for (int k = 0; k < 2; ++k) \
;         acc[ai][bj][m][n] = __builtin_amdgcn_mfma_f32_16x16x32_bf16(Bt[n][k], At[m][k], acc[ai][bj][m][n], 0, 0, 0); __builtin_amdgcn_s_setprio(0); } while (0)
; #define PG8_WAIT_V(n) asm volatile("s_waitcnt vmcnt(" #n ")" ::: "memory")
; #define PG8_BAR __builtin_amdgcn_s_barrier()
; template <class Epi>
; __device__ __forceinline__ void gemm_phase(LAS unsigned char* lds, const Sched& S, const Epi& E) {
;     ...
;             PG8_LDB(B0, 0, 0); PG8_LDB(B1, 0, 1); PG8_SCHED; PG8_LDA(At, 0, 0); PG8_STAGE(PG8_SA(1, 1), a1 + hstepA, voffA);
;             PG8_WAIT_V(8); PG8_WAIT_L(0); PG8_BAR; PG8_MMA(0, 0, At, B0); PG8_MMA(0, 1, At, B1); PG8_BAR; PG8_SCHED;
;             PG8_LDA(At, 0, 1); PG8_STAGE(PG8_SB(0, 0), b2, voffB); PG8_STAGE(PG8_SB(0, 1), b2 + hstepB, voffB); PG8_STAGE(PG8_SA(0, 0), a2, voffA);
;             PG8_WAIT_V(8); PG8_WAIT_L(0); PG8_BAR; PG8_MMA(1, 0, At, B0); PG8_MMA(1, 1, At, B1); PG8_BAR; PG8_SCHED;
;             PG8_LDB(B0, 1, 0); PG8_LDB(B1, 1, 1); PG8_SCHED; PG8_LDA(At, 1, 0); PG8_STAGE(PG8_SA(0, 1), a2 + hstepA, voffA);
;             PG8_WAIT_V(8); PG8_WAIT_L(0); PG8_BAR; PG8_MMA(0, 0, At, B0); PG8_MMA(0, 1, At, B1); PG8_BAR; PG8_SCHED;
;             PG8_LDA(At, 1, 1); PG8_STAGE(PG8_SB(1, 0), b3, voffB); PG8_STAGE(PG8_SB(1, 1), b3 + hstepB, voffB); PG8_STAGE(PG8_SA(1, 0), a3, voffA);
;             PG8_WAIT_V(8); PG8_WAIT_L(0); PG8_BAR; PG8_MMA(1, 0, At, B0); PG8_MMA(1, 1, At, B1); PG8_BAR; PG8_SCHED;
;         }
.Ltskip_downp_1:
	s_setprio 0
	s_barrier
	s_add_i32 s24, s72, s34
	v_lshl_add_u64 v[166:167], v[166:167], 0, s[0:1]
	s_mov_b32 m0, s24
	ds_read_b128 v[162:165], v224 offset:49152
	ds_read_b128 v[190:193], v224 offset:50176
	ds_read_b128 v[194:197], v224 offset:51200
	ds_read_b128 v[198:201], v224 offset:52224
	ds_read_b128 v[226:229], v224 offset:53248
	ds_read_b128 v[230:233], v224 offset:54272
	ds_read_b128 v[234:237], v224 offset:55296
	ds_read_b128 v[238:241], v224 offset:56320
	global_load_lds_dwordx4 v[166:167], off
	s_add_i32 m0, s24, 0x2000
	s_add_u32 s22, s22, 0x160080
	v_lshl_add_u64 v[166:167], v[242:243], 0, s[0:1]
	s_addc_u32 s23, s23, 0
	s_add_i32 s24, s73, s34
	global_load_lds_dwordx4 v[166:167], off
	v_lshl_add_u64 v[166:167], s[22:23], 0, v[168:169]
	s_mov_b32 m0, s24
	s_nop 0
	global_load_lds_dwordx4 v[166:167], off
	v_lshl_add_u64 v[166:167], s[22:23], 0, v[176:177]
	s_add_i32 m0, s24, 0x2000
	s_nop 0
	global_load_lds_dwordx4 v[166:167], off
	v_lshl_add_u64 v[166:167], v[244:245], 0, s[0:1]
	s_mov_b32 m0, s39
	s_nop 0
	global_load_lds_dwordx4 v[166:167], off
	v_lshl_add_u64 v[166:167], v[246:247], 0, s[0:1]
	s_mov_b32 m0, s58
	s_nop 0
	global_load_lds_dwordx4 v[166:167], off
	s_waitcnt vmcnt(8)
	s_waitcnt lgkmcnt(0)
	s_barrier
	s_setprio 1
	s_waitcnt lgkmcnt(0)
	s_setprio 0
	s_setprio 1
	s_setprio 0
	s_barrier
	s_add_u32 s4, s4, 0x100
	s_addc_u32 s5, s5, 0
	s_add_u32 vcc_lo, vcc_lo, 0x100
	s_addc_u32 vcc_hi, vcc_hi, 0
	s_cmp_ge_i32 s49, s94
	s_mov_b32 s22, s49
	s_cbranch_scc1 .Lpeel_exit_down
.Ltail_loop_down:
	s_add_i32 s49, s22, 2
	s_add_u32 s23, s4, 0xffea0080
	s_addc_u32 s24, s5, -1
	s_add_i32 s88, 0, 0x10000
	s_cmp_eq_u32 s97, s22
	s_cselect_b32 s25, s26, s24
	s_cselect_b32 s24, s27, s23
	s_cselect_b32 s23, s95, vcc_hi
	s_cselect_b32 s22, s96, vcc_lo
	s_add_i32 s72, 0, 0x14000
	v_add_u32_e32 v142, s88, v222
	v_add_u32_e32 v158, s72, v222
	ds_read_b128 v[130:133], v142
	ds_read_b128 v[134:137], v142 offset:1024
	ds_read_b128 v[138:141], v142 offset:2048
	ds_read_b128 v[142:145], v142 offset:3072
	ds_read_b128 v[146:149], v158
	ds_read_b128 v[150:153], v158 offset:1024
	ds_read_b128 v[154:157], v158 offset:2048
	ds_read_b128 v[158:161], v158 offset:3072
	v_lshl_add_u64 v[166:167], s[4:5], 0, v[186:187]
	s_add_i32 m0, s35, 0xc000
	ds_read_b128 v[162:165], v224
	ds_read_b128 v[190:193], v224 offset:1024
	ds_read_b128 v[194:197], v224 offset:2048
	ds_read_b128 v[198:201], v224 offset:3072
	ds_read_b128 v[226:229], v224 offset:4096
	ds_read_b128 v[230:233], v224 offset:5120
	ds_read_b128 v[234:237], v224 offset:6144
	ds_read_b128 v[238:241], v224 offset:7168
	global_load_lds_dwordx4 v[166:167], off
	v_lshl_add_u64 v[166:167], s[4:5], 0, v[188:189]
	s_add_i32 m0, s35, 0xe000
	s_nop 0
	global_load_lds_dwordx4 v[166:167], off
	s_waitcnt vmcnt(8)
	s_waitcnt lgkmcnt(0)
	s_barrier
	s_setprio 1
	s_waitcnt lgkmcnt(0)
	s_cmp_eq_u64 s[10:11], 0
	s_cbranch_scc1 .Ltskip_downl_0
	v_mfma_f32_16x16x32_bf16 v[126:129], v[130:133], v[162:165], v[126:129]
	v_mfma_f32_16x16x32_bf16 v[122:125], v[138:141], v[162:165], v[122:125]
	v_mfma_f32_16x16x32_bf16 v[118:121], v[130:133], v[194:197], v[118:121]
	v_mfma_f32_16x16x32_bf16 v[106:109], v[138:141], v[194:197], v[106:109]
	v_mfma_f32_16x16x32_bf16 v[94:97], v[130:133], v[226:229], v[94:97]
	v_mfma_f32_16x16x32_bf16 v[90:93], v[138:141], v[226:229], v[90:93]
	v_mfma_f32_16x16x32_bf16 v[86:89], v[130:133], v[234:237], v[86:89]
	v_mfma_f32_16x16x32_bf16 v[74:77], v[138:141], v[234:237], v[74:77]
	v_mfma_f32_16x16x32_bf16 v[126:129], v[134:137], v[190:193], v[126:129]
	v_mfma_f32_16x16x32_bf16 v[122:125], v[142:145], v[190:193], v[122:125]
	v_mfma_f32_16x16x32_bf16 v[118:121], v[134:137], v[198:201], v[118:121]
	v_mfma_f32_16x16x32_bf16 v[106:109], v[142:145], v[198:201], v[106:109]
	v_mfma_f32_16x16x32_bf16 v[94:97], v[134:137], v[230:233], v[94:97]
	v_mfma_f32_16x16x32_bf16 v[90:93], v[142:145], v[230:233], v[90:93]
	v_mfma_f32_16x16x32_bf16 v[86:89], v[134:137], v[238:241], v[86:89]
	v_mfma_f32_16x16x32_bf16 v[74:77], v[142:145], v[238:241], v[74:77]
	s_setprio 0
	s_setprio 1
	v_mfma_f32_16x16x32_bf16 v[114:117], v[146:149], v[162:165], v[114:117]
	v_mfma_f32_16x16x32_bf16 v[110:113], v[154:157], v[162:165], v[110:113]
	v_mfma_f32_16x16x32_bf16 v[102:105], v[146:149], v[194:197], v[102:105]
	v_mfma_f32_16x16x32_bf16 v[98:101], v[154:157], v[194:197], v[98:101]
	v_mfma_f32_16x16x32_bf16 v[82:85], v[146:149], v[226:229], v[82:85]
	v_mfma_f32_16x16x32_bf16 v[78:81], v[154:157], v[226:229], v[78:81]
	v_mfma_f32_16x16x32_bf16 v[70:73], v[146:149], v[234:237], v[70:73]
	v_mfma_f32_16x16x32_bf16 v[66:69], v[154:157], v[234:237], v[66:69]
	v_mfma_f32_16x16x32_bf16 v[114:117], v[150:153], v[190:193], v[114:117]
	v_mfma_f32_16x16x32_bf16 v[110:113], v[158:161], v[190:193], v[110:113]
	v_mfma_f32_16x16x32_bf16 v[102:105], v[150:153], v[198:201], v[102:105]
	v_mfma_f32_16x16x32_bf16 v[98:101], v[158:161], v[198:201], v[98:101]
	v_mfma_f32_16x16x32_bf16 v[82:85], v[150:153], v[230:233], v[82:85]
	v_mfma_f32_16x16x32_bf16 v[78:81], v[158:161], v[230:233], v[78:81]
	v_mfma_f32_16x16x32_bf16 v[70:73], v[150:153], v[238:241], v[70:73]
	v_mfma_f32_16x16x32_bf16 v[66:69], v[158:161], v[238:241], v[66:69]

; #define PG8_STAGE(bufoff, gbase, voff) do { _Pragma("unroll") for (int _i = 0; _i < 2; ++_i) \
;         __builtin_amdgcn_global_load_lds((const unsigned*)((const char*)(gbase) + (voff)[_i]), (LAS unsigned*)(lds + (bufoff) + ldsw + _i * 8192), 16, 0, 0); } while (0)
; #define PG8_LDA(dst, b, h) do { _Pragma("unroll") for (int m = 0; m < 4; ++m) _Pragma("unroll") for (int k = 0; k < 2; ++k) dst[m][k] = *(const LAS bf16x8*)(lds + PG8_SA(b, h) + aoff + m * 2048 + k * 1024); } while (0)
; #define PG8_MMA(ai, bj, At, Bt) do { __builtin_amdgcn_s_setprio(1); _Pragma("unroll") for (int m = 0; m < 4; ++m) _Pragma("unroll") for (int n = 0; n < 2; ++n) _Pragma("unroll") for (int k = 0; k < 2; ++k) \
;         acc[ai][bj][m][n] = __builtin_amdgcn_mfma_f32_16x16x32_bf16(Bt[n][k], At[m][k], acc[ai][bj][m][n], 0, 0, 0); __builtin_amdgcn_s_setprio(0); } while (0)
; #define PG8_WAIT_V(n) asm volatile("s_waitcnt vmcnt(" #n ")" ::: "memory")
; #define PG8_WAIT_L(n) asm volatile("s_waitcnt lgkmcnt(" #n ")" ::: "memory")
; #define PG8_BAR __builtin_amdgcn_s_barrier()
; #define PG8_SCHED __builtin_amdgcn_sched_barrier(0)
; template <class Epi>
; __device__ __forceinline__ void gemm_phase(LAS unsigned char* lds, const Sched& S, const Epi& E) {
;     ...
;             PG8_LDA(At, 1, 1); PG8_STAGE(PG8_SB(1, 0), b3, voffB); PG8_STAGE(PG8_SB(1, 1), b3 + hstepB, voffB); PG8_STAGE(PG8_SA(1, 0), a3, voffA);
;             PG8_WAIT_V(8); PG8_WAIT_L(0); PG8_BAR; PG8_MMA(1, 0, At, B0); PG8_MMA(1, 1, At, B1); PG8_BAR; PG8_SCHED;
;         }
.Ltskip_downl_1:
	s_setprio 0
	s_barrier
	s_add_i32 s24, s72, s34
	v_lshl_add_u64 v[166:167], v[166:167], 0, s[0:1]
	s_mov_b32 m0, s24
	ds_read_b128 v[162:165], v224 offset:49152
	ds_read_b128 v[190:193], v224 offset:50176
	ds_read_b128 v[194:197], v224 offset:51200
	ds_read_b128 v[198:201], v224 offset:52224
	ds_read_b128 v[226:229], v224 offset:53248
	ds_read_b128 v[230:233], v224 offset:54272
	ds_read_b128 v[234:237], v224 offset:55296
	ds_read_b128 v[238:241], v224 offset:56320
	global_load_lds_dwordx4 v[166:167], off
	s_add_i32 m0, s24, 0x2000
	s_add_u32 s22, s22, 0x160080
	v_lshl_add_u64 v[166:167], v[242:243], 0, s[0:1]
	s_addc_u32 s23, s23, 0
	s_add_i32 s24, s73, s34
	global_load_lds_dwordx4 v[166:167], off
	v_lshl_add_u64 v[166:167], s[22:23], 0, v[168:169]
	s_mov_b32 m0, s24
	s_nop 0
	global_load_lds_dwordx4 v[166:167], off
	v_lshl_add_u64 v[166:167], s[22:23], 0, v[176:177]
	s_add_i32 m0, s24, 0x2000
	s_nop 0
	global_load_lds_dwordx4 v[166:167], off
	v_lshl_add_u64 v[166:167], v[244:245], 0, s[0:1]
	s_mov_b32 m0, s39
	s_nop 0
	global_load_lds_dwordx4 v[166:167], off
	v_lshl_add_u64 v[166:167], v[246:247], 0, s[0:1]
	s_mov_b32 m0, s58
	s_nop 0
	global_load_lds_dwordx4 v[166:167], off
	s_waitcnt vmcnt(8)
	s_waitcnt lgkmcnt(0)
	s_barrier
	s_setprio 1
	s_waitcnt lgkmcnt(0)
	s_setprio 0
	s_setprio 1
	s_setprio 0
	s_barrier
	s_add_u32 s4, s4, 0x100
	s_addc_u32 s5, s5, 0
	s_add_u32 vcc_lo, vcc_lo, 0x100
	s_addc_u32 vcc_hi, vcc_hi, 0
	s_cmp_ge_i32 s49, s94
	s_mov_b32 s22, s49
	s_cbranch_scc0 .Ltail_loop_down
